# v40 + epilogue scalar f32 pairs (x*-log2e, 1+e) fused into v_pk_mul_f32/v_pk_add_f32 in P2/P5/P12 epilogues (same f32 math)
# speedup vs baseline: 1.0145x; 1.0020x over previous
.Ldfr_p2_b:
	s_mov_b32 s20, 0xbfb8aa3b
	s_setprio 0
	v_pk_mul_f32 v[154:155], v[126:127], s[20:21] op_sel_hi:[1,0]
	v_exp_f32_e32 v154, v154
	v_exp_f32_e32 v155, v155
	s_and_b64 vcc, exec, s[2:3]
	s_mov_b64 s[34:35], s[12:13]
	v_pk_add_f32 v[154:155], v[154:155], 1.0 op_sel_hi:[1,0]
	v_rcp_f32_e32 v156, v154
	v_rcp_f32_e32 v157, v155
	v_mul_f32_e32 v155, 0xbfb8aa3b, v128
	v_exp_f32_e32 v155, v155
	v_lshl_add_u32 v154, s14, 8, v149
	v_pk_mul_f32 v[126:127], v[126:127], v[156:157]
	v_mul_f32_e32 v156, 0xbfb8aa3b, v129
	v_exp_f32_e32 v156, v156
	v_pk_mul_f32 v[118:119], v[126:127], v[118:119]
	v_add_f32_e32 v126, 1.0, v155
	v_mul_f32_e32 v155, 0xbfb8aa3b, v122
	v_add_f32_e32 v127, 1.0, v156
	v_rcp_f32_e32 v126, v126
	v_rcp_f32_e32 v127, v127
	v_exp_f32_e32 v155, v155
	v_mul_f32_e32 v156, 0xbfb8aa3b, v123
	v_exp_f32_e32 v156, v156
	v_pk_mul_f32 v[126:127], v[128:129], v[126:127]
	v_add_f32_e32 v128, 1.0, v155
	v_mul_f32_e32 v155, 0xbfb8aa3b, v124
	v_add_f32_e32 v129, 1.0, v156
	v_exp_f32_e32 v155, v155
	v_mul_f32_e32 v156, 0xbfb8aa3b, v125
	v_exp_f32_e32 v157, v156
	v_rcp_f32_e32 v128, v128
	v_add_f32_e32 v155, 1.0, v155
	v_rcp_f32_e32 v129, v129
	v_rcp_f32_e32 v156, v155
	v_add_f32_e32 v155, 1.0, v157
	v_rcp_f32_e32 v157, v155
	v_pk_mul_f32 v[122:123], v[122:123], v[128:129]
	s_lshl_b32 s14, s15, 7
	v_pk_mul_f32 v[122:123], v[122:123], v[114:115]
	v_pk_mul_f32 v[114:115], v[124:125], v[156:157]
	s_ashr_i32 s15, s14, 31
	v_pk_mul_f32 v[124:125], v[114:115], v[116:117]
	v_mov_b64_e32 v[114:115], s[0:1]
	v_mad_i64_i32 v[116:117], s[16:17], v154, s74, v[114:115]
	s_lshl_b64 s[14:15], s[14:15], 1
	v_lshl_add_u64 v[116:117], v[116:117], 0, s[14:15]
	v_pk_mul_f32 v[120:121], v[126:127], v[120:121]
	v_lshl_add_u64 v[126:127], v[116:117], 0, v[138:139]
	v_cvt_pk_bf16_f32 v116, v118, v119
	v_mul_f32_e32 v118, 0xbfb8aa3b, v110
	v_exp_f32_e32 v119, v118
	v_mul_f32_e32 v118, 0xbfb8aa3b, v111
	v_cvt_pk_bf16_f32 v117, v120, v121
	v_exp_f32_e32 v121, v118
	v_add_f32_e32 v119, 1.0, v119
	v_rcp_f32_e32 v120, v119
	v_cvt_pk_bf16_f32 v118, v122, v123
	v_add_f32_e32 v119, 1.0, v121
	v_rcp_f32_e32 v121, v119
	v_cvt_pk_bf16_f32 v119, v124, v125
	global_store_dwordx4 v[126:127], v[116:119], off nt
	v_pk_mul_f32 v[110:111], v[110:111], v[120:121]
	s_nop 0
	v_pk_mul_f32 v[116:117], v[112:113], s[20:21] op_sel_hi:[1,0]
	v_exp_f32_e32 v116, v116
	v_exp_f32_e32 v117, v117
	v_pk_mul_f32 v[102:103], v[110:111], v[102:103]
	v_or_b32_e32 v118, 16, v154
	v_pk_add_f32 v[110:111], v[116:117], 1.0 op_sel_hi:[1,0]
	v_pk_mul_f32 v[116:117], v[106:107], s[20:21] op_sel_hi:[1,0]
	v_rcp_f32_e32 v110, v110
	v_rcp_f32_e32 v111, v111
	v_exp_f32_e32 v116, v116
	v_exp_f32_e32 v117, v117
	v_pk_mul_f32 v[110:111], v[112:113], v[110:111]
	v_pk_add_f32 v[112:113], v[116:117], 1.0 op_sel_hi:[1,0]
	v_pk_mul_f32 v[116:117], v[108:109], s[20:21] op_sel_hi:[1,0]
	v_exp_f32_e32 v116, v116
	v_exp_f32_e32 v117, v117
	v_rcp_f32_e32 v112, v112
	v_rcp_f32_e32 v113, v113
	v_pk_add_f32 v[116:117], v[116:117], 1.0 op_sel_hi:[1,0]
	v_rcp_f32_e32 v116, v116
	v_rcp_f32_e32 v117, v117
	v_pk_mul_f32 v[106:107], v[106:107], v[112:113]
	v_pk_mul_f32 v[104:105], v[110:111], v[104:105]
	v_pk_mul_f32 v[106:107], v[106:107], v[98:99]
	v_pk_mul_f32 v[98:99], v[108:109], v[116:117]
	s_nop 0
	v_pk_mul_f32 v[108:109], v[98:99], v[100:101]
	v_mad_i64_i32 v[98:99], s[16:17], v118, s74, v[114:115]
	v_mul_f32_e32 v100, 0xbfb8aa3b, v94
	v_lshl_add_u64 v[98:99], v[98:99], 0, s[14:15]
	v_exp_f32_e32 v101, v100
	v_mul_f32_e32 v100, 0xbfb8aa3b, v95
	v_lshl_add_u64 v[110:111], v[98:99], 0, v[138:139]
	v_cvt_pk_bf16_f32 v98, v102, v103
	v_exp_f32_e32 v103, v100
	v_add_f32_e32 v101, 1.0, v101
	v_rcp_f32_e32 v102, v101
	v_cvt_pk_bf16_f32 v99, v104, v105
	v_add_f32_e32 v101, 1.0, v103
	v_cvt_pk_bf16_f32 v100, v106, v107
	v_rcp_f32_e32 v103, v101
	v_cvt_pk_bf16_f32 v101, v108, v109
	global_store_dwordx4 v[110:111], v[98:101], off nt
	v_pk_mul_f32 v[94:95], v[94:95], v[102:103]
	s_nop 0
	v_pk_mul_f32 v[98:99], v[96:97], s[20:21] op_sel_hi:[1,0]
	v_exp_f32_e32 v98, v98
	v_exp_f32_e32 v99, v99
	v_pk_mul_f32 v[86:87], v[94:95], v[86:87]
	v_or_b32_e32 v100, 32, v154
	v_pk_add_f32 v[94:95], v[98:99], 1.0 op_sel_hi:[1,0]
	v_pk_mul_f32 v[98:99], v[90:91], s[20:21] op_sel_hi:[1,0]
	v_rcp_f32_e32 v94, v94
	v_rcp_f32_e32 v95, v95
	v_exp_f32_e32 v98, v98
	v_exp_f32_e32 v99, v99
	v_pk_mul_f32 v[94:95], v[96:97], v[94:95]
	v_pk_add_f32 v[96:97], v[98:99], 1.0 op_sel_hi:[1,0]
	v_pk_mul_f32 v[98:99], v[92:93], s[20:21] op_sel_hi:[1,0]
	v_exp_f32_e32 v98, v98
	v_exp_f32_e32 v99, v99
	v_rcp_f32_e32 v96, v96
	v_rcp_f32_e32 v97, v97
	v_pk_add_f32 v[98:99], v[98:99], 1.0 op_sel_hi:[1,0]
	v_rcp_f32_e32 v98, v98
	v_rcp_f32_e32 v99, v99
	v_pk_mul_f32 v[90:91], v[90:91], v[96:97]
	v_pk_mul_f32 v[88:89], v[94:95], v[88:89]
	v_pk_mul_f32 v[90:91], v[90:91], v[82:83]
	v_pk_mul_f32 v[82:83], v[92:93], v[98:99]
	s_nop 0
	v_pk_mul_f32 v[92:93], v[82:83], v[84:85]
	v_mad_i64_i32 v[82:83], s[16:17], v100, s74, v[114:115]
	v_mul_f32_e32 v84, 0xbfb8aa3b, v78
	v_lshl_add_u64 v[82:83], v[82:83], 0, s[14:15]
	v_exp_f32_e32 v85, v84
	v_mul_f32_e32 v84, 0xbfb8aa3b, v79
	v_lshl_add_u64 v[94:95], v[82:83], 0, v[138:139]
	v_cvt_pk_bf16_f32 v82, v86, v87
	v_exp_f32_e32 v87, v84
	v_add_f32_e32 v85, 1.0, v85
	v_rcp_f32_e32 v86, v85
	v_cvt_pk_bf16_f32 v83, v88, v89
	v_add_f32_e32 v85, 1.0, v87
	v_cvt_pk_bf16_f32 v84, v90, v91
	v_rcp_f32_e32 v87, v85
	v_cvt_pk_bf16_f32 v85, v92, v93
	global_store_dwordx4 v[94:95], v[82:85], off nt
	v_pk_mul_f32 v[78:79], v[78:79], v[86:87]
	s_nop 0
	v_pk_mul_f32 v[82:83], v[80:81], s[20:21] op_sel_hi:[1,0]
	v_exp_f32_e32 v82, v82
	v_exp_f32_e32 v83, v83
	v_pk_mul_f32 v[70:71], v[78:79], v[70:71]
	v_or_b32_e32 v84, 48, v154
	v_pk_add_f32 v[78:79], v[82:83], 1.0 op_sel_hi:[1,0]
	v_pk_mul_f32 v[82:83], v[74:75], s[20:21] op_sel_hi:[1,0]
	v_rcp_f32_e32 v78, v78
	v_rcp_f32_e32 v79, v79
	v_exp_f32_e32 v82, v82
	v_exp_f32_e32 v83, v83
	v_pk_mul_f32 v[78:79], v[80:81], v[78:79]
	v_pk_add_f32 v[80:81], v[82:83], 1.0 op_sel_hi:[1,0]
	v_pk_mul_f32 v[82:83], v[76:77], s[20:21] op_sel_hi:[1,0]
	v_exp_f32_e32 v82, v82
	v_exp_f32_e32 v83, v83
	v_rcp_f32_e32 v80, v80
	v_rcp_f32_e32 v81, v81
	v_pk_add_f32 v[82:83], v[82:83], 1.0 op_sel_hi:[1,0]
	v_rcp_f32_e32 v82, v82
	v_rcp_f32_e32 v83, v83
	v_pk_mul_f32 v[74:75], v[74:75], v[80:81]
	v_pk_mul_f32 v[72:73], v[78:79], v[72:73]
	v_pk_mul_f32 v[74:75], v[74:75], v[66:67]
	v_pk_mul_f32 v[66:67], v[76:77], v[82:83]
	s_nop 0
	v_pk_mul_f32 v[76:77], v[66:67], v[68:69]
	v_mad_i64_i32 v[66:67], s[16:17], v84, s74, v[114:115]
	v_mul_f32_e32 v68, 0xbfb8aa3b, v62
	v_lshl_add_u64 v[66:67], v[66:67], 0, s[14:15]
	v_exp_f32_e32 v69, v68
	v_mul_f32_e32 v68, 0xbfb8aa3b, v63
	v_lshl_add_u64 v[78:79], v[66:67], 0, v[138:139]
	v_cvt_pk_bf16_f32 v66, v70, v71
	v_exp_f32_e32 v71, v68
	v_add_f32_e32 v69, 1.0, v69
	v_rcp_f32_e32 v70, v69
	v_cvt_pk_bf16_f32 v67, v72, v73
	v_add_f32_e32 v69, 1.0, v71
	v_cvt_pk_bf16_f32 v68, v74, v75
	v_rcp_f32_e32 v71, v69
	v_cvt_pk_bf16_f32 v69, v76, v77
	global_store_dwordx4 v[78:79], v[66:69], off nt
	v_pk_mul_f32 v[62:63], v[62:63], v[70:71]
	s_nop 0
	v_pk_mul_f32 v[66:67], v[64:65], s[20:21] op_sel_hi:[1,0]
	v_exp_f32_e32 v66, v66
	v_exp_f32_e32 v67, v67
	v_pk_mul_f32 v[54:55], v[62:63], v[54:55]
	v_add_u32_e32 v68, 0x80, v154
	v_pk_add_f32 v[62:63], v[66:67], 1.0 op_sel_hi:[1,0]
	v_pk_mul_f32 v[66:67], v[58:59], s[20:21] op_sel_hi:[1,0]
	v_rcp_f32_e32 v62, v62
	v_rcp_f32_e32 v63, v63
	v_exp_f32_e32 v66, v66
	v_exp_f32_e32 v67, v67
	v_pk_mul_f32 v[62:63], v[64:65], v[62:63]
	v_pk_add_f32 v[64:65], v[66:67], 1.0 op_sel_hi:[1,0]
	v_pk_mul_f32 v[66:67], v[60:61], s[20:21] op_sel_hi:[1,0]
	v_exp_f32_e32 v66, v66
	v_exp_f32_e32 v67, v67
	v_rcp_f32_e32 v64, v64
	v_rcp_f32_e32 v65, v65
	v_pk_add_f32 v[66:67], v[66:67], 1.0 op_sel_hi:[1,0]
	v_rcp_f32_e32 v66, v66
	v_rcp_f32_e32 v67, v67
	v_pk_mul_f32 v[58:59], v[58:59], v[64:65]
	v_pk_mul_f32 v[56:57], v[62:63], v[56:57]
	v_pk_mul_f32 v[58:59], v[58:59], v[50:51]
	v_pk_mul_f32 v[50:51], v[60:61], v[66:67]
	s_nop 0
	v_pk_mul_f32 v[60:61], v[50:51], v[52:53]
	v_mad_i64_i32 v[50:51], s[16:17], v68, s74, v[114:115]
	v_mul_f32_e32 v52, 0xbfb8aa3b, v46
	v_lshl_add_u64 v[50:51], v[50:51], 0, s[14:15]
	v_exp_f32_e32 v53, v52
	v_mul_f32_e32 v52, 0xbfb8aa3b, v47
	v_lshl_add_u64 v[62:63], v[50:51], 0, v[138:139]
	v_cvt_pk_bf16_f32 v50, v54, v55
	v_exp_f32_e32 v55, v52
	v_add_f32_e32 v53, 1.0, v53
	v_rcp_f32_e32 v54, v53
	v_cvt_pk_bf16_f32 v51, v56, v57
	v_add_f32_e32 v53, 1.0, v55
	v_cvt_pk_bf16_f32 v52, v58, v59
	v_rcp_f32_e32 v55, v53
	v_cvt_pk_bf16_f32 v53, v60, v61
	global_store_dwordx4 v[62:63], v[50:53], off nt
	v_pk_mul_f32 v[46:47], v[46:47], v[54:55]
	s_nop 0
	v_pk_mul_f32 v[50:51], v[48:49], s[20:21] op_sel_hi:[1,0]
	v_exp_f32_e32 v50, v50
	v_exp_f32_e32 v51, v51
	v_pk_mul_f32 v[38:39], v[46:47], v[38:39]
	v_add_u32_e32 v52, 0x90, v154
	v_pk_add_f32 v[46:47], v[50:51], 1.0 op_sel_hi:[1,0]
	v_pk_mul_f32 v[50:51], v[42:43], s[20:21] op_sel_hi:[1,0]
	v_rcp_f32_e32 v46, v46
	v_rcp_f32_e32 v47, v47
	v_exp_f32_e32 v50, v50
	v_exp_f32_e32 v51, v51
	v_pk_mul_f32 v[46:47], v[48:49], v[46:47]
	v_pk_add_f32 v[48:49], v[50:51], 1.0 op_sel_hi:[1,0]
	v_pk_mul_f32 v[50:51], v[44:45], s[20:21] op_sel_hi:[1,0]
	v_exp_f32_e32 v50, v50
	v_exp_f32_e32 v51, v51
	v_rcp_f32_e32 v48, v48
	v_rcp_f32_e32 v49, v49
	v_pk_add_f32 v[50:51], v[50:51], 1.0 op_sel_hi:[1,0]
	v_rcp_f32_e32 v50, v50
	v_rcp_f32_e32 v51, v51
	v_pk_mul_f32 v[42:43], v[42:43], v[48:49]
	v_pk_mul_f32 v[40:41], v[46:47], v[40:41]
	v_pk_mul_f32 v[42:43], v[42:43], v[34:35]
	v_pk_mul_f32 v[34:35], v[44:45], v[50:51]
	s_nop 0
	v_pk_mul_f32 v[44:45], v[34:35], v[36:37]
	v_mad_i64_i32 v[34:35], s[16:17], v52, s74, v[114:115]
	v_mul_f32_e32 v36, 0xbfb8aa3b, v30
	v_lshl_add_u64 v[34:35], v[34:35], 0, s[14:15]
	v_exp_f32_e32 v37, v36
	v_mul_f32_e32 v36, 0xbfb8aa3b, v31
	v_lshl_add_u64 v[46:47], v[34:35], 0, v[138:139]
	v_cvt_pk_bf16_f32 v34, v38, v39
	v_exp_f32_e32 v39, v36
	v_add_f32_e32 v37, 1.0, v37
	v_rcp_f32_e32 v38, v37
	v_cvt_pk_bf16_f32 v35, v40, v41
	v_add_f32_e32 v37, 1.0, v39
	v_cvt_pk_bf16_f32 v36, v42, v43
	v_rcp_f32_e32 v39, v37
	v_cvt_pk_bf16_f32 v37, v44, v45
	global_store_dwordx4 v[46:47], v[34:37], off nt
	v_pk_mul_f32 v[30:31], v[30:31], v[38:39]
	s_nop 0
	v_pk_mul_f32 v[34:35], v[32:33], s[20:21] op_sel_hi:[1,0]
	v_exp_f32_e32 v34, v34
	v_exp_f32_e32 v35, v35
	v_pk_mul_f32 v[22:23], v[30:31], v[22:23]
	v_add_u32_e32 v36, 0xa0, v154
	v_pk_add_f32 v[30:31], v[34:35], 1.0 op_sel_hi:[1,0]
	v_pk_mul_f32 v[34:35], v[26:27], s[20:21] op_sel_hi:[1,0]
	v_rcp_f32_e32 v30, v30
	v_rcp_f32_e32 v31, v31
	v_exp_f32_e32 v34, v34
	v_exp_f32_e32 v35, v35
	v_pk_mul_f32 v[30:31], v[32:33], v[30:31]
	v_pk_add_f32 v[32:33], v[34:35], 1.0 op_sel_hi:[1,0]
	v_pk_mul_f32 v[34:35], v[28:29], s[20:21] op_sel_hi:[1,0]
	v_exp_f32_e32 v34, v34
	v_exp_f32_e32 v35, v35
	v_rcp_f32_e32 v32, v32
	v_rcp_f32_e32 v33, v33
	v_pk_add_f32 v[34:35], v[34:35], 1.0 op_sel_hi:[1,0]
	v_rcp_f32_e32 v34, v34
	v_rcp_f32_e32 v35, v35
	v_pk_mul_f32 v[26:27], v[26:27], v[32:33]
	v_pk_mul_f32 v[24:25], v[30:31], v[24:25]
	v_pk_mul_f32 v[26:27], v[26:27], v[18:19]
	v_pk_mul_f32 v[18:19], v[28:29], v[34:35]
	s_nop 0
	v_pk_mul_f32 v[28:29], v[18:19], v[20:21]
	v_mad_i64_i32 v[18:19], s[16:17], v36, s74, v[114:115]
	v_mul_f32_e32 v20, 0xbfb8aa3b, v14
	v_lshl_add_u64 v[18:19], v[18:19], 0, s[14:15]
	v_exp_f32_e32 v21, v20
	v_mul_f32_e32 v20, 0xbfb8aa3b, v15
	v_lshl_add_u64 v[30:31], v[18:19], 0, v[138:139]
	v_cvt_pk_bf16_f32 v18, v22, v23
	v_exp_f32_e32 v23, v20
	v_add_f32_e32 v21, 1.0, v21
	v_rcp_f32_e32 v22, v21
	v_cvt_pk_bf16_f32 v19, v24, v25
	v_add_f32_e32 v21, 1.0, v23
	v_cvt_pk_bf16_f32 v20, v26, v27
	v_rcp_f32_e32 v23, v21
	v_cvt_pk_bf16_f32 v21, v28, v29
	global_store_dwordx4 v[30:31], v[18:21], off nt
	v_pk_mul_f32 v[14:15], v[14:15], v[22:23]
	s_nop 0
	v_pk_mul_f32 v[18:19], v[16:17], s[20:21] op_sel_hi:[1,0]
	v_exp_f32_e32 v18, v18
	v_exp_f32_e32 v19, v19
	v_pk_mul_f32 v[6:7], v[14:15], v[6:7]
	v_add_u32_e32 v20, 0xb0, v154
	v_pk_add_f32 v[14:15], v[18:19], 1.0 op_sel_hi:[1,0]
	v_pk_mul_f32 v[18:19], v[10:11], s[20:21] op_sel_hi:[1,0]
	v_rcp_f32_e32 v14, v14
	v_rcp_f32_e32 v15, v15
	v_exp_f32_e32 v18, v18
	v_exp_f32_e32 v19, v19
	v_pk_mul_f32 v[14:15], v[16:17], v[14:15]
	v_pk_add_f32 v[16:17], v[18:19], 1.0 op_sel_hi:[1,0]
	v_pk_mul_f32 v[18:19], v[12:13], s[20:21] op_sel_hi:[1,0]
	v_exp_f32_e32 v18, v18
	v_exp_f32_e32 v19, v19
	v_rcp_f32_e32 v16, v16
	v_rcp_f32_e32 v17, v17
	v_pk_add_f32 v[18:19], v[18:19], 1.0 op_sel_hi:[1,0]
	v_rcp_f32_e32 v18, v18
	v_rcp_f32_e32 v19, v19
	v_pk_mul_f32 v[10:11], v[10:11], v[16:17]
	v_pk_mul_f32 v[8:9], v[14:15], v[8:9]
	v_pk_mul_f32 v[10:11], v[10:11], v[2:3]
	v_pk_mul_f32 v[2:3], v[12:13], v[18:19]
	s_nop 0
	v_pk_mul_f32 v[12:13], v[2:3], v[4:5]
	v_mad_i64_i32 v[2:3], s[16:17], v20, s74, v[114:115]
	v_lshl_add_u64 v[2:3], v[2:3], 0, s[14:15]
	v_lshl_add_u64 v[14:15], v[2:3], 0, v[138:139]
	v_cvt_pk_bf16_f32 v2, v6, v7
	v_cvt_pk_bf16_f32 v3, v8, v9
	v_cvt_pk_bf16_f32 v4, v10, v11
	v_cvt_pk_bf16_f32 v5, v12, v13
	s_mov_b32 s15, s6
	s_mov_b32 s14, s8
	s_mov_b64 s[16:17], s[10:11]
	global_store_dwordx4 v[14:15], v[2:5], off nt
	s_cmpk_gt_u32 s33, 0xff
	s_cbranch_scc0 .Ldfr_p2_c
	s_barrier

.Ldfr_p5_b:
	s_mov_b32 s20, 0xbfb8aa3b
	s_setprio 0
	s_min_i32 s3, s4, 0x80
	s_ashr_i32 s5, s3, 3
	s_lshl_b32 s3, s2, 8
	s_mul_hi_i32 s19, s5, 0x6000
	s_mulk_i32 s5, 0x6000
	v_or_b32_e32 v186, s3, v224
	s_add_u32 s18, s77, s5
	s_addc_u32 s19, s78, s19
	v_ashrrev_i32_e32 v187, 31, v186
	v_lshl_add_u64 v[10:11], v[186:187], 2, s[18:19]
	global_load_dwordx4 v[50:53], v[10:11], off offset:16
	global_load_dwordx4 v[54:57], v[10:11], off
	global_load_dwordx4 v[26:29], v[10:11], off offset:528
	global_load_dwordx4 v[30:33], v[10:11], off offset:512
	s_add_i32 s5, s2, -2
	s_cmp_gt_u32 s5, 3
	s_cbranch_scc1 .LBB0_1378
	v_lshl_add_u64 v[14:15], v[186:187], 2, s[6:7]
	global_load_dwordx4 v[38:41], v[14:15], off offset:-2048
	global_load_dwordx4 v[34:37], v[14:15], off offset:-2032
	global_load_dwordx4 v[10:13], v[14:15], off offset:-1536
	s_nop 0
	global_load_dwordx4 v[14:17], v[14:15], off offset:-1520
.LBB0_1378:
	s_lshl_b32 s41, s4, 8
	s_add_i32 s41, s41, s94
	v_or_b32_e32 v204, s41, v171
	v_or_b32_e32 v214, 16, v204
	v_or_b32_e32 v210, 32, v204
	v_or_b32_e32 v206, 48, v204
	v_add_u32_e32 v198, 0x90, v204
	v_ashrrev_i32_e32 v205, 31, v204
	v_ashrrev_i32_e32 v215, 31, v214
	v_ashrrev_i32_e32 v211, 31, v210
	v_ashrrev_i32_e32 v207, 31, v206
	v_ashrrev_i32_e32 v199, 31, v198
	v_add_u32_e32 v194, 0xa0, v204
	v_add_u32_e32 v188, 0xb0, v204
	v_lshl_add_u64 v[192:193], v[204:205], 2, s[0:1]
	v_lshl_add_u64 v[190:191], v[214:215], 2, s[0:1]
	v_lshl_add_u64 v[196:197], v[210:211], 2, s[0:1]
	v_lshl_add_u64 v[200:201], v[206:207], 2, s[0:1]
	v_lshl_add_u64 v[202:203], v[198:199], 2, s[0:1]
	v_ashrrev_i32_e32 v195, 31, v194
	v_ashrrev_i32_e32 v189, 31, v188
	v_lshl_add_u64 v[220:221], v[194:195], 2, s[0:1]
	v_lshl_add_u64 v[222:223], v[188:189], 2, s[0:1]
	global_load_dword v218, v[192:193], off
	global_load_dword v216, v[190:191], off
	global_load_dword v212, v[196:197], off
	global_load_dword v208, v[200:201], off
	s_nop 0
	global_load_dword v200, v[202:203], off
	global_load_dword v196, v[220:221], off
	global_load_dword v190, v[222:223], off
	s_nop 0
	global_load_dword v202, v[192:193], off offset:512
	s_ashr_i32 s39, s2, 1
	s_cmpk_gt_u32 s3, 0x1ff
	v_add_u32_e32 v176, 0xfffff600, v186
	s_cselect_b64 s[2:3], -1, 0
	s_cmp_gt_i32 s39, 2
	v_ashrrev_i32_e32 v192, 3, v176
	s_cselect_b64 s[34:35], -1, 0
	s_cmp_gt_u32 s39, 7
	v_ashrrev_i32_e32 v193, 31, v192
	s_cselect_b64 s[56:57], -1, 0
	s_cmp_eq_u32 s39, 1
	v_and_b32_e32 v191, 0x178, v186
	s_waitcnt vmcnt(0)
	v_sub_f32_e32 v242, 1.0, v38
	v_sub_f32_e32 v241, 1.0, v39
	v_sub_f32_e32 v240, 1.0, v40
	v_sub_f32_e32 v239, 1.0, v41
	v_sub_f32_e32 v238, 1.0, v34
	v_sub_f32_e32 v234, 1.0, v35
	v_sub_f32_e32 v233, 1.0, v36
	v_sub_f32_e32 v229, 1.0, v37
	s_mov_b64 s[4:5], -1
	v_lshlrev_b64 v[192:193], 15, v[192:193]
	s_cselect_b64 s[54:55], -1, 0
	s_and_b64 vcc, exec, s[2:3]
	v_pk_fma_f32 v[220:221], v[158:159], v[218:219], v[54:55] op_sel_hi:[1,0,1]
	v_pk_fma_f32 v[160:161], v[160:161], v[218:219], v[56:57] op_sel_hi:[1,0,1]
	v_pk_fma_f32 v[154:155], v[154:155], v[218:219], v[50:51] op_sel_hi:[1,0,1]
	v_pk_fma_f32 v[222:223], v[156:157], v[218:219], v[52:53] op_sel_hi:[1,0,1]
	s_cbranch_vccz .LBB0_1396
	s_and_b64 vcc, exec, s[34:35]
	s_cbranch_vccz .LBB0_1393
	s_cmp_lt_i32 s39, 4
	s_cbranch_scc1 .LBB0_1390
	s_cmp_lg_u32 s39, 4
	s_cbranch_scc0 .LBB0_1387
	s_andn2_b64 vcc, exec, s[56:57]
	s_cbranch_vccnz .LBB0_1384
	v_pk_mul_f32 v[156:157], v[220:221], s[20:21] op_sel_hi:[1,0]
	v_exp_f32_e32 v156, v156
	v_exp_f32_e32 v157, v157
	v_mul_f32_e32 v159, 0xbfb8aa3b, v161
	v_exp_f32_e32 v159, v159
	v_pk_add_f32 v[156:157], v[156:157], 1.0 op_sel_hi:[1,0]
	v_rcp_f32_e32 v156, v156
	v_rcp_f32_e32 v157, v157
	v_mul_f32_e32 v158, 0xbfb8aa3b, v160
	v_mul_f32_e32 v203, 0xbfb8aa3b, v223
	v_max_f32_e32 v176, 0x219392ef, v156
	v_max_f32_e32 v197, 0x219392ef, v157
	v_add_f32_e32 v156, 1.0, v159
	v_mul_f32_e32 v157, 0xbfb8aa3b, v154
	v_mul_f32_e32 v159, 0xbfb8aa3b, v155
	v_rcp_f32_e32 v156, v156
	v_exp_f32_e32 v157, v157
	v_exp_f32_e32 v159, v159
	v_exp_f32_e32 v158, v158
	v_max_f32_e32 v201, 0x219392ef, v156
	v_add_f32_e32 v156, 1.0, v157
	v_add_f32_e32 v157, 1.0, v159
	v_mul_f32_e32 v159, 0xbfb8aa3b, v222
	v_exp_f32_e32 v159, v159
	v_exp_f32_e32 v203, v203
	v_rcp_f32_e32 v156, v156
	v_rcp_f32_e32 v157, v157
	v_pk_add_f32 v[158:159], v[158:159], 1.0 op_sel_hi:[1,0]
	v_add_f32_e32 v203, 1.0, v203
	v_rcp_f32_e32 v158, v158
	v_rcp_f32_e32 v159, v159
	v_rcp_f32_e32 v203, v203
	v_max_f32_e32 v209, 0x219392ef, v156
	v_max_f32_e32 v213, 0x219392ef, v157
	v_lshlrev_b64 v[156:157], 12, v[204:205]
	v_lshl_add_u64 v[156:157], s[16:17], 0, v[156:157]
	v_lshl_add_u64 v[236:237], v[186:187], 1, v[156:157]
	v_max_f32_e32 v158, 0x219392ef, v158
	v_max_f32_e32 v159, 0x219392ef, v159
	v_max_f32_e32 v203, 0x219392ef, v203
	v_add_co_u32_e32 v236, vcc, 0xffffe000, v236
	v_cvt_pk_bf16_f32 v156, v176, v197
	v_cvt_pk_bf16_f32 v157, v158, v201
	v_cvt_pk_bf16_f32 v158, v209, v213
	v_cvt_pk_bf16_f32 v159, v159, v203
	v_addc_co_u32_e32 v237, vcc, -1, v237, vcc
	s_mov_b64 s[4:5], 0
	global_store_dwordx4 v[236:237], v[156:159], off nt
	s_nop 1
	v_lshlrev_b64 v[158:159], 10, v[204:205]
	v_lshl_add_u64 v[156:157], s[8:9], 0, v[158:159]
	s_branch .LBB0_1398

.LBB0_1387:
	s_andn2_b64 vcc, exec, s[4:5]
	s_cbranch_vccnz .LBB0_1389
	v_mul_f32_e32 v176, 0xbfb8aa3b, v154
	v_exp_f32_e32 v176, v176
	v_mul_f32_e32 v197, 0xbfb8aa3b, v155
	v_exp_f32_e32 v197, v197
	v_add_f32_e32 v176, 1.0, v176
	v_rcp_f32_e32 v236, v176
	v_add_f32_e32 v176, 1.0, v197
	v_mul_f32_e32 v197, 0xbfb8aa3b, v222
	v_pk_mul_f32 v[156:157], v[220:221], s[20:21] op_sel_hi:[1,0]
	v_pk_mul_f32 v[158:159], v[160:161], s[20:21] op_sel_hi:[1,0]
	v_exp_f32_e32 v197, v197
	v_mul_f32_e32 v201, 0xbfb8aa3b, v223
	v_exp_f32_e32 v156, v156
	v_exp_f32_e32 v157, v157
	v_exp_f32_e32 v158, v158
	v_exp_f32_e32 v159, v159
	v_exp_f32_e32 v201, v201
	v_rcp_f32_e32 v237, v176
	v_add_f32_e32 v176, 1.0, v197
	v_pk_add_f32 v[156:157], v[156:157], 1.0 op_sel_hi:[1,0]
	v_pk_add_f32 v[158:159], v[158:159], 1.0 op_sel_hi:[1,0]
	v_rcp_f32_e32 v244, v176
	v_add_f32_e32 v176, 1.0, v201
	v_rcp_f32_e32 v156, v156
	v_rcp_f32_e32 v157, v157
	v_rcp_f32_e32 v158, v158
	v_rcp_f32_e32 v159, v159
	v_rcp_f32_e32 v245, v176
	v_lshlrev_b64 v[246:247], 10, v[204:205]
	v_pk_mul_f32 v[156:157], v[220:221], v[156:157]
	v_pk_mul_f32 v[158:159], v[160:161], v[158:159]
	v_pk_mul_f32 v[236:237], v[154:155], v[236:237]
	v_pk_mul_f32 v[244:245], v[222:223], v[244:245]
	v_lshl_add_u64 v[246:247], s[12:13], 0, v[246:247]
	v_lshl_add_u64 v[246:247], v[186:187], 1, v[246:247]
	v_cvt_pk_bf16_f32 v156, v156, v157
	v_cvt_pk_bf16_f32 v157, v158, v159
	v_cvt_pk_bf16_f32 v158, v236, v237
	v_cvt_pk_bf16_f32 v159, v244, v245
	global_store_dwordx4 v[246:247], v[156:159], off offset:-4096 nt
	s_nop 1
	v_lshlrev_b64 v[158:159], 10, v[204:205]
	v_lshl_add_u64 v[156:157], s[8:9], 0, v[158:159]
	s_branch .LBB0_1398

.LBB0_1390:
	s_andn2_b64 vcc, exec, s[4:5]
	s_cbranch_vccnz .LBB0_1392
	v_mul_f32_e32 v176, 0xbfb8aa3b, v154
	v_exp_f32_e32 v176, v176
	v_mul_f32_e32 v197, 0xbfb8aa3b, v155
	v_exp_f32_e32 v197, v197
	v_add_f32_e32 v176, 1.0, v176
	v_rcp_f32_e32 v236, v176
	v_add_f32_e32 v176, 1.0, v197
	v_mul_f32_e32 v197, 0xbfb8aa3b, v222
	v_pk_mul_f32 v[156:157], v[220:221], s[20:21] op_sel_hi:[1,0]
	v_pk_mul_f32 v[158:159], v[160:161], s[20:21] op_sel_hi:[1,0]
	v_exp_f32_e32 v197, v197
	v_mul_f32_e32 v201, 0xbfb8aa3b, v223
	v_exp_f32_e32 v156, v156
	v_exp_f32_e32 v157, v157
	v_exp_f32_e32 v158, v158
	v_exp_f32_e32 v159, v159
	v_exp_f32_e32 v201, v201
	v_rcp_f32_e32 v237, v176
	v_add_f32_e32 v176, 1.0, v197
	v_pk_add_f32 v[156:157], v[156:157], 1.0 op_sel_hi:[1,0]
	v_pk_add_f32 v[158:159], v[158:159], 1.0 op_sel_hi:[1,0]
	v_rcp_f32_e32 v244, v176
	v_add_f32_e32 v176, 1.0, v201
	v_rcp_f32_e32 v156, v156
	v_rcp_f32_e32 v157, v157
	v_rcp_f32_e32 v158, v158
	v_rcp_f32_e32 v159, v159
	v_rcp_f32_e32 v245, v176
	v_lshlrev_b64 v[246:247], 10, v[204:205]
	v_pk_mul_f32 v[156:157], v[220:221], v[156:157]
	v_pk_mul_f32 v[158:159], v[160:161], v[158:159]
	v_pk_mul_f32 v[236:237], v[154:155], v[236:237]
	v_pk_mul_f32 v[244:245], v[222:223], v[244:245]
	v_lshl_add_u64 v[246:247], s[10:11], 0, v[246:247]
	v_lshl_add_u64 v[246:247], v[186:187], 1, v[246:247]
	v_cvt_pk_bf16_f32 v156, v156, v157
	v_cvt_pk_bf16_f32 v157, v158, v159
	v_cvt_pk_bf16_f32 v158, v236, v237
	v_cvt_pk_bf16_f32 v159, v244, v245
	global_store_dwordx4 v[246:247], v[156:159], off offset:-3072 nt
	s_nop 1
	v_lshlrev_b64 v[158:159], 10, v[204:205]
	v_lshl_add_u64 v[156:157], s[8:9], 0, v[158:159]
	s_branch .LBB0_1398

.LBB0_1393:
	s_and_b64 vcc, exec, s[4:5]
	s_cbranch_vccz .LBB0_1395
	v_mul_f32_e32 v158, 0xbfb8aa3b, v160
	v_exp_f32_e32 v158, v158
	v_mul_f32_e32 v159, 0xbfb8aa3b, v161
	v_mul_f32_e32 v176, 0xbfb8aa3b, v154
	v_exp_f32_e32 v159, v159
	v_add_f32_e32 v158, 1.0, v158
	v_rcp_f32_e32 v158, v158
	v_exp_f32_e32 v176, v176
	v_mul_f32_e32 v203, 0xbfb8aa3b, v223
	v_fma_f32 v158, v240, v158, v40
	v_log_f32_e32 v197, v158
	v_add_f32_e32 v158, 1.0, v159
	v_add_f32_e32 v159, 1.0, v176
	v_rcp_f32_e32 v159, v159
	v_mul_f32_e32 v176, 0xbfb8aa3b, v155
	v_exp_f32_e32 v176, v176
	v_pk_mul_f32 v[156:157], v[220:221], s[20:21] op_sel_hi:[1,0]
	v_fma_f32 v159, v238, v159, v34
	v_log_f32_e32 v201, v159
	v_add_f32_e32 v159, 1.0, v176
	v_mul_f32_e32 v176, 0xbfb8aa3b, v222
	v_exp_f32_e32 v176, v176
	v_exp_f32_e32 v203, v203
	v_exp_f32_e32 v156, v156
	v_exp_f32_e32 v157, v157
	v_add_f32_e32 v176, 1.0, v176
	v_add_f32_e32 v203, 1.0, v203
	v_pk_add_f32 v[156:157], v[156:157], 1.0 op_sel_hi:[1,0]
	v_rcp_f32_e32 v176, v176
	v_rcp_f32_e32 v203, v203
	v_rcp_f32_e32 v156, v156
	v_rcp_f32_e32 v157, v157
	v_rcp_f32_e32 v158, v158
	v_rcp_f32_e32 v159, v159
	v_fma_f32 v176, v233, v176, v36
	v_fma_f32 v203, v229, v203, v37
	v_fma_f32 v156, v242, v156, v38
	v_fma_f32 v157, v241, v157, v39
	v_fma_f32 v158, v239, v158, v41
	v_fma_f32 v159, v234, v159, v35
	v_log_f32_e32 v176, v176
	v_log_f32_e32 v203, v203
	v_log_f32_e32 v156, v156
	v_log_f32_e32 v209, v159
	v_log_f32_e32 v213, v158
	v_log_f32_e32 v217, v157
	s_and_b64 s[4:5], s[54:55], exec
	s_cselect_b32 s5, s87, s92
	s_cselect_b32 s4, s79, s89
	v_lshlrev_b64 v[236:237], 10, v[204:205]
	v_cvt_pk_f16_f32 v159, v176, v203
	v_lshl_add_u64 v[236:237], s[4:5], 0, v[236:237]
	v_lshlrev_b32_e32 v176, 1, v191
	v_cvt_pk_f16_f32 v158, v201, v209
	v_cvt_pk_f16_f32 v157, v197, v213
	v_cvt_pk_f16_f32 v156, v156, v217
	v_lshl_add_u64 v[236:237], v[236:237], 0, v[176:177]
	global_store_dwordx4 v[236:237], v[156:159], off
	s_nop 1
	v_lshlrev_b64 v[158:159], 10, v[204:205]
	v_lshl_add_u64 v[156:157], s[8:9], 0, v[158:159]
	s_branch .LBB0_1398

.LBB0_1418:
	v_pk_fma_f32 v[146:147], v[138:139], v[216:217], v[50:51] op_sel_hi:[1,0,1]
	v_cndmask_b32_e64 v138, 0, 1, s[2:3]
	v_cmp_ne_u32_e64 s[4:5], 1, v138
	v_cndmask_b32_e64 v138, 0, 1, s[34:35]
	v_pk_fma_f32 v[142:143], v[142:143], v[216:217], v[54:55] op_sel_hi:[1,0,1]
	v_pk_fma_f32 v[144:145], v[144:145], v[216:217], v[56:57] op_sel_hi:[1,0,1]
	v_pk_fma_f32 v[140:141], v[140:141], v[216:217], v[52:53] op_sel_hi:[1,0,1]
	s_mov_b64 s[18:19], -1
	s_andn2_b64 vcc, exec, s[2:3]
	v_cmp_ne_u32_e64 s[2:3], 1, v138
	s_cbranch_vccnz .LBB0_1436
	s_and_b64 vcc, exec, s[2:3]
	s_cbranch_vccnz .LBB0_1433
	s_cmp_lt_i32 s39, 4
	s_cbranch_scc1 .LBB0_1430
	s_cmp_lg_u32 s39, 4
	s_cbranch_scc0 .LBB0_1427
	s_andn2_b64 vcc, exec, s[56:57]
	s_cbranch_vccnz .LBB0_1424
	v_pk_mul_f32 v[138:139], v[142:143], s[20:21] op_sel_hi:[1,0]
	v_mul_f32_e32 v148, 0xbfb8aa3b, v144
	v_exp_f32_e32 v138, v138
	v_exp_f32_e32 v139, v139
	v_exp_f32_e32 v148, v148
	v_mul_f32_e32 v149, 0xbfb8aa3b, v145
	v_pk_add_f32 v[138:139], v[138:139], 1.0 op_sel_hi:[1,0]
	v_add_f32_e32 v148, 1.0, v148
	v_rcp_f32_e32 v138, v138
	v_rcp_f32_e32 v139, v139
	v_rcp_f32_e32 v148, v148
	v_exp_f32_e32 v149, v149
	v_max_f32_e32 v150, 0x219392ef, v138
	v_max_f32_e32 v151, 0x219392ef, v139
	v_max_f32_e32 v152, 0x219392ef, v148
	v_add_f32_e32 v138, 1.0, v149
	v_mul_f32_e32 v139, 0xbfb8aa3b, v146
	v_mul_f32_e32 v148, 0xbfb8aa3b, v147
	v_rcp_f32_e32 v138, v138
	v_exp_f32_e32 v139, v139
	v_exp_f32_e32 v148, v148
	v_mul_f32_e32 v153, 0xbfb8aa3b, v141
	v_max_f32_e32 v149, 0x219392ef, v138
	v_add_f32_e32 v138, 1.0, v139
	v_add_f32_e32 v139, 1.0, v148
	v_mul_f32_e32 v148, 0xbfb8aa3b, v140
	v_exp_f32_e32 v148, v148
	v_exp_f32_e32 v153, v153
	v_rcp_f32_e32 v138, v138
	v_rcp_f32_e32 v139, v139
	v_add_f32_e32 v148, 1.0, v148
	v_add_f32_e32 v153, 1.0, v153
	v_rcp_f32_e32 v148, v148
	v_rcp_f32_e32 v153, v153
	v_max_f32_e32 v156, 0x219392ef, v138
	v_max_f32_e32 v157, 0x219392ef, v139
	v_lshlrev_b64 v[138:139], 12, v[214:215]
	v_lshl_add_u64 v[138:139], s[16:17], 0, v[138:139]
	v_lshl_add_u64 v[138:139], v[186:187], 1, v[138:139]
	v_max_f32_e32 v158, 0x219392ef, v148
	v_max_f32_e32 v153, 0x219392ef, v153
	v_add_co_u32_e32 v138, vcc, 0xffffe000, v138
	v_cvt_pk_bf16_f32 v148, v150, v151
	v_cvt_pk_bf16_f32 v149, v152, v149
	v_cvt_pk_bf16_f32 v150, v156, v157
	v_cvt_pk_bf16_f32 v151, v158, v153
	v_addc_co_u32_e32 v139, vcc, -1, v139, vcc
	s_mov_b64 s[18:19], 0
	global_store_dwordx4 v[138:139], v[148:151], off nt
	s_nop 1
	v_lshlrev_b64 v[148:149], 10, v[214:215]
	v_lshl_add_u64 v[138:139], s[8:9], 0, v[148:149]
	s_branch .LBB0_1438

.LBB0_1427:
	s_andn2_b64 vcc, exec, s[18:19]
	s_cbranch_vccnz .LBB0_1429
	v_pk_mul_f32 v[148:149], v[144:145], s[20:21] op_sel_hi:[1,0]
	v_pk_mul_f32 v[138:139], v[142:143], s[20:21] op_sel_hi:[1,0]
	v_exp_f32_e32 v148, v148
	v_exp_f32_e32 v149, v149
	v_pk_mul_f32 v[150:151], v[146:147], s[20:21] op_sel_hi:[1,0]
	v_pk_mul_f32 v[152:153], v[140:141], s[20:21] op_sel_hi:[1,0]
	v_exp_f32_e32 v138, v138
	v_exp_f32_e32 v139, v139
	v_exp_f32_e32 v150, v150
	v_exp_f32_e32 v151, v151
	v_exp_f32_e32 v152, v152
	v_exp_f32_e32 v153, v153
	v_pk_add_f32 v[148:149], v[148:149], 1.0 op_sel_hi:[1,0]
	v_pk_add_f32 v[138:139], v[138:139], 1.0 op_sel_hi:[1,0]
	v_rcp_f32_e32 v148, v148
	v_rcp_f32_e32 v149, v149
	v_pk_add_f32 v[150:151], v[150:151], 1.0 op_sel_hi:[1,0]
	v_pk_add_f32 v[152:153], v[152:153], 1.0 op_sel_hi:[1,0]
	v_rcp_f32_e32 v138, v138
	v_rcp_f32_e32 v139, v139
	v_rcp_f32_e32 v150, v150
	v_rcp_f32_e32 v151, v151
	v_rcp_f32_e32 v152, v152
	v_rcp_f32_e32 v153, v153
	v_pk_mul_f32 v[156:157], v[144:145], v[148:149]
	v_lshlrev_b64 v[148:149], 10, v[214:215]
	v_pk_mul_f32 v[138:139], v[142:143], v[138:139]
	v_pk_mul_f32 v[150:151], v[146:147], v[150:151]
	v_pk_mul_f32 v[152:153], v[140:141], v[152:153]
	v_lshl_add_u64 v[148:149], s[12:13], 0, v[148:149]
	v_lshl_add_u64 v[158:159], v[186:187], 1, v[148:149]
	v_cvt_pk_bf16_f32 v148, v138, v139
	v_cvt_pk_bf16_f32 v149, v156, v157
	v_cvt_pk_bf16_f32 v150, v150, v151
	v_cvt_pk_bf16_f32 v151, v152, v153
	global_store_dwordx4 v[158:159], v[148:151], off offset:-4096 nt
	s_nop 1
	v_lshlrev_b64 v[148:149], 10, v[214:215]
	v_lshl_add_u64 v[138:139], s[8:9], 0, v[148:149]
	s_branch .LBB0_1438

.LBB0_1430:
	s_andn2_b64 vcc, exec, s[18:19]
	s_cbranch_vccnz .LBB0_1432
	v_pk_mul_f32 v[148:149], v[144:145], s[20:21] op_sel_hi:[1,0]
	v_pk_mul_f32 v[138:139], v[142:143], s[20:21] op_sel_hi:[1,0]
	v_exp_f32_e32 v148, v148
	v_exp_f32_e32 v149, v149
	v_pk_mul_f32 v[150:151], v[146:147], s[20:21] op_sel_hi:[1,0]
	v_pk_mul_f32 v[152:153], v[140:141], s[20:21] op_sel_hi:[1,0]
	v_exp_f32_e32 v138, v138
	v_exp_f32_e32 v139, v139
	v_exp_f32_e32 v150, v150
	v_exp_f32_e32 v151, v151
	v_exp_f32_e32 v152, v152
	v_exp_f32_e32 v153, v153
	v_pk_add_f32 v[148:149], v[148:149], 1.0 op_sel_hi:[1,0]
	v_pk_add_f32 v[138:139], v[138:139], 1.0 op_sel_hi:[1,0]
	v_rcp_f32_e32 v148, v148
	v_rcp_f32_e32 v149, v149
	v_pk_add_f32 v[150:151], v[150:151], 1.0 op_sel_hi:[1,0]
	v_pk_add_f32 v[152:153], v[152:153], 1.0 op_sel_hi:[1,0]
	v_rcp_f32_e32 v138, v138
	v_rcp_f32_e32 v139, v139
	v_rcp_f32_e32 v150, v150
	v_rcp_f32_e32 v151, v151
	v_rcp_f32_e32 v152, v152
	v_rcp_f32_e32 v153, v153
	v_pk_mul_f32 v[156:157], v[144:145], v[148:149]
	v_lshlrev_b64 v[148:149], 10, v[214:215]
	v_pk_mul_f32 v[138:139], v[142:143], v[138:139]
	v_pk_mul_f32 v[150:151], v[146:147], v[150:151]
	v_pk_mul_f32 v[152:153], v[140:141], v[152:153]
	v_lshl_add_u64 v[148:149], s[10:11], 0, v[148:149]
	v_lshl_add_u64 v[158:159], v[186:187], 1, v[148:149]
	v_cvt_pk_bf16_f32 v148, v138, v139
	v_cvt_pk_bf16_f32 v149, v156, v157
	v_cvt_pk_bf16_f32 v150, v150, v151
	v_cvt_pk_bf16_f32 v151, v152, v153
	global_store_dwordx4 v[158:159], v[148:151], off offset:-3072 nt
	s_nop 1
	v_lshlrev_b64 v[148:149], 10, v[214:215]
	v_lshl_add_u64 v[138:139], s[8:9], 0, v[148:149]
	s_branch .LBB0_1438

.LBB0_1433:
	s_and_b64 vcc, exec, s[18:19]
	s_cbranch_vccz .LBB0_1435
	v_mul_f32_e32 v150, 0xbfb8aa3b, v144
	v_exp_f32_e32 v150, v150
	v_mul_f32_e32 v151, 0xbfb8aa3b, v145
	v_mul_f32_e32 v152, 0xbfb8aa3b, v146
	v_exp_f32_e32 v151, v151
	v_add_f32_e32 v150, 1.0, v150
	v_rcp_f32_e32 v150, v150
	v_exp_f32_e32 v152, v152
	v_mul_f32_e32 v138, 0xbfb8aa3b, v142
	v_mul_f32_e32 v149, 0xbfb8aa3b, v143
	v_fma_f32 v150, v240, v150, v40
	v_log_f32_e32 v153, v150
	v_add_f32_e32 v150, 1.0, v151
	v_add_f32_e32 v151, 1.0, v152
	v_rcp_f32_e32 v151, v151
	v_mul_f32_e32 v152, 0xbfb8aa3b, v147
	v_exp_f32_e32 v152, v152
	v_exp_f32_e32 v148, v138
	v_fma_f32 v151, v238, v151, v34
	v_exp_f32_e32 v149, v149
	v_log_f32_e32 v156, v151
	v_add_f32_e32 v151, 1.0, v152
	v_mul_f32_e32 v152, 0xbfb8aa3b, v140
	v_mul_f32_e32 v157, 0xbfb8aa3b, v141
	v_exp_f32_e32 v152, v152
	v_exp_f32_e32 v157, v157
	v_pk_add_f32 v[148:149], v[148:149], 1.0 op_sel_hi:[1,0]
	v_rcp_f32_e32 v148, v148
	v_rcp_f32_e32 v149, v149
	v_add_f32_e32 v152, 1.0, v152
	v_add_f32_e32 v157, 1.0, v157
	v_rcp_f32_e32 v150, v150
	v_rcp_f32_e32 v151, v151
	v_rcp_f32_e32 v152, v152
	v_rcp_f32_e32 v157, v157
	v_fma_f32 v148, v242, v148, v38
	v_fma_f32 v149, v241, v149, v39
	v_log_f32_e32 v148, v148
	v_fma_f32 v150, v239, v150, v41
	v_fma_f32 v151, v234, v151, v35
	v_fma_f32 v152, v233, v152, v36
	v_fma_f32 v157, v229, v157, v37
	v_log_f32_e32 v176, v149
	v_log_f32_e32 v152, v152
	v_log_f32_e32 v157, v157
	v_log_f32_e32 v158, v151
	v_log_f32_e32 v159, v150
	s_and_b64 s[18:19], s[54:55], exec
	s_cselect_b32 s19, s87, s92
	s_cselect_b32 s18, s79, s89
	v_lshlrev_b64 v[138:139], 10, v[214:215]
	v_cvt_pk_f16_f32 v148, v148, v176
	v_lshl_add_u64 v[138:139], s[18:19], 0, v[138:139]
	v_lshlrev_b32_e32 v176, 1, v191
	v_cvt_pk_f16_f32 v151, v152, v157
	v_cvt_pk_f16_f32 v150, v156, v158
	v_cvt_pk_f16_f32 v149, v153, v159
	v_lshl_add_u64 v[138:139], v[138:139], 0, v[176:177]
	global_store_dwordx4 v[138:139], v[148:151], off
	s_nop 1
	v_lshlrev_b64 v[148:149], 10, v[214:215]
	v_lshl_add_u64 v[138:139], s[8:9], 0, v[148:149]
	s_branch .LBB0_1438

.LBB0_1438:
	v_mov_b32_e32 v217, v216
	v_pk_fma_f32 v[134:135], v[134:135], v[216:217], v[30:31]
	v_pk_fma_f32 v[136:137], v[136:137], v[216:217], v[32:33]
	v_pk_fma_f32 v[130:131], v[130:131], v[216:217], v[26:27]
	v_pk_fma_f32 v[132:133], v[132:133], v[216:217], v[28:29]
	s_and_b64 vcc, exec, s[4:5]
	s_mov_b64 s[18:19], -1
	s_cbranch_vccnz .LBB0_1456
	s_and_b64 vcc, exec, s[2:3]
	s_cbranch_vccnz .LBB0_1453
	s_cmp_lt_i32 s39, 4
	s_cbranch_scc1 .LBB0_1450
	s_cmp_lg_u32 s39, 4
	s_cbranch_scc0 .LBB0_1447
	s_andn2_b64 vcc, exec, s[56:57]
	s_cbranch_vccnz .LBB0_1444
	v_pk_mul_f32 v[140:141], v[134:135], s[20:21] op_sel_hi:[1,0]
	v_exp_f32_e32 v140, v140
	v_exp_f32_e32 v141, v141
	v_mul_f32_e32 v143, 0xbfb8aa3b, v137
	v_exp_f32_e32 v143, v143
	v_pk_add_f32 v[140:141], v[140:141], 1.0 op_sel_hi:[1,0]
	v_rcp_f32_e32 v140, v140
	v_rcp_f32_e32 v141, v141
	v_mul_f32_e32 v144, 0xbfb8aa3b, v133
	v_mul_f32_e32 v142, 0xbfb8aa3b, v136
	v_max_f32_e32 v146, 0x219392ef, v140
	v_max_f32_e32 v147, 0x219392ef, v141
	v_add_f32_e32 v140, 1.0, v143
	v_mul_f32_e32 v141, 0xbfb8aa3b, v130
	v_mul_f32_e32 v143, 0xbfb8aa3b, v131
	v_rcp_f32_e32 v140, v140
	v_exp_f32_e32 v141, v141
	v_exp_f32_e32 v143, v143
	v_exp_f32_e32 v144, v144
	v_max_f32_e32 v150, 0x219392ef, v140
	v_add_f32_e32 v140, 1.0, v141
	v_add_f32_e32 v141, 1.0, v143
	v_mul_f32_e32 v143, 0xbfb8aa3b, v132
	v_exp_f32_e32 v142, v142
	v_exp_f32_e32 v143, v143
	v_rcp_f32_e32 v140, v140
	v_rcp_f32_e32 v141, v141
	v_add_f32_e32 v144, 1.0, v144
	v_pk_add_f32 v[142:143], v[142:143], 1.0 op_sel_hi:[1,0]
	v_rcp_f32_e32 v144, v144
	v_rcp_f32_e32 v142, v142
	v_rcp_f32_e32 v143, v143
	v_max_f32_e32 v151, 0x219392ef, v140
	v_max_f32_e32 v152, 0x219392ef, v141
	v_lshlrev_b64 v[140:141], 12, v[214:215]
	v_lshl_add_u64 v[140:141], s[16:17], 0, v[140:141]
	v_max_f32_e32 v153, 0x219392ef, v144
	v_lshl_add_u64 v[144:145], v[186:187], 1, v[140:141]
	v_max_f32_e32 v142, 0x219392ef, v142
	v_max_f32_e32 v143, 0x219392ef, v143
	v_add_co_u32_e32 v144, vcc, 0xfffff000, v144
	v_cvt_pk_bf16_f32 v140, v146, v147
	v_cvt_pk_bf16_f32 v141, v142, v150
	v_cvt_pk_bf16_f32 v142, v151, v152
	v_cvt_pk_bf16_f32 v143, v143, v153
	v_addc_co_u32_e32 v145, vcc, -1, v145, vcc
	s_mov_b64 s[18:19], 0
	global_store_dwordx4 v[144:145], v[140:143], off offset:-3840 nt
	s_nop 1
	s_branch .LBB0_1458

.LBB0_1447:
	s_andn2_b64 vcc, exec, s[18:19]
	s_cbranch_vccnz .LBB0_1449
	v_pk_mul_f32 v[140:141], v[134:135], s[20:21] op_sel_hi:[1,0]
	v_pk_mul_f32 v[142:143], v[136:137], s[20:21] op_sel_hi:[1,0]
	v_pk_mul_f32 v[144:145], v[130:131], s[20:21] op_sel_hi:[1,0]
	v_pk_mul_f32 v[146:147], v[132:133], s[20:21] op_sel_hi:[1,0]
	v_exp_f32_e32 v140, v140
	v_exp_f32_e32 v141, v141
	v_exp_f32_e32 v142, v142
	v_exp_f32_e32 v143, v143
	v_exp_f32_e32 v144, v144
	v_exp_f32_e32 v145, v145
	v_exp_f32_e32 v146, v146
	v_exp_f32_e32 v147, v147
	v_pk_add_f32 v[140:141], v[140:141], 1.0 op_sel_hi:[1,0]
	v_pk_add_f32 v[142:143], v[142:143], 1.0 op_sel_hi:[1,0]
	v_pk_add_f32 v[144:145], v[144:145], 1.0 op_sel_hi:[1,0]
	v_pk_add_f32 v[146:147], v[146:147], 1.0 op_sel_hi:[1,0]
	v_rcp_f32_e32 v140, v140
	v_rcp_f32_e32 v141, v141
	v_rcp_f32_e32 v142, v142
	v_rcp_f32_e32 v143, v143
	v_rcp_f32_e32 v144, v144
	v_rcp_f32_e32 v145, v145
	v_rcp_f32_e32 v146, v146
	v_rcp_f32_e32 v147, v147
	v_pk_mul_f32 v[140:141], v[134:135], v[140:141]
	v_pk_mul_f32 v[142:143], v[136:137], v[142:143]
	v_pk_mul_f32 v[144:145], v[130:131], v[144:145]
	v_pk_mul_f32 v[146:147], v[132:133], v[146:147]
	v_lshl_add_u64 v[150:151], s[12:13], 0, v[148:149]
	v_lshl_add_u64 v[150:151], v[186:187], 1, v[150:151]
	v_cvt_pk_bf16_f32 v140, v140, v141
	v_cvt_pk_bf16_f32 v141, v142, v143
	v_cvt_pk_bf16_f32 v142, v144, v145
	v_cvt_pk_bf16_f32 v143, v146, v147
	global_store_dwordx4 v[150:151], v[140:143], off offset:-3840 nt
	s_nop 1
	s_branch .LBB0_1458

.LBB0_1450:
	s_andn2_b64 vcc, exec, s[18:19]
	s_cbranch_vccnz .LBB0_1452
	v_pk_mul_f32 v[140:141], v[134:135], s[20:21] op_sel_hi:[1,0]
	v_pk_mul_f32 v[142:143], v[136:137], s[20:21] op_sel_hi:[1,0]
	v_pk_mul_f32 v[144:145], v[130:131], s[20:21] op_sel_hi:[1,0]
	v_pk_mul_f32 v[146:147], v[132:133], s[20:21] op_sel_hi:[1,0]
	v_exp_f32_e32 v140, v140
	v_exp_f32_e32 v141, v141
	v_exp_f32_e32 v142, v142
	v_exp_f32_e32 v143, v143
	v_exp_f32_e32 v144, v144
	v_exp_f32_e32 v145, v145
	v_exp_f32_e32 v146, v146
	v_exp_f32_e32 v147, v147
	v_pk_add_f32 v[140:141], v[140:141], 1.0 op_sel_hi:[1,0]
	v_pk_add_f32 v[142:143], v[142:143], 1.0 op_sel_hi:[1,0]
	v_pk_add_f32 v[144:145], v[144:145], 1.0 op_sel_hi:[1,0]
	v_pk_add_f32 v[146:147], v[146:147], 1.0 op_sel_hi:[1,0]
	v_rcp_f32_e32 v140, v140
	v_rcp_f32_e32 v141, v141
	v_rcp_f32_e32 v142, v142
	v_rcp_f32_e32 v143, v143
	v_rcp_f32_e32 v144, v144
	v_rcp_f32_e32 v145, v145
	v_rcp_f32_e32 v146, v146
	v_rcp_f32_e32 v147, v147
	v_pk_mul_f32 v[140:141], v[134:135], v[140:141]
	v_pk_mul_f32 v[142:143], v[136:137], v[142:143]
	v_pk_mul_f32 v[144:145], v[130:131], v[144:145]
	v_pk_mul_f32 v[146:147], v[132:133], v[146:147]
	v_lshl_add_u64 v[150:151], s[10:11], 0, v[148:149]
	v_lshl_add_u64 v[150:151], v[186:187], 1, v[150:151]
	v_cvt_pk_bf16_f32 v140, v140, v141
	v_cvt_pk_bf16_f32 v141, v142, v143
	v_cvt_pk_bf16_f32 v142, v144, v145
	v_cvt_pk_bf16_f32 v143, v146, v147
	global_store_dwordx4 v[150:151], v[140:143], off offset:-2816 nt
	s_nop 1
	s_branch .LBB0_1458

.LBB0_1453:
	s_and_b64 vcc, exec, s[18:19]
	s_cbranch_vccz .LBB0_1455
	v_mul_f32_e32 v142, 0xbfb8aa3b, v136
	v_exp_f32_e32 v142, v142
	v_mul_f32_e32 v143, 0xbfb8aa3b, v137
	v_mul_f32_e32 v144, 0xbfb8aa3b, v130
	v_exp_f32_e32 v143, v143
	v_add_f32_e32 v142, 1.0, v142
	v_rcp_f32_e32 v142, v142
	v_exp_f32_e32 v144, v144
	v_mul_f32_e32 v147, 0xbfb8aa3b, v133
	v_fma_f32 v142, v235, v142, v12
	v_log_f32_e32 v145, v142
	v_add_f32_e32 v142, 1.0, v143
	v_add_f32_e32 v143, 1.0, v144
	v_rcp_f32_e32 v143, v143
	v_mul_f32_e32 v144, 0xbfb8aa3b, v131
	v_exp_f32_e32 v144, v144
	v_pk_mul_f32 v[140:141], v[134:135], s[20:21] op_sel_hi:[1,0]
	v_fma_f32 v143, v223, v143, v14
	v_log_f32_e32 v146, v143
	v_add_f32_e32 v143, 1.0, v144
	v_mul_f32_e32 v144, 0xbfb8aa3b, v132
	v_exp_f32_e32 v144, v144
	v_exp_f32_e32 v147, v147
	v_exp_f32_e32 v140, v140
	v_exp_f32_e32 v141, v141
	v_add_f32_e32 v144, 1.0, v144
	v_add_f32_e32 v147, 1.0, v147
	v_pk_add_f32 v[140:141], v[140:141], 1.0 op_sel_hi:[1,0]
	v_rcp_f32_e32 v142, v142
	v_rcp_f32_e32 v144, v144
	v_rcp_f32_e32 v147, v147
	v_rcp_f32_e32 v140, v140
	v_rcp_f32_e32 v141, v141
	v_rcp_f32_e32 v143, v143
	v_fma_f32 v142, v222, v142, v13
	v_fma_f32 v144, v221, v144, v16
	v_fma_f32 v147, v161, v147, v17
	v_fma_f32 v140, v237, v140, v10
	v_fma_f32 v141, v236, v141, v11
	v_fma_f32 v143, v220, v143, v15
	v_log_f32_e32 v144, v144
	v_log_f32_e32 v147, v147
	v_log_f32_e32 v151, v142
	v_log_f32_e32 v140, v140
	v_log_f32_e32 v150, v143
	v_log_f32_e32 v152, v141
	s_and_b64 s[18:19], s[54:55], exec
	s_cselect_b32 s19, s87, s92
	s_cselect_b32 s18, s79, s89
	v_cvt_pk_f16_f32 v143, v144, v147
	v_cvt_pk_f16_f32 v141, v145, v151
	v_lshl_add_u64 v[144:145], s[18:19], 0, v[148:149]
	v_lshlrev_b32_e32 v176, 1, v160
	v_cvt_pk_f16_f32 v142, v146, v150
	v_cvt_pk_f16_f32 v140, v140, v152
	v_lshl_add_u64 v[144:145], v[144:145], 0, v[176:177]
	global_store_dwordx4 v[144:145], v[140:143], off
	s_nop 1
	s_branch .LBB0_1458

.LBB0_1458:
	v_pk_fma_f32 v[126:127], v[126:127], v[212:213], v[54:55] op_sel_hi:[1,0,1]
	v_pk_fma_f32 v[128:129], v[128:129], v[212:213], v[56:57] op_sel_hi:[1,0,1]
	v_pk_fma_f32 v[130:131], v[122:123], v[212:213], v[50:51] op_sel_hi:[1,0,1]
	v_pk_fma_f32 v[124:125], v[124:125], v[212:213], v[52:53] op_sel_hi:[1,0,1]
	s_and_b64 vcc, exec, s[4:5]
	s_mov_b64 s[18:19], -1
	s_cbranch_vccnz .LBB0_1476
	s_and_b64 vcc, exec, s[2:3]
	s_cbranch_vccnz .LBB0_1473
	s_cmp_lt_i32 s39, 4
	s_cbranch_scc1 .LBB0_1470
	s_cmp_lg_u32 s39, 4
	s_cbranch_scc0 .LBB0_1467
	s_andn2_b64 vcc, exec, s[56:57]
	s_cbranch_vccnz .LBB0_1464
	v_pk_mul_f32 v[122:123], v[126:127], s[20:21] op_sel_hi:[1,0]
	v_mul_f32_e32 v132, 0xbfb8aa3b, v128
	v_exp_f32_e32 v122, v122
	v_exp_f32_e32 v123, v123
	v_exp_f32_e32 v132, v132
	v_mul_f32_e32 v133, 0xbfb8aa3b, v129
	v_pk_add_f32 v[122:123], v[122:123], 1.0 op_sel_hi:[1,0]
	v_add_f32_e32 v132, 1.0, v132
	v_rcp_f32_e32 v122, v122
	v_rcp_f32_e32 v123, v123
	v_rcp_f32_e32 v132, v132
	v_exp_f32_e32 v133, v133
	v_max_f32_e32 v134, 0x219392ef, v122
	v_max_f32_e32 v135, 0x219392ef, v123
	v_max_f32_e32 v136, 0x219392ef, v132
	v_add_f32_e32 v122, 1.0, v133
	v_mul_f32_e32 v123, 0xbfb8aa3b, v130
	v_mul_f32_e32 v132, 0xbfb8aa3b, v131
	v_rcp_f32_e32 v122, v122
	v_exp_f32_e32 v123, v123
	v_exp_f32_e32 v132, v132
	v_mul_f32_e32 v137, 0xbfb8aa3b, v125
	v_max_f32_e32 v133, 0x219392ef, v122
	v_add_f32_e32 v122, 1.0, v123
	v_add_f32_e32 v123, 1.0, v132
	v_mul_f32_e32 v132, 0xbfb8aa3b, v124
	v_exp_f32_e32 v132, v132
	v_exp_f32_e32 v137, v137
	v_rcp_f32_e32 v122, v122
	v_rcp_f32_e32 v123, v123
	v_add_f32_e32 v132, 1.0, v132
	v_add_f32_e32 v137, 1.0, v137
	v_rcp_f32_e32 v132, v132
	v_rcp_f32_e32 v137, v137
	v_max_f32_e32 v138, 0x219392ef, v122
	v_max_f32_e32 v139, 0x219392ef, v123
	v_lshlrev_b64 v[122:123], 12, v[210:211]
	v_lshl_add_u64 v[122:123], s[16:17], 0, v[122:123]
	v_lshl_add_u64 v[122:123], v[186:187], 1, v[122:123]
	v_max_f32_e32 v140, 0x219392ef, v132
	v_max_f32_e32 v137, 0x219392ef, v137
	v_add_co_u32_e32 v122, vcc, 0xffffe000, v122
	v_cvt_pk_bf16_f32 v132, v134, v135
	v_cvt_pk_bf16_f32 v133, v136, v133
	v_cvt_pk_bf16_f32 v134, v138, v139
	v_cvt_pk_bf16_f32 v135, v140, v137
	v_addc_co_u32_e32 v123, vcc, -1, v123, vcc
	s_mov_b64 s[18:19], 0
	global_store_dwordx4 v[122:123], v[132:135], off nt
	s_nop 1
	v_lshlrev_b64 v[132:133], 10, v[210:211]
	v_lshl_add_u64 v[122:123], s[8:9], 0, v[132:133]
	s_branch .LBB0_1478

.LBB0_1467:
	s_andn2_b64 vcc, exec, s[18:19]
	s_cbranch_vccnz .LBB0_1469
	v_pk_mul_f32 v[132:133], v[128:129], s[20:21] op_sel_hi:[1,0]
	v_pk_mul_f32 v[122:123], v[126:127], s[20:21] op_sel_hi:[1,0]
	v_exp_f32_e32 v132, v132
	v_exp_f32_e32 v133, v133
	v_pk_mul_f32 v[134:135], v[130:131], s[20:21] op_sel_hi:[1,0]
	v_pk_mul_f32 v[136:137], v[124:125], s[20:21] op_sel_hi:[1,0]
	v_exp_f32_e32 v122, v122
	v_exp_f32_e32 v123, v123
	v_exp_f32_e32 v134, v134
	v_exp_f32_e32 v135, v135
	v_exp_f32_e32 v136, v136
	v_exp_f32_e32 v137, v137
	v_pk_add_f32 v[132:133], v[132:133], 1.0 op_sel_hi:[1,0]
	v_pk_add_f32 v[122:123], v[122:123], 1.0 op_sel_hi:[1,0]
	v_rcp_f32_e32 v132, v132
	v_rcp_f32_e32 v133, v133
	v_pk_add_f32 v[134:135], v[134:135], 1.0 op_sel_hi:[1,0]
	v_pk_add_f32 v[136:137], v[136:137], 1.0 op_sel_hi:[1,0]
	v_rcp_f32_e32 v122, v122
	v_rcp_f32_e32 v123, v123
	v_rcp_f32_e32 v134, v134
	v_rcp_f32_e32 v135, v135
	v_rcp_f32_e32 v136, v136
	v_rcp_f32_e32 v137, v137
	v_pk_mul_f32 v[138:139], v[128:129], v[132:133]
	v_lshlrev_b64 v[132:133], 10, v[210:211]
	v_pk_mul_f32 v[122:123], v[126:127], v[122:123]
	v_pk_mul_f32 v[134:135], v[130:131], v[134:135]
	v_pk_mul_f32 v[136:137], v[124:125], v[136:137]
	v_lshl_add_u64 v[132:133], s[12:13], 0, v[132:133]
	v_lshl_add_u64 v[140:141], v[186:187], 1, v[132:133]
	v_cvt_pk_bf16_f32 v132, v122, v123
	v_cvt_pk_bf16_f32 v133, v138, v139
	v_cvt_pk_bf16_f32 v134, v134, v135
	v_cvt_pk_bf16_f32 v135, v136, v137
	global_store_dwordx4 v[140:141], v[132:135], off offset:-4096 nt
	s_nop 1
	v_lshlrev_b64 v[132:133], 10, v[210:211]
	v_lshl_add_u64 v[122:123], s[8:9], 0, v[132:133]
	s_branch .LBB0_1478

.LBB0_1470:
	s_andn2_b64 vcc, exec, s[18:19]
	s_cbranch_vccnz .LBB0_1472
	v_pk_mul_f32 v[132:133], v[128:129], s[20:21] op_sel_hi:[1,0]
	v_pk_mul_f32 v[122:123], v[126:127], s[20:21] op_sel_hi:[1,0]
	v_exp_f32_e32 v132, v132
	v_exp_f32_e32 v133, v133
	v_pk_mul_f32 v[134:135], v[130:131], s[20:21] op_sel_hi:[1,0]
	v_pk_mul_f32 v[136:137], v[124:125], s[20:21] op_sel_hi:[1,0]
	v_exp_f32_e32 v122, v122
	v_exp_f32_e32 v123, v123
	v_exp_f32_e32 v134, v134
	v_exp_f32_e32 v135, v135
	v_exp_f32_e32 v136, v136
	v_exp_f32_e32 v137, v137
	v_pk_add_f32 v[132:133], v[132:133], 1.0 op_sel_hi:[1,0]
	v_pk_add_f32 v[122:123], v[122:123], 1.0 op_sel_hi:[1,0]
	v_rcp_f32_e32 v132, v132
	v_rcp_f32_e32 v133, v133
	v_pk_add_f32 v[134:135], v[134:135], 1.0 op_sel_hi:[1,0]
	v_pk_add_f32 v[136:137], v[136:137], 1.0 op_sel_hi:[1,0]
	v_rcp_f32_e32 v122, v122
	v_rcp_f32_e32 v123, v123
	v_rcp_f32_e32 v134, v134
	v_rcp_f32_e32 v135, v135
	v_rcp_f32_e32 v136, v136
	v_rcp_f32_e32 v137, v137
	v_pk_mul_f32 v[138:139], v[128:129], v[132:133]
	v_lshlrev_b64 v[132:133], 10, v[210:211]
	v_pk_mul_f32 v[122:123], v[126:127], v[122:123]
	v_pk_mul_f32 v[134:135], v[130:131], v[134:135]
	v_pk_mul_f32 v[136:137], v[124:125], v[136:137]
	v_lshl_add_u64 v[132:133], s[10:11], 0, v[132:133]
	v_lshl_add_u64 v[140:141], v[186:187], 1, v[132:133]
	v_cvt_pk_bf16_f32 v132, v122, v123
	v_cvt_pk_bf16_f32 v133, v138, v139
	v_cvt_pk_bf16_f32 v134, v134, v135
	v_cvt_pk_bf16_f32 v135, v136, v137
	global_store_dwordx4 v[140:141], v[132:135], off offset:-3072 nt
	s_nop 1
	v_lshlrev_b64 v[132:133], 10, v[210:211]
	v_lshl_add_u64 v[122:123], s[8:9], 0, v[132:133]
	s_branch .LBB0_1478

.LBB0_1473:
	s_and_b64 vcc, exec, s[18:19]
	s_cbranch_vccz .LBB0_1475
	v_mul_f32_e32 v134, 0xbfb8aa3b, v128
	v_exp_f32_e32 v134, v134
	v_mul_f32_e32 v135, 0xbfb8aa3b, v129
	v_mul_f32_e32 v136, 0xbfb8aa3b, v130
	v_exp_f32_e32 v135, v135
	v_add_f32_e32 v134, 1.0, v134
	v_rcp_f32_e32 v134, v134
	v_exp_f32_e32 v136, v136
	v_mul_f32_e32 v122, 0xbfb8aa3b, v126
	v_mul_f32_e32 v133, 0xbfb8aa3b, v127
	v_fma_f32 v134, v240, v134, v40
	v_log_f32_e32 v137, v134
	v_add_f32_e32 v134, 1.0, v135
	v_add_f32_e32 v135, 1.0, v136
	v_rcp_f32_e32 v135, v135
	v_mul_f32_e32 v136, 0xbfb8aa3b, v131
	v_exp_f32_e32 v136, v136
	v_mul_f32_e32 v139, 0xbfb8aa3b, v125
	v_fma_f32 v135, v238, v135, v34
	v_log_f32_e32 v138, v135
	v_add_f32_e32 v135, 1.0, v136
	v_mul_f32_e32 v136, 0xbfb8aa3b, v124
	v_exp_f32_e32 v132, v122
	v_exp_f32_e32 v133, v133
	v_exp_f32_e32 v136, v136
	v_exp_f32_e32 v139, v139
	v_pk_add_f32 v[132:133], v[132:133], 1.0 op_sel_hi:[1,0]
	v_add_f32_e32 v136, 1.0, v136
	v_add_f32_e32 v139, 1.0, v139
	v_rcp_f32_e32 v132, v132
	v_rcp_f32_e32 v133, v133
	v_rcp_f32_e32 v134, v134
	v_rcp_f32_e32 v135, v135
	v_rcp_f32_e32 v136, v136
	v_rcp_f32_e32 v139, v139
	v_fma_f32 v132, v242, v132, v38
	v_fma_f32 v133, v241, v133, v39
	v_fma_f32 v134, v239, v134, v41
	v_fma_f32 v135, v234, v135, v35
	v_fma_f32 v136, v233, v136, v36
	v_fma_f32 v139, v229, v139, v37
	v_log_f32_e32 v132, v132
	v_log_f32_e32 v136, v136
	v_log_f32_e32 v139, v139
	v_log_f32_e32 v140, v135
	v_log_f32_e32 v141, v134
	v_log_f32_e32 v142, v133
	s_and_b64 s[18:19], s[54:55], exec
	s_cselect_b32 s19, s87, s92
	s_cselect_b32 s18, s79, s89
	v_lshlrev_b64 v[122:123], 10, v[210:211]
	v_lshl_add_u64 v[122:123], s[18:19], 0, v[122:123]
	v_lshlrev_b32_e32 v176, 1, v191
	v_cvt_pk_f16_f32 v135, v136, v139
	v_cvt_pk_f16_f32 v134, v138, v140
	v_cvt_pk_f16_f32 v133, v137, v141
	v_cvt_pk_f16_f32 v132, v132, v142
	v_lshl_add_u64 v[122:123], v[122:123], 0, v[176:177]
	global_store_dwordx4 v[122:123], v[132:135], off
	s_nop 1
	v_lshlrev_b64 v[132:133], 10, v[210:211]
	v_lshl_add_u64 v[122:123], s[8:9], 0, v[132:133]
	s_branch .LBB0_1478

.LBB0_1478:
	v_mov_b32_e32 v213, v212
	v_pk_fma_f32 v[118:119], v[118:119], v[212:213], v[30:31]
	v_pk_fma_f32 v[120:121], v[120:121], v[212:213], v[32:33]
	v_pk_fma_f32 v[114:115], v[114:115], v[212:213], v[26:27]
	v_pk_fma_f32 v[116:117], v[116:117], v[212:213], v[28:29]
	s_and_b64 vcc, exec, s[4:5]
	s_mov_b64 s[18:19], -1
	s_cbranch_vccnz .LBB0_1496
	s_and_b64 vcc, exec, s[2:3]
	s_cbranch_vccnz .LBB0_1493
	s_cmp_lt_i32 s39, 4
	s_cbranch_scc1 .LBB0_1490
	s_cmp_lg_u32 s39, 4
	s_cbranch_scc0 .LBB0_1487
	s_andn2_b64 vcc, exec, s[56:57]
	s_cbranch_vccnz .LBB0_1484
	v_pk_mul_f32 v[124:125], v[118:119], s[20:21] op_sel_hi:[1,0]
	v_exp_f32_e32 v124, v124
	v_exp_f32_e32 v125, v125
	v_mul_f32_e32 v127, 0xbfb8aa3b, v121
	v_exp_f32_e32 v127, v127
	v_pk_add_f32 v[124:125], v[124:125], 1.0 op_sel_hi:[1,0]
	v_rcp_f32_e32 v124, v124
	v_rcp_f32_e32 v125, v125
	v_mul_f32_e32 v128, 0xbfb8aa3b, v117
	v_mul_f32_e32 v126, 0xbfb8aa3b, v120
	v_max_f32_e32 v130, 0x219392ef, v124
	v_max_f32_e32 v131, 0x219392ef, v125
	v_add_f32_e32 v124, 1.0, v127
	v_mul_f32_e32 v125, 0xbfb8aa3b, v114
	v_mul_f32_e32 v127, 0xbfb8aa3b, v115
	v_rcp_f32_e32 v124, v124
	v_exp_f32_e32 v125, v125
	v_exp_f32_e32 v127, v127
	v_exp_f32_e32 v128, v128
	v_max_f32_e32 v134, 0x219392ef, v124
	v_add_f32_e32 v124, 1.0, v125
	v_add_f32_e32 v125, 1.0, v127
	v_mul_f32_e32 v127, 0xbfb8aa3b, v116
	v_exp_f32_e32 v126, v126
	v_exp_f32_e32 v127, v127
	v_rcp_f32_e32 v124, v124
	v_rcp_f32_e32 v125, v125
	v_add_f32_e32 v128, 1.0, v128
	v_pk_add_f32 v[126:127], v[126:127], 1.0 op_sel_hi:[1,0]
	v_rcp_f32_e32 v128, v128
	v_rcp_f32_e32 v126, v126
	v_rcp_f32_e32 v127, v127
	v_max_f32_e32 v135, 0x219392ef, v124
	v_max_f32_e32 v136, 0x219392ef, v125
	v_lshlrev_b64 v[124:125], 12, v[210:211]
	v_lshl_add_u64 v[124:125], s[16:17], 0, v[124:125]
	v_max_f32_e32 v137, 0x219392ef, v128
	v_lshl_add_u64 v[128:129], v[186:187], 1, v[124:125]
	v_max_f32_e32 v126, 0x219392ef, v126
	v_max_f32_e32 v127, 0x219392ef, v127
	v_add_co_u32_e32 v128, vcc, 0xfffff000, v128
	v_cvt_pk_bf16_f32 v124, v130, v131
	v_cvt_pk_bf16_f32 v125, v126, v134
	v_cvt_pk_bf16_f32 v126, v135, v136
	v_cvt_pk_bf16_f32 v127, v127, v137
	v_addc_co_u32_e32 v129, vcc, -1, v129, vcc
	s_mov_b64 s[18:19], 0
	global_store_dwordx4 v[128:129], v[124:127], off offset:-3840 nt
	s_nop 1
	s_branch .LBB0_1498

.LBB0_1487:
	s_andn2_b64 vcc, exec, s[18:19]
	s_cbranch_vccnz .LBB0_1489
	v_pk_mul_f32 v[124:125], v[118:119], s[20:21] op_sel_hi:[1,0]
	v_pk_mul_f32 v[126:127], v[120:121], s[20:21] op_sel_hi:[1,0]
	v_pk_mul_f32 v[128:129], v[114:115], s[20:21] op_sel_hi:[1,0]
	v_pk_mul_f32 v[130:131], v[116:117], s[20:21] op_sel_hi:[1,0]
	v_exp_f32_e32 v124, v124
	v_exp_f32_e32 v125, v125
	v_exp_f32_e32 v126, v126
	v_exp_f32_e32 v127, v127
	v_exp_f32_e32 v128, v128
	v_exp_f32_e32 v129, v129
	v_exp_f32_e32 v130, v130
	v_exp_f32_e32 v131, v131
	v_pk_add_f32 v[124:125], v[124:125], 1.0 op_sel_hi:[1,0]
	v_pk_add_f32 v[126:127], v[126:127], 1.0 op_sel_hi:[1,0]
	v_pk_add_f32 v[128:129], v[128:129], 1.0 op_sel_hi:[1,0]
	v_pk_add_f32 v[130:131], v[130:131], 1.0 op_sel_hi:[1,0]
	v_rcp_f32_e32 v124, v124
	v_rcp_f32_e32 v125, v125
	v_rcp_f32_e32 v126, v126
	v_rcp_f32_e32 v127, v127
	v_rcp_f32_e32 v128, v128
	v_rcp_f32_e32 v129, v129
	v_rcp_f32_e32 v130, v130
	v_rcp_f32_e32 v131, v131
	v_pk_mul_f32 v[124:125], v[118:119], v[124:125]
	v_pk_mul_f32 v[126:127], v[120:121], v[126:127]
	v_pk_mul_f32 v[128:129], v[114:115], v[128:129]
	v_pk_mul_f32 v[130:131], v[116:117], v[130:131]
	v_lshl_add_u64 v[134:135], s[12:13], 0, v[132:133]
	v_lshl_add_u64 v[134:135], v[186:187], 1, v[134:135]
	v_cvt_pk_bf16_f32 v124, v124, v125
	v_cvt_pk_bf16_f32 v125, v126, v127
	v_cvt_pk_bf16_f32 v126, v128, v129
	v_cvt_pk_bf16_f32 v127, v130, v131
	global_store_dwordx4 v[134:135], v[124:127], off offset:-3840 nt
	s_nop 1
	s_branch .LBB0_1498

.LBB0_1490:
	s_andn2_b64 vcc, exec, s[18:19]
	s_cbranch_vccnz .LBB0_1492
	v_pk_mul_f32 v[124:125], v[118:119], s[20:21] op_sel_hi:[1,0]
	v_pk_mul_f32 v[126:127], v[120:121], s[20:21] op_sel_hi:[1,0]
	v_pk_mul_f32 v[128:129], v[114:115], s[20:21] op_sel_hi:[1,0]
	v_pk_mul_f32 v[130:131], v[116:117], s[20:21] op_sel_hi:[1,0]
	v_exp_f32_e32 v124, v124
	v_exp_f32_e32 v125, v125
	v_exp_f32_e32 v126, v126
	v_exp_f32_e32 v127, v127
	v_exp_f32_e32 v128, v128
	v_exp_f32_e32 v129, v129
	v_exp_f32_e32 v130, v130
	v_exp_f32_e32 v131, v131
	v_pk_add_f32 v[124:125], v[124:125], 1.0 op_sel_hi:[1,0]
	v_pk_add_f32 v[126:127], v[126:127], 1.0 op_sel_hi:[1,0]
	v_pk_add_f32 v[128:129], v[128:129], 1.0 op_sel_hi:[1,0]
	v_pk_add_f32 v[130:131], v[130:131], 1.0 op_sel_hi:[1,0]
	v_rcp_f32_e32 v124, v124
	v_rcp_f32_e32 v125, v125
	v_rcp_f32_e32 v126, v126
	v_rcp_f32_e32 v127, v127
	v_rcp_f32_e32 v128, v128
	v_rcp_f32_e32 v129, v129
	v_rcp_f32_e32 v130, v130
	v_rcp_f32_e32 v131, v131
	v_pk_mul_f32 v[124:125], v[118:119], v[124:125]
	v_pk_mul_f32 v[126:127], v[120:121], v[126:127]
	v_pk_mul_f32 v[128:129], v[114:115], v[128:129]
	v_pk_mul_f32 v[130:131], v[116:117], v[130:131]
	v_lshl_add_u64 v[134:135], s[10:11], 0, v[132:133]
	v_lshl_add_u64 v[134:135], v[186:187], 1, v[134:135]
	v_cvt_pk_bf16_f32 v124, v124, v125
	v_cvt_pk_bf16_f32 v125, v126, v127
	v_cvt_pk_bf16_f32 v126, v128, v129
	v_cvt_pk_bf16_f32 v127, v130, v131
	global_store_dwordx4 v[134:135], v[124:127], off offset:-2816 nt
	s_nop 1
	s_branch .LBB0_1498

.LBB0_1493:
	s_and_b64 vcc, exec, s[18:19]
	s_cbranch_vccz .LBB0_1495
	v_mul_f32_e32 v126, 0xbfb8aa3b, v120
	v_exp_f32_e32 v126, v126
	v_mul_f32_e32 v127, 0xbfb8aa3b, v121
	v_mul_f32_e32 v128, 0xbfb8aa3b, v114
	v_exp_f32_e32 v127, v127
	v_add_f32_e32 v126, 1.0, v126
	v_rcp_f32_e32 v126, v126
	v_exp_f32_e32 v128, v128
	v_mul_f32_e32 v131, 0xbfb8aa3b, v117
	v_fma_f32 v126, v235, v126, v12
	v_log_f32_e32 v129, v126
	v_add_f32_e32 v126, 1.0, v127
	v_add_f32_e32 v127, 1.0, v128
	v_rcp_f32_e32 v127, v127
	v_mul_f32_e32 v128, 0xbfb8aa3b, v115
	v_exp_f32_e32 v128, v128
	v_pk_mul_f32 v[124:125], v[118:119], s[20:21] op_sel_hi:[1,0]
	v_fma_f32 v127, v223, v127, v14
	v_log_f32_e32 v130, v127
	v_add_f32_e32 v127, 1.0, v128
	v_mul_f32_e32 v128, 0xbfb8aa3b, v116
	v_exp_f32_e32 v128, v128
	v_exp_f32_e32 v131, v131
	v_exp_f32_e32 v124, v124
	v_exp_f32_e32 v125, v125
	v_add_f32_e32 v128, 1.0, v128
	v_add_f32_e32 v131, 1.0, v131
	v_pk_add_f32 v[124:125], v[124:125], 1.0 op_sel_hi:[1,0]
	v_rcp_f32_e32 v126, v126
	v_rcp_f32_e32 v128, v128
	v_rcp_f32_e32 v131, v131
	v_rcp_f32_e32 v124, v124
	v_rcp_f32_e32 v125, v125
	v_rcp_f32_e32 v127, v127
	v_fma_f32 v126, v222, v126, v13
	v_fma_f32 v128, v221, v128, v16
	v_fma_f32 v131, v161, v131, v17
	v_fma_f32 v124, v237, v124, v10
	v_fma_f32 v125, v236, v125, v11
	v_fma_f32 v127, v220, v127, v15
	v_log_f32_e32 v128, v128
	v_log_f32_e32 v131, v131
	v_log_f32_e32 v135, v126
	v_log_f32_e32 v124, v124
	v_log_f32_e32 v134, v127
	v_log_f32_e32 v136, v125
	s_and_b64 s[18:19], s[54:55], exec
	s_cselect_b32 s19, s87, s92
	s_cselect_b32 s18, s79, s89
	v_cvt_pk_f16_f32 v127, v128, v131
	v_cvt_pk_f16_f32 v125, v129, v135
	v_lshl_add_u64 v[128:129], s[18:19], 0, v[132:133]
	v_lshlrev_b32_e32 v176, 1, v160
	v_cvt_pk_f16_f32 v126, v130, v134
	v_cvt_pk_f16_f32 v124, v124, v136
	v_lshl_add_u64 v[128:129], v[128:129], 0, v[176:177]
	global_store_dwordx4 v[128:129], v[124:127], off
	s_nop 1
	s_branch .LBB0_1498

.LBB0_1498:
	v_pk_fma_f32 v[110:111], v[110:111], v[208:209], v[54:55] op_sel_hi:[1,0,1]
	v_pk_fma_f32 v[112:113], v[112:113], v[208:209], v[56:57] op_sel_hi:[1,0,1]
	v_pk_fma_f32 v[114:115], v[106:107], v[208:209], v[50:51] op_sel_hi:[1,0,1]
	v_pk_fma_f32 v[108:109], v[108:109], v[208:209], v[52:53] op_sel_hi:[1,0,1]
	s_and_b64 vcc, exec, s[4:5]
	s_mov_b64 s[18:19], -1
	s_cbranch_vccnz .LBB0_1516
	s_and_b64 vcc, exec, s[2:3]
	s_cbranch_vccnz .LBB0_1513
	s_cmp_lt_i32 s39, 4
	s_cbranch_scc1 .LBB0_1510
	s_cmp_lg_u32 s39, 4
	s_cbranch_scc0 .LBB0_1507
	s_andn2_b64 vcc, exec, s[56:57]
	s_cbranch_vccnz .LBB0_1504
	v_pk_mul_f32 v[106:107], v[110:111], s[20:21] op_sel_hi:[1,0]
	v_mul_f32_e32 v116, 0xbfb8aa3b, v112
	v_exp_f32_e32 v106, v106
	v_exp_f32_e32 v107, v107
	v_exp_f32_e32 v116, v116
	v_mul_f32_e32 v117, 0xbfb8aa3b, v113
	v_pk_add_f32 v[106:107], v[106:107], 1.0 op_sel_hi:[1,0]
	v_add_f32_e32 v116, 1.0, v116
	v_rcp_f32_e32 v106, v106
	v_rcp_f32_e32 v107, v107
	v_rcp_f32_e32 v116, v116
	v_exp_f32_e32 v117, v117
	v_max_f32_e32 v118, 0x219392ef, v106
	v_max_f32_e32 v119, 0x219392ef, v107
	v_max_f32_e32 v120, 0x219392ef, v116
	v_add_f32_e32 v106, 1.0, v117
	v_mul_f32_e32 v107, 0xbfb8aa3b, v114
	v_mul_f32_e32 v116, 0xbfb8aa3b, v115
	v_rcp_f32_e32 v106, v106
	v_exp_f32_e32 v107, v107
	v_exp_f32_e32 v116, v116
	v_mul_f32_e32 v121, 0xbfb8aa3b, v109
	v_max_f32_e32 v117, 0x219392ef, v106
	v_add_f32_e32 v106, 1.0, v107
	v_add_f32_e32 v107, 1.0, v116
	v_mul_f32_e32 v116, 0xbfb8aa3b, v108
	v_exp_f32_e32 v116, v116
	v_exp_f32_e32 v121, v121
	v_rcp_f32_e32 v106, v106
	v_rcp_f32_e32 v107, v107
	v_add_f32_e32 v116, 1.0, v116
	v_add_f32_e32 v121, 1.0, v121
	v_rcp_f32_e32 v116, v116
	v_rcp_f32_e32 v121, v121
	v_max_f32_e32 v122, 0x219392ef, v106
	v_max_f32_e32 v123, 0x219392ef, v107
	v_lshlrev_b64 v[106:107], 12, v[206:207]
	v_lshl_add_u64 v[106:107], s[16:17], 0, v[106:107]
	v_lshl_add_u64 v[106:107], v[186:187], 1, v[106:107]
	v_max_f32_e32 v124, 0x219392ef, v116
	v_max_f32_e32 v121, 0x219392ef, v121
	v_add_co_u32_e32 v106, vcc, 0xffffe000, v106
	v_cvt_pk_bf16_f32 v116, v118, v119
	v_cvt_pk_bf16_f32 v117, v120, v117
	v_cvt_pk_bf16_f32 v118, v122, v123
	v_cvt_pk_bf16_f32 v119, v124, v121
	v_addc_co_u32_e32 v107, vcc, -1, v107, vcc
	s_mov_b64 s[18:19], 0
	global_store_dwordx4 v[106:107], v[116:119], off nt
	s_nop 1
	v_lshlrev_b64 v[116:117], 10, v[206:207]
	v_lshl_add_u64 v[106:107], s[8:9], 0, v[116:117]
	s_branch .LBB0_1518

.LBB0_1507:
	s_andn2_b64 vcc, exec, s[18:19]
	s_cbranch_vccnz .LBB0_1509
	v_pk_mul_f32 v[116:117], v[112:113], s[20:21] op_sel_hi:[1,0]
	v_pk_mul_f32 v[106:107], v[110:111], s[20:21] op_sel_hi:[1,0]
	v_exp_f32_e32 v116, v116
	v_exp_f32_e32 v117, v117
	v_pk_mul_f32 v[118:119], v[114:115], s[20:21] op_sel_hi:[1,0]
	v_pk_mul_f32 v[120:121], v[108:109], s[20:21] op_sel_hi:[1,0]
	v_exp_f32_e32 v106, v106
	v_exp_f32_e32 v107, v107
	v_exp_f32_e32 v118, v118
	v_exp_f32_e32 v119, v119
	v_exp_f32_e32 v120, v120
	v_exp_f32_e32 v121, v121
	v_pk_add_f32 v[116:117], v[116:117], 1.0 op_sel_hi:[1,0]
	v_pk_add_f32 v[106:107], v[106:107], 1.0 op_sel_hi:[1,0]
	v_rcp_f32_e32 v116, v116
	v_rcp_f32_e32 v117, v117
	v_pk_add_f32 v[118:119], v[118:119], 1.0 op_sel_hi:[1,0]
	v_pk_add_f32 v[120:121], v[120:121], 1.0 op_sel_hi:[1,0]
	v_rcp_f32_e32 v106, v106
	v_rcp_f32_e32 v107, v107
	v_rcp_f32_e32 v118, v118
	v_rcp_f32_e32 v119, v119
	v_rcp_f32_e32 v120, v120
	v_rcp_f32_e32 v121, v121
	v_pk_mul_f32 v[122:123], v[112:113], v[116:117]
	v_lshlrev_b64 v[116:117], 10, v[206:207]
	v_pk_mul_f32 v[106:107], v[110:111], v[106:107]
	v_pk_mul_f32 v[118:119], v[114:115], v[118:119]
	v_pk_mul_f32 v[120:121], v[108:109], v[120:121]
	v_lshl_add_u64 v[116:117], s[12:13], 0, v[116:117]
	v_lshl_add_u64 v[124:125], v[186:187], 1, v[116:117]
	v_cvt_pk_bf16_f32 v116, v106, v107
	v_cvt_pk_bf16_f32 v117, v122, v123
	v_cvt_pk_bf16_f32 v118, v118, v119
	v_cvt_pk_bf16_f32 v119, v120, v121
	global_store_dwordx4 v[124:125], v[116:119], off offset:-4096 nt
	s_nop 1
	v_lshlrev_b64 v[116:117], 10, v[206:207]
	v_lshl_add_u64 v[106:107], s[8:9], 0, v[116:117]
	s_branch .LBB0_1518

.LBB0_1510:
	s_andn2_b64 vcc, exec, s[18:19]
	s_cbranch_vccnz .LBB0_1512
	v_pk_mul_f32 v[116:117], v[112:113], s[20:21] op_sel_hi:[1,0]
	v_pk_mul_f32 v[106:107], v[110:111], s[20:21] op_sel_hi:[1,0]
	v_exp_f32_e32 v116, v116
	v_exp_f32_e32 v117, v117
	v_pk_mul_f32 v[118:119], v[114:115], s[20:21] op_sel_hi:[1,0]
	v_pk_mul_f32 v[120:121], v[108:109], s[20:21] op_sel_hi:[1,0]
	v_exp_f32_e32 v106, v106
	v_exp_f32_e32 v107, v107
	v_exp_f32_e32 v118, v118
	v_exp_f32_e32 v119, v119
	v_exp_f32_e32 v120, v120
	v_exp_f32_e32 v121, v121
	v_pk_add_f32 v[116:117], v[116:117], 1.0 op_sel_hi:[1,0]
	v_pk_add_f32 v[106:107], v[106:107], 1.0 op_sel_hi:[1,0]
	v_rcp_f32_e32 v116, v116
	v_rcp_f32_e32 v117, v117
	v_pk_add_f32 v[118:119], v[118:119], 1.0 op_sel_hi:[1,0]
	v_pk_add_f32 v[120:121], v[120:121], 1.0 op_sel_hi:[1,0]
	v_rcp_f32_e32 v106, v106
	v_rcp_f32_e32 v107, v107
	v_rcp_f32_e32 v118, v118
	v_rcp_f32_e32 v119, v119
	v_rcp_f32_e32 v120, v120
	v_rcp_f32_e32 v121, v121
	v_pk_mul_f32 v[122:123], v[112:113], v[116:117]
	v_lshlrev_b64 v[116:117], 10, v[206:207]
	v_pk_mul_f32 v[106:107], v[110:111], v[106:107]
	v_pk_mul_f32 v[118:119], v[114:115], v[118:119]
	v_pk_mul_f32 v[120:121], v[108:109], v[120:121]
	v_lshl_add_u64 v[116:117], s[10:11], 0, v[116:117]
	v_lshl_add_u64 v[124:125], v[186:187], 1, v[116:117]
	v_cvt_pk_bf16_f32 v116, v106, v107
	v_cvt_pk_bf16_f32 v117, v122, v123
	v_cvt_pk_bf16_f32 v118, v118, v119
	v_cvt_pk_bf16_f32 v119, v120, v121
	global_store_dwordx4 v[124:125], v[116:119], off offset:-3072 nt
	s_nop 1
	v_lshlrev_b64 v[116:117], 10, v[206:207]
	v_lshl_add_u64 v[106:107], s[8:9], 0, v[116:117]
	s_branch .LBB0_1518

.LBB0_1513:
	s_and_b64 vcc, exec, s[18:19]
	s_cbranch_vccz .LBB0_1515
	v_mul_f32_e32 v118, 0xbfb8aa3b, v112
	v_exp_f32_e32 v118, v118
	v_mul_f32_e32 v119, 0xbfb8aa3b, v113
	v_mul_f32_e32 v120, 0xbfb8aa3b, v114
	v_exp_f32_e32 v119, v119
	v_add_f32_e32 v118, 1.0, v118
	v_rcp_f32_e32 v118, v118
	v_exp_f32_e32 v120, v120
	v_mul_f32_e32 v106, 0xbfb8aa3b, v110
	v_mul_f32_e32 v117, 0xbfb8aa3b, v111
	v_fma_f32 v118, v240, v118, v40
	v_log_f32_e32 v121, v118
	v_add_f32_e32 v118, 1.0, v119
	v_add_f32_e32 v119, 1.0, v120
	v_rcp_f32_e32 v119, v119
	v_mul_f32_e32 v120, 0xbfb8aa3b, v115
	v_exp_f32_e32 v120, v120
	v_mul_f32_e32 v123, 0xbfb8aa3b, v109
	v_fma_f32 v119, v238, v119, v34
	v_log_f32_e32 v122, v119
	v_add_f32_e32 v119, 1.0, v120
	v_mul_f32_e32 v120, 0xbfb8aa3b, v108
	v_exp_f32_e32 v116, v106
	v_exp_f32_e32 v117, v117
	v_exp_f32_e32 v120, v120
	v_exp_f32_e32 v123, v123
	v_pk_add_f32 v[116:117], v[116:117], 1.0 op_sel_hi:[1,0]
	v_add_f32_e32 v120, 1.0, v120
	v_add_f32_e32 v123, 1.0, v123
	v_rcp_f32_e32 v116, v116
	v_rcp_f32_e32 v117, v117
	v_rcp_f32_e32 v118, v118
	v_rcp_f32_e32 v119, v119
	v_rcp_f32_e32 v120, v120
	v_rcp_f32_e32 v123, v123
	v_fma_f32 v116, v242, v116, v38
	v_fma_f32 v117, v241, v117, v39
	v_fma_f32 v118, v239, v118, v41
	v_fma_f32 v119, v234, v119, v35
	v_fma_f32 v120, v233, v120, v36
	v_fma_f32 v123, v229, v123, v37
	v_log_f32_e32 v116, v116
	v_log_f32_e32 v120, v120
	v_log_f32_e32 v123, v123
	v_log_f32_e32 v124, v119
	v_log_f32_e32 v125, v118
	v_log_f32_e32 v126, v117
	s_and_b64 s[18:19], s[54:55], exec
	s_cselect_b32 s19, s87, s92
	s_cselect_b32 s18, s79, s89
	v_lshlrev_b64 v[106:107], 10, v[206:207]
	v_lshl_add_u64 v[106:107], s[18:19], 0, v[106:107]
	v_lshlrev_b32_e32 v176, 1, v191
	v_cvt_pk_f16_f32 v119, v120, v123
	v_cvt_pk_f16_f32 v118, v122, v124
	v_cvt_pk_f16_f32 v117, v121, v125
	v_cvt_pk_f16_f32 v116, v116, v126
	v_lshl_add_u64 v[106:107], v[106:107], 0, v[176:177]
	global_store_dwordx4 v[106:107], v[116:119], off
	s_nop 1
	v_lshlrev_b64 v[116:117], 10, v[206:207]
	v_lshl_add_u64 v[106:107], s[8:9], 0, v[116:117]
	s_branch .LBB0_1518

.LBB0_1518:
	v_mov_b32_e32 v209, v208
	v_pk_fma_f32 v[102:103], v[102:103], v[208:209], v[30:31]
	v_pk_fma_f32 v[104:105], v[104:105], v[208:209], v[32:33]
	v_pk_fma_f32 v[98:99], v[98:99], v[208:209], v[26:27]
	v_pk_fma_f32 v[100:101], v[100:101], v[208:209], v[28:29]
	s_and_b64 vcc, exec, s[4:5]
	s_mov_b64 s[18:19], -1
	s_cbranch_vccnz .LBB0_1536
	s_and_b64 vcc, exec, s[2:3]
	s_cbranch_vccnz .LBB0_1533
	s_cmp_lt_i32 s39, 4
	s_cbranch_scc1 .LBB0_1530
	s_cmp_lg_u32 s39, 4
	s_cbranch_scc0 .LBB0_1527
	s_andn2_b64 vcc, exec, s[56:57]
	s_cbranch_vccnz .LBB0_1524
	v_pk_mul_f32 v[108:109], v[102:103], s[20:21] op_sel_hi:[1,0]
	v_exp_f32_e32 v108, v108
	v_exp_f32_e32 v109, v109
	v_mul_f32_e32 v111, 0xbfb8aa3b, v105
	v_exp_f32_e32 v111, v111
	v_pk_add_f32 v[108:109], v[108:109], 1.0 op_sel_hi:[1,0]
	v_rcp_f32_e32 v108, v108
	v_rcp_f32_e32 v109, v109
	v_mul_f32_e32 v112, 0xbfb8aa3b, v101
	v_mul_f32_e32 v110, 0xbfb8aa3b, v104
	v_max_f32_e32 v114, 0x219392ef, v108
	v_max_f32_e32 v115, 0x219392ef, v109
	v_add_f32_e32 v108, 1.0, v111
	v_mul_f32_e32 v109, 0xbfb8aa3b, v98
	v_mul_f32_e32 v111, 0xbfb8aa3b, v99
	v_rcp_f32_e32 v108, v108
	v_exp_f32_e32 v109, v109
	v_exp_f32_e32 v111, v111
	v_exp_f32_e32 v112, v112
	v_max_f32_e32 v118, 0x219392ef, v108
	v_add_f32_e32 v108, 1.0, v109
	v_add_f32_e32 v109, 1.0, v111
	v_mul_f32_e32 v111, 0xbfb8aa3b, v100
	v_exp_f32_e32 v110, v110
	v_exp_f32_e32 v111, v111
	v_rcp_f32_e32 v108, v108
	v_rcp_f32_e32 v109, v109
	v_add_f32_e32 v112, 1.0, v112
	v_pk_add_f32 v[110:111], v[110:111], 1.0 op_sel_hi:[1,0]
	v_rcp_f32_e32 v112, v112
	v_rcp_f32_e32 v110, v110
	v_rcp_f32_e32 v111, v111
	v_max_f32_e32 v119, 0x219392ef, v108
	v_max_f32_e32 v120, 0x219392ef, v109
	v_lshlrev_b64 v[108:109], 12, v[206:207]
	v_lshl_add_u64 v[108:109], s[16:17], 0, v[108:109]
	v_max_f32_e32 v121, 0x219392ef, v112
	v_lshl_add_u64 v[112:113], v[186:187], 1, v[108:109]
	v_max_f32_e32 v110, 0x219392ef, v110
	v_max_f32_e32 v111, 0x219392ef, v111
	v_add_co_u32_e32 v112, vcc, 0xfffff000, v112
	v_cvt_pk_bf16_f32 v108, v114, v115
	v_cvt_pk_bf16_f32 v109, v110, v118
	v_cvt_pk_bf16_f32 v110, v119, v120
	v_cvt_pk_bf16_f32 v111, v111, v121
	v_addc_co_u32_e32 v113, vcc, -1, v113, vcc
	s_mov_b64 s[18:19], 0
	global_store_dwordx4 v[112:113], v[108:111], off offset:-3840 nt
	s_nop 1
	s_branch .LBB0_1538

.LBB0_1527:
	s_andn2_b64 vcc, exec, s[18:19]
	s_cbranch_vccnz .LBB0_1529
	v_pk_mul_f32 v[108:109], v[102:103], s[20:21] op_sel_hi:[1,0]
	v_pk_mul_f32 v[110:111], v[104:105], s[20:21] op_sel_hi:[1,0]
	v_pk_mul_f32 v[112:113], v[98:99], s[20:21] op_sel_hi:[1,0]
	v_pk_mul_f32 v[114:115], v[100:101], s[20:21] op_sel_hi:[1,0]
	v_exp_f32_e32 v108, v108
	v_exp_f32_e32 v109, v109
	v_exp_f32_e32 v110, v110
	v_exp_f32_e32 v111, v111
	v_exp_f32_e32 v112, v112
	v_exp_f32_e32 v113, v113
	v_exp_f32_e32 v114, v114
	v_exp_f32_e32 v115, v115
	v_pk_add_f32 v[108:109], v[108:109], 1.0 op_sel_hi:[1,0]
	v_pk_add_f32 v[110:111], v[110:111], 1.0 op_sel_hi:[1,0]
	v_pk_add_f32 v[112:113], v[112:113], 1.0 op_sel_hi:[1,0]
	v_pk_add_f32 v[114:115], v[114:115], 1.0 op_sel_hi:[1,0]
	v_rcp_f32_e32 v108, v108
	v_rcp_f32_e32 v109, v109
	v_rcp_f32_e32 v110, v110
	v_rcp_f32_e32 v111, v111
	v_rcp_f32_e32 v112, v112
	v_rcp_f32_e32 v113, v113
	v_rcp_f32_e32 v114, v114
	v_rcp_f32_e32 v115, v115
	v_pk_mul_f32 v[108:109], v[102:103], v[108:109]
	v_pk_mul_f32 v[110:111], v[104:105], v[110:111]
	v_pk_mul_f32 v[112:113], v[98:99], v[112:113]
	v_pk_mul_f32 v[114:115], v[100:101], v[114:115]
	v_lshl_add_u64 v[118:119], s[12:13], 0, v[116:117]
	v_lshl_add_u64 v[118:119], v[186:187], 1, v[118:119]
	v_cvt_pk_bf16_f32 v108, v108, v109
	v_cvt_pk_bf16_f32 v109, v110, v111
	v_cvt_pk_bf16_f32 v110, v112, v113
	v_cvt_pk_bf16_f32 v111, v114, v115
	global_store_dwordx4 v[118:119], v[108:111], off offset:-3840 nt
	s_nop 1
	s_branch .LBB0_1538

.LBB0_1530:
	s_andn2_b64 vcc, exec, s[18:19]
	s_cbranch_vccnz .LBB0_1532
	v_pk_mul_f32 v[108:109], v[102:103], s[20:21] op_sel_hi:[1,0]
	v_pk_mul_f32 v[110:111], v[104:105], s[20:21] op_sel_hi:[1,0]
	v_pk_mul_f32 v[112:113], v[98:99], s[20:21] op_sel_hi:[1,0]
	v_pk_mul_f32 v[114:115], v[100:101], s[20:21] op_sel_hi:[1,0]
	v_exp_f32_e32 v108, v108
	v_exp_f32_e32 v109, v109
	v_exp_f32_e32 v110, v110
	v_exp_f32_e32 v111, v111
	v_exp_f32_e32 v112, v112
	v_exp_f32_e32 v113, v113
	v_exp_f32_e32 v114, v114
	v_exp_f32_e32 v115, v115
	v_pk_add_f32 v[108:109], v[108:109], 1.0 op_sel_hi:[1,0]
	v_pk_add_f32 v[110:111], v[110:111], 1.0 op_sel_hi:[1,0]
	v_pk_add_f32 v[112:113], v[112:113], 1.0 op_sel_hi:[1,0]
	v_pk_add_f32 v[114:115], v[114:115], 1.0 op_sel_hi:[1,0]
	v_rcp_f32_e32 v108, v108
	v_rcp_f32_e32 v109, v109
	v_rcp_f32_e32 v110, v110
	v_rcp_f32_e32 v111, v111
	v_rcp_f32_e32 v112, v112
	v_rcp_f32_e32 v113, v113
	v_rcp_f32_e32 v114, v114
	v_rcp_f32_e32 v115, v115
	v_pk_mul_f32 v[108:109], v[102:103], v[108:109]
	v_pk_mul_f32 v[110:111], v[104:105], v[110:111]
	v_pk_mul_f32 v[112:113], v[98:99], v[112:113]
	v_pk_mul_f32 v[114:115], v[100:101], v[114:115]
	v_lshl_add_u64 v[118:119], s[10:11], 0, v[116:117]
	v_lshl_add_u64 v[118:119], v[186:187], 1, v[118:119]
	v_cvt_pk_bf16_f32 v108, v108, v109
	v_cvt_pk_bf16_f32 v109, v110, v111
	v_cvt_pk_bf16_f32 v110, v112, v113
	v_cvt_pk_bf16_f32 v111, v114, v115
	global_store_dwordx4 v[118:119], v[108:111], off offset:-2816 nt
	s_nop 1
	s_branch .LBB0_1538

.LBB0_1533:
	s_and_b64 vcc, exec, s[18:19]
	s_cbranch_vccz .LBB0_1535
	v_mul_f32_e32 v110, 0xbfb8aa3b, v104
	v_exp_f32_e32 v110, v110
	v_mul_f32_e32 v111, 0xbfb8aa3b, v105
	v_mul_f32_e32 v112, 0xbfb8aa3b, v98
	v_exp_f32_e32 v111, v111
	v_add_f32_e32 v110, 1.0, v110
	v_rcp_f32_e32 v110, v110
	v_exp_f32_e32 v112, v112
	v_mul_f32_e32 v115, 0xbfb8aa3b, v101
	v_fma_f32 v110, v235, v110, v12
	v_log_f32_e32 v113, v110
	v_add_f32_e32 v110, 1.0, v111
	v_add_f32_e32 v111, 1.0, v112
	v_rcp_f32_e32 v111, v111
	v_mul_f32_e32 v112, 0xbfb8aa3b, v99
	v_exp_f32_e32 v112, v112
	v_pk_mul_f32 v[108:109], v[102:103], s[20:21] op_sel_hi:[1,0]
	v_fma_f32 v111, v223, v111, v14
	v_log_f32_e32 v114, v111
	v_add_f32_e32 v111, 1.0, v112
	v_mul_f32_e32 v112, 0xbfb8aa3b, v100
	v_exp_f32_e32 v112, v112
	v_exp_f32_e32 v115, v115
	v_exp_f32_e32 v108, v108
	v_exp_f32_e32 v109, v109
	v_add_f32_e32 v112, 1.0, v112
	v_add_f32_e32 v115, 1.0, v115
	v_pk_add_f32 v[108:109], v[108:109], 1.0 op_sel_hi:[1,0]
	v_rcp_f32_e32 v110, v110
	v_rcp_f32_e32 v112, v112
	v_rcp_f32_e32 v115, v115
	v_rcp_f32_e32 v108, v108
	v_rcp_f32_e32 v109, v109
	v_rcp_f32_e32 v111, v111
	v_fma_f32 v110, v222, v110, v13
	v_fma_f32 v112, v221, v112, v16
	v_fma_f32 v115, v161, v115, v17
	v_fma_f32 v108, v237, v108, v10
	v_fma_f32 v109, v236, v109, v11
	v_fma_f32 v111, v220, v111, v15
	v_log_f32_e32 v112, v112
	v_log_f32_e32 v115, v115
	v_log_f32_e32 v119, v110
	v_log_f32_e32 v108, v108
	v_log_f32_e32 v118, v111
	v_log_f32_e32 v120, v109
	s_and_b64 s[18:19], s[54:55], exec
	s_cselect_b32 s19, s87, s92
	s_cselect_b32 s18, s79, s89
	v_cvt_pk_f16_f32 v111, v112, v115
	v_cvt_pk_f16_f32 v109, v113, v119
	v_lshl_add_u64 v[112:113], s[18:19], 0, v[116:117]
	v_lshlrev_b32_e32 v176, 1, v160
	v_cvt_pk_f16_f32 v110, v114, v118
	v_cvt_pk_f16_f32 v108, v108, v120
	v_lshl_add_u64 v[112:113], v[112:113], 0, v[176:177]
	global_store_dwordx4 v[112:113], v[108:111], off
	s_nop 1
	s_branch .LBB0_1538

.LBB0_1538:
	v_add_u32_e32 v98, 0x80, v204
	v_ashrrev_i32_e32 v99, 31, v98
	v_pk_fma_f32 v[94:95], v[94:95], v[202:203], v[54:55] op_sel_hi:[1,0,1]
	v_pk_fma_f32 v[96:97], v[96:97], v[202:203], v[56:57] op_sel_hi:[1,0,1]
	v_pk_fma_f32 v[100:101], v[90:91], v[202:203], v[50:51] op_sel_hi:[1,0,1]
	v_pk_fma_f32 v[92:93], v[92:93], v[202:203], v[52:53] op_sel_hi:[1,0,1]
	s_and_b64 vcc, exec, s[4:5]
	s_mov_b64 s[18:19], -1
	s_cbranch_vccnz .LBB0_1556
	s_and_b64 vcc, exec, s[2:3]
	s_cbranch_vccnz .LBB0_1553
	s_cmp_lt_i32 s39, 4
	s_cbranch_scc1 .LBB0_1550
	s_cmp_lg_u32 s39, 4
	s_cbranch_scc0 .LBB0_1547
	s_andn2_b64 vcc, exec, s[56:57]
	s_cbranch_vccnz .LBB0_1544
	v_pk_mul_f32 v[90:91], v[94:95], s[20:21] op_sel_hi:[1,0]
	v_mul_f32_e32 v102, 0xbfb8aa3b, v96
	v_exp_f32_e32 v90, v90
	v_exp_f32_e32 v91, v91
	v_exp_f32_e32 v102, v102
	v_mul_f32_e32 v103, 0xbfb8aa3b, v97
	v_pk_add_f32 v[90:91], v[90:91], 1.0 op_sel_hi:[1,0]
	v_add_f32_e32 v102, 1.0, v102
	v_rcp_f32_e32 v90, v90
	v_rcp_f32_e32 v91, v91
	v_rcp_f32_e32 v102, v102
	v_exp_f32_e32 v103, v103
	v_max_f32_e32 v104, 0x219392ef, v90
	v_max_f32_e32 v105, 0x219392ef, v91
	v_max_f32_e32 v106, 0x219392ef, v102
	v_add_f32_e32 v90, 1.0, v103
	v_mul_f32_e32 v91, 0xbfb8aa3b, v100
	v_mul_f32_e32 v102, 0xbfb8aa3b, v101
	v_rcp_f32_e32 v90, v90
	v_exp_f32_e32 v91, v91
	v_exp_f32_e32 v102, v102
	v_mul_f32_e32 v107, 0xbfb8aa3b, v93
	v_max_f32_e32 v103, 0x219392ef, v90
	v_add_f32_e32 v90, 1.0, v91
	v_add_f32_e32 v91, 1.0, v102
	v_mul_f32_e32 v102, 0xbfb8aa3b, v92
	v_exp_f32_e32 v102, v102
	v_exp_f32_e32 v107, v107
	v_rcp_f32_e32 v90, v90
	v_rcp_f32_e32 v91, v91
	v_add_f32_e32 v102, 1.0, v102
	v_add_f32_e32 v107, 1.0, v107
	v_rcp_f32_e32 v102, v102
	v_rcp_f32_e32 v107, v107
	v_max_f32_e32 v108, 0x219392ef, v90
	v_max_f32_e32 v109, 0x219392ef, v91
	v_lshlrev_b64 v[90:91], 12, v[98:99]
	v_lshl_add_u64 v[90:91], s[16:17], 0, v[90:91]
	v_lshl_add_u64 v[90:91], v[186:187], 1, v[90:91]
	v_max_f32_e32 v110, 0x219392ef, v102
	v_max_f32_e32 v107, 0x219392ef, v107
	v_add_co_u32_e32 v90, vcc, 0xffffe000, v90
	v_cvt_pk_bf16_f32 v102, v104, v105
	v_cvt_pk_bf16_f32 v103, v106, v103
	v_cvt_pk_bf16_f32 v104, v108, v109
	v_cvt_pk_bf16_f32 v105, v110, v107
	v_addc_co_u32_e32 v91, vcc, -1, v91, vcc
	s_mov_b64 s[18:19], 0
	global_store_dwordx4 v[90:91], v[102:105], off nt
	s_nop 1
	v_lshlrev_b64 v[102:103], 10, v[98:99]
	v_lshl_add_u64 v[90:91], s[8:9], 0, v[102:103]
	s_branch .LBB0_1558

.LBB0_1547:
	s_andn2_b64 vcc, exec, s[18:19]
	s_cbranch_vccnz .LBB0_1549
	v_pk_mul_f32 v[102:103], v[96:97], s[20:21] op_sel_hi:[1,0]
	v_pk_mul_f32 v[90:91], v[94:95], s[20:21] op_sel_hi:[1,0]
	v_exp_f32_e32 v102, v102
	v_exp_f32_e32 v103, v103
	v_pk_mul_f32 v[104:105], v[100:101], s[20:21] op_sel_hi:[1,0]
	v_pk_mul_f32 v[106:107], v[92:93], s[20:21] op_sel_hi:[1,0]
	v_exp_f32_e32 v90, v90
	v_exp_f32_e32 v91, v91
	v_exp_f32_e32 v104, v104
	v_exp_f32_e32 v105, v105
	v_exp_f32_e32 v106, v106
	v_exp_f32_e32 v107, v107
	v_pk_add_f32 v[102:103], v[102:103], 1.0 op_sel_hi:[1,0]
	v_pk_add_f32 v[90:91], v[90:91], 1.0 op_sel_hi:[1,0]
	v_rcp_f32_e32 v102, v102
	v_rcp_f32_e32 v103, v103
	v_pk_add_f32 v[104:105], v[104:105], 1.0 op_sel_hi:[1,0]
	v_pk_add_f32 v[106:107], v[106:107], 1.0 op_sel_hi:[1,0]
	v_rcp_f32_e32 v90, v90
	v_rcp_f32_e32 v91, v91
	v_rcp_f32_e32 v104, v104
	v_rcp_f32_e32 v105, v105
	v_rcp_f32_e32 v106, v106
	v_rcp_f32_e32 v107, v107
	v_pk_mul_f32 v[108:109], v[96:97], v[102:103]
	v_lshlrev_b64 v[102:103], 10, v[98:99]
	v_pk_mul_f32 v[90:91], v[94:95], v[90:91]
	v_pk_mul_f32 v[104:105], v[100:101], v[104:105]
	v_pk_mul_f32 v[106:107], v[92:93], v[106:107]
	v_lshl_add_u64 v[102:103], s[12:13], 0, v[102:103]
	v_lshl_add_u64 v[110:111], v[186:187], 1, v[102:103]
	v_cvt_pk_bf16_f32 v102, v90, v91
	v_cvt_pk_bf16_f32 v103, v108, v109
	v_cvt_pk_bf16_f32 v104, v104, v105
	v_cvt_pk_bf16_f32 v105, v106, v107
	global_store_dwordx4 v[110:111], v[102:105], off offset:-4096 nt
	s_nop 1
	v_lshlrev_b64 v[102:103], 10, v[98:99]
	v_lshl_add_u64 v[90:91], s[8:9], 0, v[102:103]
	s_branch .LBB0_1558

.LBB0_1550:
	s_andn2_b64 vcc, exec, s[18:19]
	s_cbranch_vccnz .LBB0_1552
	v_pk_mul_f32 v[102:103], v[96:97], s[20:21] op_sel_hi:[1,0]
	v_pk_mul_f32 v[90:91], v[94:95], s[20:21] op_sel_hi:[1,0]
	v_exp_f32_e32 v102, v102
	v_exp_f32_e32 v103, v103
	v_pk_mul_f32 v[104:105], v[100:101], s[20:21] op_sel_hi:[1,0]
	v_pk_mul_f32 v[106:107], v[92:93], s[20:21] op_sel_hi:[1,0]
	v_exp_f32_e32 v90, v90
	v_exp_f32_e32 v91, v91
	v_exp_f32_e32 v104, v104
	v_exp_f32_e32 v105, v105
	v_exp_f32_e32 v106, v106
	v_exp_f32_e32 v107, v107
	v_pk_add_f32 v[102:103], v[102:103], 1.0 op_sel_hi:[1,0]
	v_pk_add_f32 v[90:91], v[90:91], 1.0 op_sel_hi:[1,0]
	v_rcp_f32_e32 v102, v102
	v_rcp_f32_e32 v103, v103
	v_pk_add_f32 v[104:105], v[104:105], 1.0 op_sel_hi:[1,0]
	v_pk_add_f32 v[106:107], v[106:107], 1.0 op_sel_hi:[1,0]
	v_rcp_f32_e32 v90, v90
	v_rcp_f32_e32 v91, v91
	v_rcp_f32_e32 v104, v104
	v_rcp_f32_e32 v105, v105
	v_rcp_f32_e32 v106, v106
	v_rcp_f32_e32 v107, v107
	v_pk_mul_f32 v[108:109], v[96:97], v[102:103]
	v_lshlrev_b64 v[102:103], 10, v[98:99]
	v_pk_mul_f32 v[90:91], v[94:95], v[90:91]
	v_pk_mul_f32 v[104:105], v[100:101], v[104:105]
	v_pk_mul_f32 v[106:107], v[92:93], v[106:107]
	v_lshl_add_u64 v[102:103], s[10:11], 0, v[102:103]
	v_lshl_add_u64 v[110:111], v[186:187], 1, v[102:103]
	v_cvt_pk_bf16_f32 v102, v90, v91
	v_cvt_pk_bf16_f32 v103, v108, v109
	v_cvt_pk_bf16_f32 v104, v104, v105
	v_cvt_pk_bf16_f32 v105, v106, v107
	global_store_dwordx4 v[110:111], v[102:105], off offset:-3072 nt
	s_nop 1
	v_lshlrev_b64 v[102:103], 10, v[98:99]
	v_lshl_add_u64 v[90:91], s[8:9], 0, v[102:103]
	s_branch .LBB0_1558

.LBB0_1553:
	s_and_b64 vcc, exec, s[18:19]
	s_cbranch_vccz .LBB0_1555
	v_mul_f32_e32 v104, 0xbfb8aa3b, v96
	v_exp_f32_e32 v104, v104
	v_mul_f32_e32 v105, 0xbfb8aa3b, v97
	v_mul_f32_e32 v106, 0xbfb8aa3b, v100
	v_exp_f32_e32 v105, v105
	v_add_f32_e32 v104, 1.0, v104
	v_rcp_f32_e32 v104, v104
	v_exp_f32_e32 v106, v106
	v_mul_f32_e32 v90, 0xbfb8aa3b, v94
	v_mul_f32_e32 v103, 0xbfb8aa3b, v95
	v_fma_f32 v104, v240, v104, v40
	v_log_f32_e32 v107, v104
	v_add_f32_e32 v104, 1.0, v105
	v_add_f32_e32 v105, 1.0, v106
	v_rcp_f32_e32 v105, v105
	v_mul_f32_e32 v106, 0xbfb8aa3b, v101
	v_exp_f32_e32 v106, v106
	v_mul_f32_e32 v109, 0xbfb8aa3b, v93
	v_fma_f32 v105, v238, v105, v34
	v_log_f32_e32 v108, v105
	v_add_f32_e32 v105, 1.0, v106
	v_mul_f32_e32 v106, 0xbfb8aa3b, v92
	v_exp_f32_e32 v102, v90
	v_exp_f32_e32 v103, v103
	v_exp_f32_e32 v106, v106
	v_exp_f32_e32 v109, v109
	v_pk_add_f32 v[102:103], v[102:103], 1.0 op_sel_hi:[1,0]
	v_add_f32_e32 v106, 1.0, v106
	v_add_f32_e32 v109, 1.0, v109
	v_rcp_f32_e32 v102, v102
	v_rcp_f32_e32 v103, v103
	v_rcp_f32_e32 v104, v104
	v_rcp_f32_e32 v105, v105
	v_rcp_f32_e32 v106, v106
	v_rcp_f32_e32 v109, v109
	v_fma_f32 v102, v242, v102, v38
	v_fma_f32 v103, v241, v103, v39
	v_fma_f32 v104, v239, v104, v41
	v_fma_f32 v105, v234, v105, v35
	v_fma_f32 v106, v233, v106, v36
	v_fma_f32 v109, v229, v109, v37
	v_log_f32_e32 v102, v102
	v_log_f32_e32 v106, v106
	v_log_f32_e32 v109, v109
	v_log_f32_e32 v110, v105
	v_log_f32_e32 v111, v104
	v_log_f32_e32 v112, v103
	s_and_b64 s[18:19], s[54:55], exec
	s_cselect_b32 s19, s87, s92
	s_cselect_b32 s18, s79, s89
	v_lshlrev_b64 v[90:91], 10, v[98:99]
	v_lshl_add_u64 v[90:91], s[18:19], 0, v[90:91]
	v_lshlrev_b32_e32 v176, 1, v191
	v_cvt_pk_f16_f32 v105, v106, v109
	v_cvt_pk_f16_f32 v104, v108, v110
	v_cvt_pk_f16_f32 v103, v107, v111
	v_cvt_pk_f16_f32 v102, v102, v112
	v_lshl_add_u64 v[90:91], v[90:91], 0, v[176:177]
	global_store_dwordx4 v[90:91], v[102:105], off
	s_nop 1
	v_lshlrev_b64 v[102:103], 10, v[98:99]
	v_lshl_add_u64 v[90:91], s[8:9], 0, v[102:103]
	s_branch .LBB0_1558

.LBB0_1558:
	v_mov_b32_e32 v203, v202
	v_pk_fma_f32 v[86:87], v[86:87], v[202:203], v[30:31]
	v_pk_fma_f32 v[88:89], v[88:89], v[202:203], v[32:33]
	v_pk_fma_f32 v[82:83], v[82:83], v[202:203], v[26:27]
	v_pk_fma_f32 v[84:85], v[84:85], v[202:203], v[28:29]
	s_and_b64 vcc, exec, s[4:5]
	s_mov_b64 s[18:19], -1
	s_cbranch_vccnz .LBB0_1576
	s_and_b64 vcc, exec, s[2:3]
	s_cbranch_vccnz .LBB0_1573
	s_cmp_lt_i32 s39, 4
	s_cbranch_scc1 .LBB0_1570
	s_cmp_lg_u32 s39, 4
	s_cbranch_scc0 .LBB0_1567
	s_andn2_b64 vcc, exec, s[56:57]
	s_cbranch_vccnz .LBB0_1564
	v_pk_mul_f32 v[92:93], v[86:87], s[20:21] op_sel_hi:[1,0]
	v_exp_f32_e32 v92, v92
	v_exp_f32_e32 v93, v93
	v_mul_f32_e32 v95, 0xbfb8aa3b, v89
	v_exp_f32_e32 v95, v95
	v_pk_add_f32 v[92:93], v[92:93], 1.0 op_sel_hi:[1,0]
	v_rcp_f32_e32 v92, v92
	v_rcp_f32_e32 v93, v93
	v_mul_f32_e32 v96, 0xbfb8aa3b, v85
	v_mul_f32_e32 v94, 0xbfb8aa3b, v88
	v_max_f32_e32 v100, 0x219392ef, v92
	v_max_f32_e32 v101, 0x219392ef, v93
	v_add_f32_e32 v92, 1.0, v95
	v_mul_f32_e32 v93, 0xbfb8aa3b, v82
	v_mul_f32_e32 v95, 0xbfb8aa3b, v83
	v_rcp_f32_e32 v92, v92
	v_exp_f32_e32 v93, v93
	v_exp_f32_e32 v95, v95
	v_exp_f32_e32 v96, v96
	v_max_f32_e32 v104, 0x219392ef, v92
	v_add_f32_e32 v92, 1.0, v93
	v_add_f32_e32 v93, 1.0, v95
	v_mul_f32_e32 v95, 0xbfb8aa3b, v84
	v_exp_f32_e32 v94, v94
	v_exp_f32_e32 v95, v95
	v_rcp_f32_e32 v92, v92
	v_rcp_f32_e32 v93, v93
	v_add_f32_e32 v96, 1.0, v96
	v_pk_add_f32 v[94:95], v[94:95], 1.0 op_sel_hi:[1,0]
	v_rcp_f32_e32 v96, v96
	v_rcp_f32_e32 v94, v94
	v_rcp_f32_e32 v95, v95
	v_max_f32_e32 v105, 0x219392ef, v92
	v_max_f32_e32 v106, 0x219392ef, v93
	v_lshlrev_b64 v[92:93], 12, v[98:99]
	v_lshl_add_u64 v[92:93], s[16:17], 0, v[92:93]
	v_max_f32_e32 v107, 0x219392ef, v96
	v_lshl_add_u64 v[96:97], v[186:187], 1, v[92:93]
	v_max_f32_e32 v94, 0x219392ef, v94
	v_max_f32_e32 v95, 0x219392ef, v95
	v_add_co_u32_e32 v96, vcc, 0xfffff000, v96
	v_cvt_pk_bf16_f32 v92, v100, v101
	v_cvt_pk_bf16_f32 v93, v94, v104
	v_cvt_pk_bf16_f32 v94, v105, v106
	v_cvt_pk_bf16_f32 v95, v95, v107
	v_addc_co_u32_e32 v97, vcc, -1, v97, vcc
	s_mov_b64 s[18:19], 0
	global_store_dwordx4 v[96:97], v[92:95], off offset:-3840 nt
	s_nop 1
	s_branch .LBB0_1578

.LBB0_1567:
	s_andn2_b64 vcc, exec, s[18:19]
	s_cbranch_vccnz .LBB0_1569
	v_mul_f32_e32 v99, 0xbfb8aa3b, v84
	v_pk_mul_f32 v[92:93], v[86:87], s[20:21] op_sel_hi:[1,0]
	v_pk_mul_f32 v[94:95], v[88:89], s[20:21] op_sel_hi:[1,0]
	v_pk_mul_f32 v[96:97], v[82:83], s[20:21] op_sel_hi:[1,0]
	v_exp_f32_e32 v99, v99
	v_mul_f32_e32 v100, 0xbfb8aa3b, v85
	v_exp_f32_e32 v92, v92
	v_exp_f32_e32 v93, v93
	v_exp_f32_e32 v94, v94
	v_exp_f32_e32 v95, v95
	v_exp_f32_e32 v96, v96
	v_exp_f32_e32 v97, v97
	v_exp_f32_e32 v101, v100
	v_add_f32_e32 v99, 1.0, v99
	v_pk_add_f32 v[92:93], v[92:93], 1.0 op_sel_hi:[1,0]
	v_pk_add_f32 v[94:95], v[94:95], 1.0 op_sel_hi:[1,0]
	v_pk_add_f32 v[96:97], v[96:97], 1.0 op_sel_hi:[1,0]
	v_rcp_f32_e32 v100, v99
	v_add_f32_e32 v99, 1.0, v101
	v_rcp_f32_e32 v92, v92
	v_rcp_f32_e32 v93, v93
	v_rcp_f32_e32 v94, v94
	v_rcp_f32_e32 v95, v95
	v_rcp_f32_e32 v96, v96
	v_rcp_f32_e32 v97, v97
	v_rcp_f32_e32 v101, v99
	v_pk_mul_f32 v[92:93], v[86:87], v[92:93]
	v_pk_mul_f32 v[94:95], v[88:89], v[94:95]
	v_pk_mul_f32 v[96:97], v[82:83], v[96:97]
	v_pk_mul_f32 v[100:101], v[84:85], v[100:101]
	v_lshl_add_u64 v[104:105], s[12:13], 0, v[102:103]
	v_lshl_add_u64 v[104:105], v[186:187], 1, v[104:105]
	v_cvt_pk_bf16_f32 v92, v92, v93
	v_cvt_pk_bf16_f32 v93, v94, v95
	v_cvt_pk_bf16_f32 v94, v96, v97
	v_cvt_pk_bf16_f32 v95, v100, v101
	global_store_dwordx4 v[104:105], v[92:95], off offset:-3840 nt
	s_nop 1
	s_branch .LBB0_1578

.LBB0_1570:
	s_andn2_b64 vcc, exec, s[18:19]
	s_cbranch_vccnz .LBB0_1572
	v_mul_f32_e32 v99, 0xbfb8aa3b, v84
	v_pk_mul_f32 v[92:93], v[86:87], s[20:21] op_sel_hi:[1,0]
	v_pk_mul_f32 v[94:95], v[88:89], s[20:21] op_sel_hi:[1,0]
	v_pk_mul_f32 v[96:97], v[82:83], s[20:21] op_sel_hi:[1,0]
	v_exp_f32_e32 v99, v99
	v_mul_f32_e32 v100, 0xbfb8aa3b, v85
	v_exp_f32_e32 v92, v92
	v_exp_f32_e32 v93, v93
	v_exp_f32_e32 v94, v94
	v_exp_f32_e32 v95, v95
	v_exp_f32_e32 v96, v96
	v_exp_f32_e32 v97, v97
	v_exp_f32_e32 v101, v100
	v_add_f32_e32 v99, 1.0, v99
	v_pk_add_f32 v[92:93], v[92:93], 1.0 op_sel_hi:[1,0]
	v_pk_add_f32 v[94:95], v[94:95], 1.0 op_sel_hi:[1,0]
	v_pk_add_f32 v[96:97], v[96:97], 1.0 op_sel_hi:[1,0]
	v_rcp_f32_e32 v100, v99
	v_add_f32_e32 v99, 1.0, v101
	v_rcp_f32_e32 v92, v92
	v_rcp_f32_e32 v93, v93
	v_rcp_f32_e32 v94, v94
	v_rcp_f32_e32 v95, v95
	v_rcp_f32_e32 v96, v96
	v_rcp_f32_e32 v97, v97
	v_rcp_f32_e32 v101, v99
	v_pk_mul_f32 v[92:93], v[86:87], v[92:93]
	v_pk_mul_f32 v[94:95], v[88:89], v[94:95]
	v_pk_mul_f32 v[96:97], v[82:83], v[96:97]
	v_pk_mul_f32 v[100:101], v[84:85], v[100:101]
	v_lshl_add_u64 v[104:105], s[10:11], 0, v[102:103]
	v_lshl_add_u64 v[104:105], v[186:187], 1, v[104:105]
	v_cvt_pk_bf16_f32 v92, v92, v93
	v_cvt_pk_bf16_f32 v93, v94, v95
	v_cvt_pk_bf16_f32 v94, v96, v97
	v_cvt_pk_bf16_f32 v95, v100, v101
	global_store_dwordx4 v[104:105], v[92:95], off offset:-2816 nt
	s_nop 1
	s_branch .LBB0_1578

.LBB0_1573:
	s_and_b64 vcc, exec, s[18:19]
	s_cbranch_vccz .LBB0_1575
	v_mul_f32_e32 v94, 0xbfb8aa3b, v88
	v_exp_f32_e32 v94, v94
	v_mul_f32_e32 v95, 0xbfb8aa3b, v89
	v_mul_f32_e32 v96, 0xbfb8aa3b, v82
	v_exp_f32_e32 v95, v95
	v_add_f32_e32 v94, 1.0, v94
	v_rcp_f32_e32 v94, v94
	v_exp_f32_e32 v96, v96
	v_mul_f32_e32 v100, 0xbfb8aa3b, v85
	v_fma_f32 v94, v235, v94, v12
	v_log_f32_e32 v97, v94
	v_add_f32_e32 v94, 1.0, v95
	v_add_f32_e32 v95, 1.0, v96
	v_rcp_f32_e32 v95, v95
	v_mul_f32_e32 v96, 0xbfb8aa3b, v83
	v_exp_f32_e32 v96, v96
	v_pk_mul_f32 v[92:93], v[86:87], s[20:21] op_sel_hi:[1,0]
	v_fma_f32 v95, v223, v95, v14
	v_log_f32_e32 v99, v95
	v_add_f32_e32 v95, 1.0, v96
	v_mul_f32_e32 v96, 0xbfb8aa3b, v84
	v_exp_f32_e32 v96, v96
	v_exp_f32_e32 v100, v100
	v_exp_f32_e32 v92, v92
	v_exp_f32_e32 v93, v93
	v_add_f32_e32 v96, 1.0, v96
	v_add_f32_e32 v100, 1.0, v100
	v_pk_add_f32 v[92:93], v[92:93], 1.0 op_sel_hi:[1,0]
	v_rcp_f32_e32 v94, v94
	v_rcp_f32_e32 v96, v96
	v_rcp_f32_e32 v100, v100
	v_rcp_f32_e32 v92, v92
	v_rcp_f32_e32 v93, v93
	v_rcp_f32_e32 v95, v95
	v_fma_f32 v94, v222, v94, v13
	v_fma_f32 v96, v221, v96, v16
	v_fma_f32 v100, v161, v100, v17
	v_fma_f32 v92, v237, v92, v10
	v_fma_f32 v93, v236, v93, v11
	v_fma_f32 v95, v220, v95, v15
	v_log_f32_e32 v96, v96
	v_log_f32_e32 v100, v100
	v_log_f32_e32 v104, v94
	v_log_f32_e32 v92, v92
	v_log_f32_e32 v101, v95
	v_log_f32_e32 v105, v93
	s_and_b64 s[18:19], s[54:55], exec
	s_cselect_b32 s19, s87, s92
	s_cselect_b32 s18, s79, s89
	v_cvt_pk_f16_f32 v95, v96, v100
	v_cvt_pk_f16_f32 v93, v97, v104
	v_lshl_add_u64 v[96:97], s[18:19], 0, v[102:103]
	v_lshlrev_b32_e32 v176, 1, v160
	v_cvt_pk_f16_f32 v94, v99, v101
	v_cvt_pk_f16_f32 v92, v92, v105
	v_lshl_add_u64 v[96:97], v[96:97], 0, v[176:177]
	global_store_dwordx4 v[96:97], v[92:95], off
	s_nop 1
	s_branch .LBB0_1578

.LBB0_1578:
	v_pk_fma_f32 v[78:79], v[78:79], v[200:201], v[54:55] op_sel_hi:[1,0,1]
	v_pk_fma_f32 v[80:81], v[80:81], v[200:201], v[56:57] op_sel_hi:[1,0,1]
	v_pk_fma_f32 v[82:83], v[74:75], v[200:201], v[50:51] op_sel_hi:[1,0,1]
	v_pk_fma_f32 v[76:77], v[76:77], v[200:201], v[52:53] op_sel_hi:[1,0,1]
	s_and_b64 vcc, exec, s[4:5]
	s_mov_b64 s[18:19], -1
	s_cbranch_vccnz .LBB0_1596
	s_and_b64 vcc, exec, s[2:3]
	s_cbranch_vccnz .LBB0_1593
	s_cmp_lt_i32 s39, 4
	s_cbranch_scc1 .LBB0_1590
	s_cmp_lg_u32 s39, 4
	s_cbranch_scc0 .LBB0_1587
	s_andn2_b64 vcc, exec, s[56:57]
	s_cbranch_vccnz .LBB0_1584
	v_pk_mul_f32 v[74:75], v[78:79], s[20:21] op_sel_hi:[1,0]
	v_mul_f32_e32 v84, 0xbfb8aa3b, v80
	v_exp_f32_e32 v74, v74
	v_exp_f32_e32 v75, v75
	v_exp_f32_e32 v84, v84
	v_mul_f32_e32 v85, 0xbfb8aa3b, v81
	v_pk_add_f32 v[74:75], v[74:75], 1.0 op_sel_hi:[1,0]
	v_add_f32_e32 v84, 1.0, v84
	v_rcp_f32_e32 v74, v74
	v_rcp_f32_e32 v75, v75
	v_rcp_f32_e32 v84, v84
	v_exp_f32_e32 v85, v85
	v_max_f32_e32 v86, 0x219392ef, v74
	v_max_f32_e32 v87, 0x219392ef, v75
	v_max_f32_e32 v88, 0x219392ef, v84
	v_add_f32_e32 v74, 1.0, v85
	v_mul_f32_e32 v75, 0xbfb8aa3b, v82
	v_mul_f32_e32 v84, 0xbfb8aa3b, v83
	v_rcp_f32_e32 v74, v74
	v_exp_f32_e32 v75, v75
	v_exp_f32_e32 v84, v84
	v_mul_f32_e32 v89, 0xbfb8aa3b, v77
	v_max_f32_e32 v85, 0x219392ef, v74
	v_add_f32_e32 v74, 1.0, v75
	v_add_f32_e32 v75, 1.0, v84
	v_mul_f32_e32 v84, 0xbfb8aa3b, v76
	v_exp_f32_e32 v84, v84
	v_exp_f32_e32 v89, v89
	v_rcp_f32_e32 v74, v74
	v_rcp_f32_e32 v75, v75
	v_add_f32_e32 v84, 1.0, v84
	v_add_f32_e32 v89, 1.0, v89
	v_rcp_f32_e32 v84, v84
	v_rcp_f32_e32 v89, v89
	v_max_f32_e32 v90, 0x219392ef, v74
	v_max_f32_e32 v91, 0x219392ef, v75
	v_lshlrev_b64 v[74:75], 12, v[198:199]
	v_lshl_add_u64 v[74:75], s[16:17], 0, v[74:75]
	v_lshl_add_u64 v[74:75], v[186:187], 1, v[74:75]
	v_max_f32_e32 v92, 0x219392ef, v84
	v_max_f32_e32 v89, 0x219392ef, v89
	v_add_co_u32_e32 v74, vcc, 0xffffe000, v74
	v_cvt_pk_bf16_f32 v84, v86, v87
	v_cvt_pk_bf16_f32 v85, v88, v85
	v_cvt_pk_bf16_f32 v86, v90, v91
	v_cvt_pk_bf16_f32 v87, v92, v89
	v_addc_co_u32_e32 v75, vcc, -1, v75, vcc
	s_mov_b64 s[18:19], 0
	global_store_dwordx4 v[74:75], v[84:87], off nt
	s_nop 1
	v_lshlrev_b64 v[84:85], 10, v[198:199]
	v_lshl_add_u64 v[74:75], s[8:9], 0, v[84:85]
	s_branch .LBB0_1598

.LBB0_1587:
	s_andn2_b64 vcc, exec, s[18:19]
	s_cbranch_vccnz .LBB0_1589
	v_pk_mul_f32 v[84:85], v[80:81], s[20:21] op_sel_hi:[1,0]
	v_pk_mul_f32 v[74:75], v[78:79], s[20:21] op_sel_hi:[1,0]
	v_exp_f32_e32 v84, v84
	v_exp_f32_e32 v85, v85
	v_pk_mul_f32 v[86:87], v[82:83], s[20:21] op_sel_hi:[1,0]
	v_pk_mul_f32 v[88:89], v[76:77], s[20:21] op_sel_hi:[1,0]
	v_exp_f32_e32 v74, v74
	v_exp_f32_e32 v75, v75
	v_exp_f32_e32 v86, v86
	v_exp_f32_e32 v87, v87
	v_exp_f32_e32 v88, v88
	v_exp_f32_e32 v89, v89
	v_pk_add_f32 v[84:85], v[84:85], 1.0 op_sel_hi:[1,0]
	v_pk_add_f32 v[74:75], v[74:75], 1.0 op_sel_hi:[1,0]
	v_rcp_f32_e32 v84, v84
	v_rcp_f32_e32 v85, v85
	v_pk_add_f32 v[86:87], v[86:87], 1.0 op_sel_hi:[1,0]
	v_pk_add_f32 v[88:89], v[88:89], 1.0 op_sel_hi:[1,0]
	v_rcp_f32_e32 v74, v74
	v_rcp_f32_e32 v75, v75
	v_rcp_f32_e32 v86, v86
	v_rcp_f32_e32 v87, v87
	v_rcp_f32_e32 v88, v88
	v_rcp_f32_e32 v89, v89
	v_pk_mul_f32 v[90:91], v[80:81], v[84:85]
	v_lshlrev_b64 v[84:85], 10, v[198:199]
	v_pk_mul_f32 v[74:75], v[78:79], v[74:75]
	v_pk_mul_f32 v[86:87], v[82:83], v[86:87]
	v_pk_mul_f32 v[88:89], v[76:77], v[88:89]
	v_lshl_add_u64 v[84:85], s[12:13], 0, v[84:85]
	v_lshl_add_u64 v[92:93], v[186:187], 1, v[84:85]
	v_cvt_pk_bf16_f32 v84, v74, v75
	v_cvt_pk_bf16_f32 v85, v90, v91
	v_cvt_pk_bf16_f32 v86, v86, v87
	v_cvt_pk_bf16_f32 v87, v88, v89
	global_store_dwordx4 v[92:93], v[84:87], off offset:-4096 nt
	s_nop 1
	v_lshlrev_b64 v[84:85], 10, v[198:199]
	v_lshl_add_u64 v[74:75], s[8:9], 0, v[84:85]
	s_branch .LBB0_1598

.LBB0_1590:
	s_andn2_b64 vcc, exec, s[18:19]
	s_cbranch_vccnz .LBB0_1592
	v_pk_mul_f32 v[84:85], v[80:81], s[20:21] op_sel_hi:[1,0]
	v_pk_mul_f32 v[74:75], v[78:79], s[20:21] op_sel_hi:[1,0]
	v_exp_f32_e32 v84, v84
	v_exp_f32_e32 v85, v85
	v_pk_mul_f32 v[86:87], v[82:83], s[20:21] op_sel_hi:[1,0]
	v_pk_mul_f32 v[88:89], v[76:77], s[20:21] op_sel_hi:[1,0]
	v_exp_f32_e32 v74, v74
	v_exp_f32_e32 v75, v75
	v_exp_f32_e32 v86, v86
	v_exp_f32_e32 v87, v87
	v_exp_f32_e32 v88, v88
	v_exp_f32_e32 v89, v89
	v_pk_add_f32 v[84:85], v[84:85], 1.0 op_sel_hi:[1,0]
	v_pk_add_f32 v[74:75], v[74:75], 1.0 op_sel_hi:[1,0]
	v_rcp_f32_e32 v84, v84
	v_rcp_f32_e32 v85, v85
	v_pk_add_f32 v[86:87], v[86:87], 1.0 op_sel_hi:[1,0]
	v_pk_add_f32 v[88:89], v[88:89], 1.0 op_sel_hi:[1,0]
	v_rcp_f32_e32 v74, v74
	v_rcp_f32_e32 v75, v75
	v_rcp_f32_e32 v86, v86
	v_rcp_f32_e32 v87, v87
	v_rcp_f32_e32 v88, v88
	v_rcp_f32_e32 v89, v89
	v_pk_mul_f32 v[90:91], v[80:81], v[84:85]
	v_lshlrev_b64 v[84:85], 10, v[198:199]
	v_pk_mul_f32 v[74:75], v[78:79], v[74:75]
	v_pk_mul_f32 v[86:87], v[82:83], v[86:87]
	v_pk_mul_f32 v[88:89], v[76:77], v[88:89]
	v_lshl_add_u64 v[84:85], s[10:11], 0, v[84:85]
	v_lshl_add_u64 v[92:93], v[186:187], 1, v[84:85]
	v_cvt_pk_bf16_f32 v84, v74, v75
	v_cvt_pk_bf16_f32 v85, v90, v91
	v_cvt_pk_bf16_f32 v86, v86, v87
	v_cvt_pk_bf16_f32 v87, v88, v89
	global_store_dwordx4 v[92:93], v[84:87], off offset:-3072 nt
	s_nop 1
	v_lshlrev_b64 v[84:85], 10, v[198:199]
	v_lshl_add_u64 v[74:75], s[8:9], 0, v[84:85]
	s_branch .LBB0_1598

.LBB0_1593:
	s_and_b64 vcc, exec, s[18:19]
	s_cbranch_vccz .LBB0_1595
	v_mul_f32_e32 v86, 0xbfb8aa3b, v80
	v_exp_f32_e32 v86, v86
	v_mul_f32_e32 v87, 0xbfb8aa3b, v81
	v_mul_f32_e32 v88, 0xbfb8aa3b, v82
	v_exp_f32_e32 v87, v87
	v_add_f32_e32 v86, 1.0, v86
	v_rcp_f32_e32 v86, v86
	v_exp_f32_e32 v88, v88
	v_mul_f32_e32 v74, 0xbfb8aa3b, v78
	v_mul_f32_e32 v85, 0xbfb8aa3b, v79
	v_fma_f32 v86, v240, v86, v40
	v_log_f32_e32 v89, v86
	v_add_f32_e32 v86, 1.0, v87
	v_add_f32_e32 v87, 1.0, v88
	v_rcp_f32_e32 v87, v87
	v_mul_f32_e32 v88, 0xbfb8aa3b, v83
	v_exp_f32_e32 v88, v88
	v_mul_f32_e32 v91, 0xbfb8aa3b, v77
	v_fma_f32 v87, v238, v87, v34
	v_log_f32_e32 v90, v87
	v_add_f32_e32 v87, 1.0, v88
	v_mul_f32_e32 v88, 0xbfb8aa3b, v76
	v_exp_f32_e32 v84, v74
	v_exp_f32_e32 v85, v85
	v_exp_f32_e32 v88, v88
	v_exp_f32_e32 v91, v91
	v_pk_add_f32 v[84:85], v[84:85], 1.0 op_sel_hi:[1,0]
	v_add_f32_e32 v88, 1.0, v88
	v_add_f32_e32 v91, 1.0, v91
	v_rcp_f32_e32 v84, v84
	v_rcp_f32_e32 v85, v85
	v_rcp_f32_e32 v86, v86
	v_rcp_f32_e32 v87, v87
	v_rcp_f32_e32 v88, v88
	v_rcp_f32_e32 v91, v91
	v_fma_f32 v84, v242, v84, v38
	v_fma_f32 v85, v241, v85, v39
	v_fma_f32 v86, v239, v86, v41
	v_fma_f32 v87, v234, v87, v35
	v_fma_f32 v88, v233, v88, v36
	v_fma_f32 v91, v229, v91, v37
	v_log_f32_e32 v84, v84
	v_log_f32_e32 v88, v88
	v_log_f32_e32 v91, v91
	v_log_f32_e32 v92, v87
	v_log_f32_e32 v93, v86
	v_log_f32_e32 v94, v85
	s_and_b64 s[18:19], s[54:55], exec
	s_cselect_b32 s19, s87, s92
	s_cselect_b32 s18, s79, s89
	v_lshlrev_b64 v[74:75], 10, v[198:199]
	v_lshl_add_u64 v[74:75], s[18:19], 0, v[74:75]
	v_lshlrev_b32_e32 v176, 1, v191
	v_cvt_pk_f16_f32 v87, v88, v91
	v_cvt_pk_f16_f32 v86, v90, v92
	v_cvt_pk_f16_f32 v85, v89, v93
	v_cvt_pk_f16_f32 v84, v84, v94
	v_lshl_add_u64 v[74:75], v[74:75], 0, v[176:177]
	global_store_dwordx4 v[74:75], v[84:87], off
	s_nop 1
	v_lshlrev_b64 v[84:85], 10, v[198:199]
	v_lshl_add_u64 v[74:75], s[8:9], 0, v[84:85]
	s_branch .LBB0_1598

.LBB0_1598:
	v_mov_b32_e32 v201, v200
	v_pk_fma_f32 v[70:71], v[70:71], v[200:201], v[30:31]
	v_pk_fma_f32 v[72:73], v[72:73], v[200:201], v[32:33]
	v_pk_fma_f32 v[66:67], v[66:67], v[200:201], v[26:27]
	v_pk_fma_f32 v[68:69], v[68:69], v[200:201], v[28:29]
	s_and_b64 vcc, exec, s[4:5]
	s_mov_b64 s[18:19], -1
	s_cbranch_vccnz .LBB0_1616
	s_and_b64 vcc, exec, s[2:3]
	s_cbranch_vccnz .LBB0_1613
	s_cmp_lt_i32 s39, 4
	s_cbranch_scc1 .LBB0_1610
	s_cmp_lg_u32 s39, 4
	s_cbranch_scc0 .LBB0_1607
	s_andn2_b64 vcc, exec, s[56:57]
	s_cbranch_vccnz .LBB0_1604
	v_pk_mul_f32 v[76:77], v[70:71], s[20:21] op_sel_hi:[1,0]
	v_exp_f32_e32 v76, v76
	v_exp_f32_e32 v77, v77
	v_mul_f32_e32 v79, 0xbfb8aa3b, v73
	v_exp_f32_e32 v79, v79
	v_pk_add_f32 v[76:77], v[76:77], 1.0 op_sel_hi:[1,0]
	v_rcp_f32_e32 v76, v76
	v_rcp_f32_e32 v77, v77
	v_mul_f32_e32 v80, 0xbfb8aa3b, v69
	v_mul_f32_e32 v78, 0xbfb8aa3b, v72
	v_max_f32_e32 v82, 0x219392ef, v76
	v_max_f32_e32 v83, 0x219392ef, v77
	v_add_f32_e32 v76, 1.0, v79
	v_mul_f32_e32 v77, 0xbfb8aa3b, v66
	v_mul_f32_e32 v79, 0xbfb8aa3b, v67
	v_rcp_f32_e32 v76, v76
	v_exp_f32_e32 v77, v77
	v_exp_f32_e32 v79, v79
	v_exp_f32_e32 v80, v80
	v_max_f32_e32 v86, 0x219392ef, v76
	v_add_f32_e32 v76, 1.0, v77
	v_add_f32_e32 v77, 1.0, v79
	v_mul_f32_e32 v79, 0xbfb8aa3b, v68
	v_exp_f32_e32 v78, v78
	v_exp_f32_e32 v79, v79
	v_rcp_f32_e32 v76, v76
	v_rcp_f32_e32 v77, v77
	v_add_f32_e32 v80, 1.0, v80
	v_pk_add_f32 v[78:79], v[78:79], 1.0 op_sel_hi:[1,0]
	v_rcp_f32_e32 v80, v80
	v_rcp_f32_e32 v78, v78
	v_rcp_f32_e32 v79, v79
	v_max_f32_e32 v87, 0x219392ef, v76
	v_max_f32_e32 v88, 0x219392ef, v77
	v_lshlrev_b64 v[76:77], 12, v[198:199]
	v_lshl_add_u64 v[76:77], s[16:17], 0, v[76:77]
	v_max_f32_e32 v89, 0x219392ef, v80
	v_lshl_add_u64 v[80:81], v[186:187], 1, v[76:77]
	v_max_f32_e32 v78, 0x219392ef, v78
	v_max_f32_e32 v79, 0x219392ef, v79
	v_add_co_u32_e32 v80, vcc, 0xfffff000, v80
	v_cvt_pk_bf16_f32 v76, v82, v83
	v_cvt_pk_bf16_f32 v77, v78, v86
	v_cvt_pk_bf16_f32 v78, v87, v88
	v_cvt_pk_bf16_f32 v79, v79, v89
	v_addc_co_u32_e32 v81, vcc, -1, v81, vcc
	s_mov_b64 s[18:19], 0
	global_store_dwordx4 v[80:81], v[76:79], off offset:-3840 nt
	s_nop 1
	s_branch .LBB0_1618

.LBB0_1607:
	s_andn2_b64 vcc, exec, s[18:19]
	s_cbranch_vccnz .LBB0_1609
	v_pk_mul_f32 v[76:77], v[70:71], s[20:21] op_sel_hi:[1,0]
	v_pk_mul_f32 v[78:79], v[72:73], s[20:21] op_sel_hi:[1,0]
	v_pk_mul_f32 v[80:81], v[66:67], s[20:21] op_sel_hi:[1,0]
	v_pk_mul_f32 v[82:83], v[68:69], s[20:21] op_sel_hi:[1,0]
	v_exp_f32_e32 v76, v76
	v_exp_f32_e32 v77, v77
	v_exp_f32_e32 v78, v78
	v_exp_f32_e32 v79, v79
	v_exp_f32_e32 v80, v80
	v_exp_f32_e32 v81, v81
	v_exp_f32_e32 v82, v82
	v_exp_f32_e32 v83, v83
	v_pk_add_f32 v[76:77], v[76:77], 1.0 op_sel_hi:[1,0]
	v_pk_add_f32 v[78:79], v[78:79], 1.0 op_sel_hi:[1,0]
	v_pk_add_f32 v[80:81], v[80:81], 1.0 op_sel_hi:[1,0]
	v_pk_add_f32 v[82:83], v[82:83], 1.0 op_sel_hi:[1,0]
	v_rcp_f32_e32 v76, v76
	v_rcp_f32_e32 v77, v77
	v_rcp_f32_e32 v78, v78
	v_rcp_f32_e32 v79, v79
	v_rcp_f32_e32 v80, v80
	v_rcp_f32_e32 v81, v81
	v_rcp_f32_e32 v82, v82
	v_rcp_f32_e32 v83, v83
	v_pk_mul_f32 v[76:77], v[70:71], v[76:77]
	v_pk_mul_f32 v[78:79], v[72:73], v[78:79]
	v_pk_mul_f32 v[80:81], v[66:67], v[80:81]
	v_pk_mul_f32 v[82:83], v[68:69], v[82:83]
	v_lshl_add_u64 v[86:87], s[12:13], 0, v[84:85]
	v_lshl_add_u64 v[86:87], v[186:187], 1, v[86:87]
	v_cvt_pk_bf16_f32 v76, v76, v77
	v_cvt_pk_bf16_f32 v77, v78, v79
	v_cvt_pk_bf16_f32 v78, v80, v81
	v_cvt_pk_bf16_f32 v79, v82, v83
	global_store_dwordx4 v[86:87], v[76:79], off offset:-3840 nt
	s_nop 1
	s_branch .LBB0_1618

.LBB0_1610:
	s_andn2_b64 vcc, exec, s[18:19]
	s_cbranch_vccnz .LBB0_1612
	v_pk_mul_f32 v[76:77], v[70:71], s[20:21] op_sel_hi:[1,0]
	v_pk_mul_f32 v[78:79], v[72:73], s[20:21] op_sel_hi:[1,0]
	v_pk_mul_f32 v[80:81], v[66:67], s[20:21] op_sel_hi:[1,0]
	v_pk_mul_f32 v[82:83], v[68:69], s[20:21] op_sel_hi:[1,0]
	v_exp_f32_e32 v76, v76
	v_exp_f32_e32 v77, v77
	v_exp_f32_e32 v78, v78
	v_exp_f32_e32 v79, v79
	v_exp_f32_e32 v80, v80
	v_exp_f32_e32 v81, v81
	v_exp_f32_e32 v82, v82
	v_exp_f32_e32 v83, v83
	v_pk_add_f32 v[76:77], v[76:77], 1.0 op_sel_hi:[1,0]
	v_pk_add_f32 v[78:79], v[78:79], 1.0 op_sel_hi:[1,0]
	v_pk_add_f32 v[80:81], v[80:81], 1.0 op_sel_hi:[1,0]
	v_pk_add_f32 v[82:83], v[82:83], 1.0 op_sel_hi:[1,0]
	v_rcp_f32_e32 v76, v76
	v_rcp_f32_e32 v77, v77
	v_rcp_f32_e32 v78, v78
	v_rcp_f32_e32 v79, v79
	v_rcp_f32_e32 v80, v80
	v_rcp_f32_e32 v81, v81
	v_rcp_f32_e32 v82, v82
	v_rcp_f32_e32 v83, v83
	v_pk_mul_f32 v[76:77], v[70:71], v[76:77]
	v_pk_mul_f32 v[78:79], v[72:73], v[78:79]
	v_pk_mul_f32 v[80:81], v[66:67], v[80:81]
	v_pk_mul_f32 v[82:83], v[68:69], v[82:83]
	v_lshl_add_u64 v[86:87], s[10:11], 0, v[84:85]
	v_lshl_add_u64 v[86:87], v[186:187], 1, v[86:87]
	v_cvt_pk_bf16_f32 v76, v76, v77
	v_cvt_pk_bf16_f32 v77, v78, v79
	v_cvt_pk_bf16_f32 v78, v80, v81
	v_cvt_pk_bf16_f32 v79, v82, v83
	global_store_dwordx4 v[86:87], v[76:79], off offset:-2816 nt
	s_nop 1
	s_branch .LBB0_1618

.LBB0_1613:
	s_and_b64 vcc, exec, s[18:19]
	s_cbranch_vccz .LBB0_1615
	v_mul_f32_e32 v78, 0xbfb8aa3b, v72
	v_exp_f32_e32 v78, v78
	v_mul_f32_e32 v79, 0xbfb8aa3b, v73
	v_mul_f32_e32 v80, 0xbfb8aa3b, v66
	v_exp_f32_e32 v79, v79
	v_add_f32_e32 v78, 1.0, v78
	v_rcp_f32_e32 v78, v78
	v_exp_f32_e32 v80, v80
	v_mul_f32_e32 v83, 0xbfb8aa3b, v69
	v_fma_f32 v78, v235, v78, v12
	v_log_f32_e32 v81, v78
	v_add_f32_e32 v78, 1.0, v79
	v_add_f32_e32 v79, 1.0, v80
	v_rcp_f32_e32 v79, v79
	v_mul_f32_e32 v80, 0xbfb8aa3b, v67
	v_exp_f32_e32 v80, v80
	v_pk_mul_f32 v[76:77], v[70:71], s[20:21] op_sel_hi:[1,0]
	v_fma_f32 v79, v223, v79, v14
	v_log_f32_e32 v82, v79
	v_add_f32_e32 v79, 1.0, v80
	v_mul_f32_e32 v80, 0xbfb8aa3b, v68
	v_exp_f32_e32 v80, v80
	v_exp_f32_e32 v83, v83
	v_exp_f32_e32 v76, v76
	v_exp_f32_e32 v77, v77
	v_add_f32_e32 v80, 1.0, v80
	v_add_f32_e32 v83, 1.0, v83
	v_pk_add_f32 v[76:77], v[76:77], 1.0 op_sel_hi:[1,0]
	v_rcp_f32_e32 v78, v78
	v_rcp_f32_e32 v80, v80
	v_rcp_f32_e32 v83, v83
	v_rcp_f32_e32 v76, v76
	v_rcp_f32_e32 v77, v77
	v_rcp_f32_e32 v79, v79
	v_fma_f32 v78, v222, v78, v13
	v_fma_f32 v80, v221, v80, v16
	v_fma_f32 v83, v161, v83, v17
	v_fma_f32 v76, v237, v76, v10
	v_fma_f32 v77, v236, v77, v11
	v_fma_f32 v79, v220, v79, v15
	v_log_f32_e32 v80, v80
	v_log_f32_e32 v83, v83
	v_log_f32_e32 v87, v78
	v_log_f32_e32 v76, v76
	v_log_f32_e32 v86, v79
	v_log_f32_e32 v88, v77
	s_and_b64 s[18:19], s[54:55], exec
	s_cselect_b32 s19, s87, s92
	s_cselect_b32 s18, s79, s89
	v_cvt_pk_f16_f32 v79, v80, v83
	v_cvt_pk_f16_f32 v77, v81, v87
	v_lshl_add_u64 v[80:81], s[18:19], 0, v[84:85]
	v_lshlrev_b32_e32 v176, 1, v160
	v_cvt_pk_f16_f32 v78, v82, v86
	v_cvt_pk_f16_f32 v76, v76, v88
	v_lshl_add_u64 v[80:81], v[80:81], 0, v[176:177]
	global_store_dwordx4 v[80:81], v[76:79], off
	s_nop 1
	s_branch .LBB0_1618

.LBB0_1618:
	v_pk_fma_f32 v[62:63], v[62:63], v[196:197], v[54:55] op_sel_hi:[1,0,1]
	v_pk_fma_f32 v[64:65], v[64:65], v[196:197], v[56:57] op_sel_hi:[1,0,1]
	v_pk_fma_f32 v[66:67], v[58:59], v[196:197], v[50:51] op_sel_hi:[1,0,1]
	v_pk_fma_f32 v[60:61], v[60:61], v[196:197], v[52:53] op_sel_hi:[1,0,1]
	s_and_b64 vcc, exec, s[4:5]
	s_mov_b64 s[18:19], -1
	s_cbranch_vccnz .LBB0_1636
	s_and_b64 vcc, exec, s[2:3]
	s_cbranch_vccnz .LBB0_1633
	s_cmp_lt_i32 s39, 4
	s_cbranch_scc1 .LBB0_1630
	s_cmp_lg_u32 s39, 4
	s_cbranch_scc0 .LBB0_1627
	s_andn2_b64 vcc, exec, s[56:57]
	s_cbranch_vccnz .LBB0_1624
	v_pk_mul_f32 v[58:59], v[62:63], s[20:21] op_sel_hi:[1,0]
	v_mul_f32_e32 v68, 0xbfb8aa3b, v64
	v_exp_f32_e32 v58, v58
	v_exp_f32_e32 v59, v59
	v_exp_f32_e32 v68, v68
	v_mul_f32_e32 v69, 0xbfb8aa3b, v65
	v_pk_add_f32 v[58:59], v[58:59], 1.0 op_sel_hi:[1,0]
	v_add_f32_e32 v68, 1.0, v68
	v_rcp_f32_e32 v58, v58
	v_rcp_f32_e32 v59, v59
	v_rcp_f32_e32 v68, v68
	v_exp_f32_e32 v69, v69
	v_max_f32_e32 v70, 0x219392ef, v58
	v_max_f32_e32 v71, 0x219392ef, v59
	v_max_f32_e32 v72, 0x219392ef, v68
	v_add_f32_e32 v58, 1.0, v69
	v_mul_f32_e32 v59, 0xbfb8aa3b, v66
	v_mul_f32_e32 v68, 0xbfb8aa3b, v67
	v_rcp_f32_e32 v58, v58
	v_exp_f32_e32 v59, v59
	v_exp_f32_e32 v68, v68
	v_mul_f32_e32 v73, 0xbfb8aa3b, v61
	v_max_f32_e32 v69, 0x219392ef, v58
	v_add_f32_e32 v58, 1.0, v59
	v_add_f32_e32 v59, 1.0, v68
	v_mul_f32_e32 v68, 0xbfb8aa3b, v60
	v_exp_f32_e32 v68, v68
	v_exp_f32_e32 v73, v73
	v_rcp_f32_e32 v58, v58
	v_rcp_f32_e32 v59, v59
	v_add_f32_e32 v68, 1.0, v68
	v_add_f32_e32 v73, 1.0, v73
	v_rcp_f32_e32 v68, v68
	v_rcp_f32_e32 v73, v73
	v_max_f32_e32 v74, 0x219392ef, v58
	v_max_f32_e32 v75, 0x219392ef, v59
	v_lshlrev_b64 v[58:59], 12, v[194:195]
	v_lshl_add_u64 v[58:59], s[16:17], 0, v[58:59]
	v_lshl_add_u64 v[58:59], v[186:187], 1, v[58:59]
	v_max_f32_e32 v76, 0x219392ef, v68
	v_max_f32_e32 v73, 0x219392ef, v73
	v_add_co_u32_e32 v58, vcc, 0xffffe000, v58
	v_cvt_pk_bf16_f32 v68, v70, v71
	v_cvt_pk_bf16_f32 v69, v72, v69
	v_cvt_pk_bf16_f32 v70, v74, v75
	v_cvt_pk_bf16_f32 v71, v76, v73
	v_addc_co_u32_e32 v59, vcc, -1, v59, vcc
	s_mov_b64 s[18:19], 0
	global_store_dwordx4 v[58:59], v[68:71], off nt
	s_nop 1
	v_lshlrev_b64 v[68:69], 10, v[194:195]
	v_lshl_add_u64 v[58:59], s[8:9], 0, v[68:69]
	s_branch .LBB0_1638

.LBB0_1627:
	s_andn2_b64 vcc, exec, s[18:19]
	s_cbranch_vccnz .LBB0_1629
	v_pk_mul_f32 v[68:69], v[64:65], s[20:21] op_sel_hi:[1,0]
	v_pk_mul_f32 v[58:59], v[62:63], s[20:21] op_sel_hi:[1,0]
	v_exp_f32_e32 v68, v68
	v_exp_f32_e32 v69, v69
	v_pk_mul_f32 v[70:71], v[66:67], s[20:21] op_sel_hi:[1,0]
	v_pk_mul_f32 v[72:73], v[60:61], s[20:21] op_sel_hi:[1,0]
	v_exp_f32_e32 v58, v58
	v_exp_f32_e32 v59, v59
	v_exp_f32_e32 v70, v70
	v_exp_f32_e32 v71, v71
	v_exp_f32_e32 v72, v72
	v_exp_f32_e32 v73, v73
	v_pk_add_f32 v[68:69], v[68:69], 1.0 op_sel_hi:[1,0]
	v_pk_add_f32 v[58:59], v[58:59], 1.0 op_sel_hi:[1,0]
	v_rcp_f32_e32 v68, v68
	v_rcp_f32_e32 v69, v69
	v_pk_add_f32 v[70:71], v[70:71], 1.0 op_sel_hi:[1,0]
	v_pk_add_f32 v[72:73], v[72:73], 1.0 op_sel_hi:[1,0]
	v_rcp_f32_e32 v58, v58
	v_rcp_f32_e32 v59, v59
	v_rcp_f32_e32 v70, v70
	v_rcp_f32_e32 v71, v71
	v_rcp_f32_e32 v72, v72
	v_rcp_f32_e32 v73, v73
	v_pk_mul_f32 v[74:75], v[64:65], v[68:69]
	v_lshlrev_b64 v[68:69], 10, v[194:195]
	v_pk_mul_f32 v[58:59], v[62:63], v[58:59]
	v_pk_mul_f32 v[70:71], v[66:67], v[70:71]
	v_pk_mul_f32 v[72:73], v[60:61], v[72:73]
	v_lshl_add_u64 v[68:69], s[12:13], 0, v[68:69]
	v_lshl_add_u64 v[76:77], v[186:187], 1, v[68:69]
	v_cvt_pk_bf16_f32 v68, v58, v59
	v_cvt_pk_bf16_f32 v69, v74, v75
	v_cvt_pk_bf16_f32 v70, v70, v71
	v_cvt_pk_bf16_f32 v71, v72, v73
	global_store_dwordx4 v[76:77], v[68:71], off offset:-4096 nt
	s_nop 1
	v_lshlrev_b64 v[68:69], 10, v[194:195]
	v_lshl_add_u64 v[58:59], s[8:9], 0, v[68:69]
	s_branch .LBB0_1638

.LBB0_1630:
	s_andn2_b64 vcc, exec, s[18:19]
	s_cbranch_vccnz .LBB0_1632
	v_pk_mul_f32 v[68:69], v[64:65], s[20:21] op_sel_hi:[1,0]
	v_pk_mul_f32 v[58:59], v[62:63], s[20:21] op_sel_hi:[1,0]
	v_exp_f32_e32 v68, v68
	v_exp_f32_e32 v69, v69
	v_pk_mul_f32 v[70:71], v[66:67], s[20:21] op_sel_hi:[1,0]
	v_pk_mul_f32 v[72:73], v[60:61], s[20:21] op_sel_hi:[1,0]
	v_exp_f32_e32 v58, v58
	v_exp_f32_e32 v59, v59
	v_exp_f32_e32 v70, v70
	v_exp_f32_e32 v71, v71
	v_exp_f32_e32 v72, v72
	v_exp_f32_e32 v73, v73
	v_pk_add_f32 v[68:69], v[68:69], 1.0 op_sel_hi:[1,0]
	v_pk_add_f32 v[58:59], v[58:59], 1.0 op_sel_hi:[1,0]
	v_rcp_f32_e32 v68, v68
	v_rcp_f32_e32 v69, v69
	v_pk_add_f32 v[70:71], v[70:71], 1.0 op_sel_hi:[1,0]
	v_pk_add_f32 v[72:73], v[72:73], 1.0 op_sel_hi:[1,0]
	v_rcp_f32_e32 v58, v58
	v_rcp_f32_e32 v59, v59
	v_rcp_f32_e32 v70, v70
	v_rcp_f32_e32 v71, v71
	v_rcp_f32_e32 v72, v72
	v_rcp_f32_e32 v73, v73
	v_pk_mul_f32 v[74:75], v[64:65], v[68:69]
	v_lshlrev_b64 v[68:69], 10, v[194:195]
	v_pk_mul_f32 v[58:59], v[62:63], v[58:59]
	v_pk_mul_f32 v[70:71], v[66:67], v[70:71]
	v_pk_mul_f32 v[72:73], v[60:61], v[72:73]
	v_lshl_add_u64 v[68:69], s[10:11], 0, v[68:69]
	v_lshl_add_u64 v[76:77], v[186:187], 1, v[68:69]
	v_cvt_pk_bf16_f32 v68, v58, v59
	v_cvt_pk_bf16_f32 v69, v74, v75
	v_cvt_pk_bf16_f32 v70, v70, v71
	v_cvt_pk_bf16_f32 v71, v72, v73
	global_store_dwordx4 v[76:77], v[68:71], off offset:-3072 nt
	s_nop 1
	v_lshlrev_b64 v[68:69], 10, v[194:195]
	v_lshl_add_u64 v[58:59], s[8:9], 0, v[68:69]
	s_branch .LBB0_1638

.LBB0_1633:
	s_and_b64 vcc, exec, s[18:19]
	s_cbranch_vccz .LBB0_1635
	v_mul_f32_e32 v70, 0xbfb8aa3b, v64
	v_exp_f32_e32 v70, v70
	v_mul_f32_e32 v71, 0xbfb8aa3b, v65
	v_mul_f32_e32 v72, 0xbfb8aa3b, v66
	v_exp_f32_e32 v71, v71
	v_add_f32_e32 v70, 1.0, v70
	v_rcp_f32_e32 v70, v70
	v_exp_f32_e32 v72, v72
	v_mul_f32_e32 v58, 0xbfb8aa3b, v62
	v_mul_f32_e32 v69, 0xbfb8aa3b, v63
	v_fma_f32 v70, v240, v70, v40
	v_log_f32_e32 v73, v70
	v_add_f32_e32 v70, 1.0, v71
	v_add_f32_e32 v71, 1.0, v72
	v_rcp_f32_e32 v71, v71
	v_mul_f32_e32 v72, 0xbfb8aa3b, v67
	v_exp_f32_e32 v72, v72
	v_mul_f32_e32 v75, 0xbfb8aa3b, v61
	v_fma_f32 v71, v238, v71, v34
	v_log_f32_e32 v74, v71
	v_add_f32_e32 v71, 1.0, v72
	v_mul_f32_e32 v72, 0xbfb8aa3b, v60
	v_exp_f32_e32 v68, v58
	v_exp_f32_e32 v69, v69
	v_exp_f32_e32 v72, v72
	v_exp_f32_e32 v75, v75
	v_pk_add_f32 v[68:69], v[68:69], 1.0 op_sel_hi:[1,0]
	v_add_f32_e32 v72, 1.0, v72
	v_add_f32_e32 v75, 1.0, v75
	v_rcp_f32_e32 v68, v68
	v_rcp_f32_e32 v69, v69
	v_rcp_f32_e32 v70, v70
	v_rcp_f32_e32 v71, v71
	v_rcp_f32_e32 v72, v72
	v_rcp_f32_e32 v75, v75
	v_fma_f32 v68, v242, v68, v38
	v_fma_f32 v69, v241, v69, v39
	v_fma_f32 v70, v239, v70, v41
	v_fma_f32 v71, v234, v71, v35
	v_fma_f32 v72, v233, v72, v36
	v_fma_f32 v75, v229, v75, v37
	v_log_f32_e32 v68, v68
	v_log_f32_e32 v72, v72
	v_log_f32_e32 v75, v75
	v_log_f32_e32 v76, v71
	v_log_f32_e32 v77, v70
	v_log_f32_e32 v78, v69
	s_and_b64 s[18:19], s[54:55], exec
	s_cselect_b32 s19, s87, s92
	s_cselect_b32 s18, s79, s89
	v_lshlrev_b64 v[58:59], 10, v[194:195]
	v_lshl_add_u64 v[58:59], s[18:19], 0, v[58:59]
	v_lshlrev_b32_e32 v176, 1, v191
	v_cvt_pk_f16_f32 v71, v72, v75
	v_cvt_pk_f16_f32 v70, v74, v76
	v_cvt_pk_f16_f32 v69, v73, v77
	v_cvt_pk_f16_f32 v68, v68, v78
	v_lshl_add_u64 v[58:59], v[58:59], 0, v[176:177]
	global_store_dwordx4 v[58:59], v[68:71], off
	s_nop 1
	v_lshlrev_b64 v[68:69], 10, v[194:195]
	v_lshl_add_u64 v[58:59], s[8:9], 0, v[68:69]
	s_branch .LBB0_1638

.LBB0_1638:
	v_mov_b32_e32 v197, v196
	v_pk_fma_f32 v[46:47], v[46:47], v[196:197], v[30:31]
	v_pk_fma_f32 v[48:49], v[48:49], v[196:197], v[32:33]
	v_pk_fma_f32 v[42:43], v[42:43], v[196:197], v[26:27]
	v_pk_fma_f32 v[44:45], v[44:45], v[196:197], v[28:29]
	s_and_b64 vcc, exec, s[4:5]
	s_mov_b64 s[18:19], -1
	s_cbranch_vccnz .LBB0_1656
	s_and_b64 vcc, exec, s[2:3]
	s_cbranch_vccnz .LBB0_1653
	s_cmp_lt_i32 s39, 4
	s_cbranch_scc1 .LBB0_1650
	s_cmp_lg_u32 s39, 4
	s_cbranch_scc0 .LBB0_1647
	s_andn2_b64 vcc, exec, s[56:57]
	s_cbranch_vccnz .LBB0_1644
	v_pk_mul_f32 v[60:61], v[46:47], s[20:21] op_sel_hi:[1,0]
	v_exp_f32_e32 v60, v60
	v_exp_f32_e32 v61, v61
	v_mul_f32_e32 v63, 0xbfb8aa3b, v49
	v_exp_f32_e32 v63, v63
	v_pk_add_f32 v[60:61], v[60:61], 1.0 op_sel_hi:[1,0]
	v_rcp_f32_e32 v60, v60
	v_rcp_f32_e32 v61, v61
	v_mul_f32_e32 v64, 0xbfb8aa3b, v45
	v_mul_f32_e32 v62, 0xbfb8aa3b, v48
	v_max_f32_e32 v66, 0x219392ef, v60
	v_max_f32_e32 v67, 0x219392ef, v61
	v_add_f32_e32 v60, 1.0, v63
	v_mul_f32_e32 v61, 0xbfb8aa3b, v42
	v_mul_f32_e32 v63, 0xbfb8aa3b, v43
	v_rcp_f32_e32 v60, v60
	v_exp_f32_e32 v61, v61
	v_exp_f32_e32 v63, v63
	v_exp_f32_e32 v64, v64
	v_max_f32_e32 v70, 0x219392ef, v60
	v_add_f32_e32 v60, 1.0, v61
	v_add_f32_e32 v61, 1.0, v63
	v_mul_f32_e32 v63, 0xbfb8aa3b, v44
	v_exp_f32_e32 v62, v62
	v_exp_f32_e32 v63, v63
	v_rcp_f32_e32 v60, v60
	v_rcp_f32_e32 v61, v61
	v_add_f32_e32 v64, 1.0, v64
	v_pk_add_f32 v[62:63], v[62:63], 1.0 op_sel_hi:[1,0]
	v_rcp_f32_e32 v64, v64
	v_rcp_f32_e32 v62, v62
	v_rcp_f32_e32 v63, v63
	v_max_f32_e32 v71, 0x219392ef, v60
	v_max_f32_e32 v72, 0x219392ef, v61
	v_lshlrev_b64 v[60:61], 12, v[194:195]
	v_lshl_add_u64 v[60:61], s[16:17], 0, v[60:61]
	v_max_f32_e32 v73, 0x219392ef, v64
	v_lshl_add_u64 v[64:65], v[186:187], 1, v[60:61]
	v_max_f32_e32 v62, 0x219392ef, v62
	v_max_f32_e32 v63, 0x219392ef, v63
	v_add_co_u32_e32 v64, vcc, 0xfffff000, v64
	v_cvt_pk_bf16_f32 v60, v66, v67
	v_cvt_pk_bf16_f32 v61, v62, v70
	v_cvt_pk_bf16_f32 v62, v71, v72
	v_cvt_pk_bf16_f32 v63, v63, v73
	v_addc_co_u32_e32 v65, vcc, -1, v65, vcc
	s_mov_b64 s[18:19], 0
	global_store_dwordx4 v[64:65], v[60:63], off offset:-3840 nt
	s_nop 1
	s_branch .LBB0_1658

.LBB0_1647:
	s_andn2_b64 vcc, exec, s[18:19]
	s_cbranch_vccnz .LBB0_1649
	v_pk_mul_f32 v[60:61], v[46:47], s[20:21] op_sel_hi:[1,0]
	v_pk_mul_f32 v[62:63], v[48:49], s[20:21] op_sel_hi:[1,0]
	v_pk_mul_f32 v[64:65], v[42:43], s[20:21] op_sel_hi:[1,0]
	v_pk_mul_f32 v[66:67], v[44:45], s[20:21] op_sel_hi:[1,0]
	v_exp_f32_e32 v60, v60
	v_exp_f32_e32 v61, v61
	v_exp_f32_e32 v62, v62
	v_exp_f32_e32 v63, v63
	v_exp_f32_e32 v64, v64
	v_exp_f32_e32 v65, v65
	v_exp_f32_e32 v66, v66
	v_exp_f32_e32 v67, v67
	v_pk_add_f32 v[60:61], v[60:61], 1.0 op_sel_hi:[1,0]
	v_pk_add_f32 v[62:63], v[62:63], 1.0 op_sel_hi:[1,0]
	v_pk_add_f32 v[64:65], v[64:65], 1.0 op_sel_hi:[1,0]
	v_pk_add_f32 v[66:67], v[66:67], 1.0 op_sel_hi:[1,0]
	v_rcp_f32_e32 v60, v60
	v_rcp_f32_e32 v61, v61
	v_rcp_f32_e32 v62, v62
	v_rcp_f32_e32 v63, v63
	v_rcp_f32_e32 v64, v64
	v_rcp_f32_e32 v65, v65
	v_rcp_f32_e32 v66, v66
	v_rcp_f32_e32 v67, v67
	v_pk_mul_f32 v[60:61], v[46:47], v[60:61]
	v_pk_mul_f32 v[62:63], v[48:49], v[62:63]
	v_pk_mul_f32 v[64:65], v[42:43], v[64:65]
	v_pk_mul_f32 v[66:67], v[44:45], v[66:67]
	v_lshl_add_u64 v[70:71], s[12:13], 0, v[68:69]
	v_lshl_add_u64 v[70:71], v[186:187], 1, v[70:71]
	v_cvt_pk_bf16_f32 v60, v60, v61
	v_cvt_pk_bf16_f32 v61, v62, v63
	v_cvt_pk_bf16_f32 v62, v64, v65
	v_cvt_pk_bf16_f32 v63, v66, v67
	global_store_dwordx4 v[70:71], v[60:63], off offset:-3840 nt
	s_nop 1
	s_branch .LBB0_1658

.LBB0_1650:
	s_andn2_b64 vcc, exec, s[18:19]
	s_cbranch_vccnz .LBB0_1652
	v_pk_mul_f32 v[60:61], v[46:47], s[20:21] op_sel_hi:[1,0]
	v_pk_mul_f32 v[62:63], v[48:49], s[20:21] op_sel_hi:[1,0]
	v_pk_mul_f32 v[64:65], v[42:43], s[20:21] op_sel_hi:[1,0]
	v_pk_mul_f32 v[66:67], v[44:45], s[20:21] op_sel_hi:[1,0]
	v_exp_f32_e32 v60, v60
	v_exp_f32_e32 v61, v61
	v_exp_f32_e32 v62, v62
	v_exp_f32_e32 v63, v63
	v_exp_f32_e32 v64, v64
	v_exp_f32_e32 v65, v65
	v_exp_f32_e32 v66, v66
	v_exp_f32_e32 v67, v67
	v_pk_add_f32 v[60:61], v[60:61], 1.0 op_sel_hi:[1,0]
	v_pk_add_f32 v[62:63], v[62:63], 1.0 op_sel_hi:[1,0]
	v_pk_add_f32 v[64:65], v[64:65], 1.0 op_sel_hi:[1,0]
	v_pk_add_f32 v[66:67], v[66:67], 1.0 op_sel_hi:[1,0]
	v_rcp_f32_e32 v60, v60
	v_rcp_f32_e32 v61, v61
	v_rcp_f32_e32 v62, v62
	v_rcp_f32_e32 v63, v63
	v_rcp_f32_e32 v64, v64
	v_rcp_f32_e32 v65, v65
	v_rcp_f32_e32 v66, v66
	v_rcp_f32_e32 v67, v67
	v_pk_mul_f32 v[60:61], v[46:47], v[60:61]
	v_pk_mul_f32 v[62:63], v[48:49], v[62:63]
	v_pk_mul_f32 v[64:65], v[42:43], v[64:65]
	v_pk_mul_f32 v[66:67], v[44:45], v[66:67]
	v_lshl_add_u64 v[70:71], s[10:11], 0, v[68:69]
	v_lshl_add_u64 v[70:71], v[186:187], 1, v[70:71]
	v_cvt_pk_bf16_f32 v60, v60, v61
	v_cvt_pk_bf16_f32 v61, v62, v63
	v_cvt_pk_bf16_f32 v62, v64, v65
	v_cvt_pk_bf16_f32 v63, v66, v67
	global_store_dwordx4 v[70:71], v[60:63], off offset:-2816 nt
	s_nop 1
	s_branch .LBB0_1658

.LBB0_1653:
	s_and_b64 vcc, exec, s[18:19]
	s_cbranch_vccz .LBB0_1655
	v_mul_f32_e32 v62, 0xbfb8aa3b, v48
	v_exp_f32_e32 v62, v62
	v_mul_f32_e32 v63, 0xbfb8aa3b, v49
	v_mul_f32_e32 v64, 0xbfb8aa3b, v42
	v_exp_f32_e32 v63, v63
	v_add_f32_e32 v62, 1.0, v62
	v_rcp_f32_e32 v62, v62
	v_exp_f32_e32 v64, v64
	v_mul_f32_e32 v67, 0xbfb8aa3b, v45
	v_fma_f32 v62, v235, v62, v12
	v_log_f32_e32 v65, v62
	v_add_f32_e32 v62, 1.0, v63
	v_add_f32_e32 v63, 1.0, v64
	v_rcp_f32_e32 v63, v63
	v_mul_f32_e32 v64, 0xbfb8aa3b, v43
	v_exp_f32_e32 v64, v64
	v_pk_mul_f32 v[60:61], v[46:47], s[20:21] op_sel_hi:[1,0]
	v_fma_f32 v63, v223, v63, v14
	v_log_f32_e32 v66, v63
	v_add_f32_e32 v63, 1.0, v64
	v_mul_f32_e32 v64, 0xbfb8aa3b, v44
	v_exp_f32_e32 v64, v64
	v_exp_f32_e32 v67, v67
	v_exp_f32_e32 v60, v60
	v_exp_f32_e32 v61, v61
	v_add_f32_e32 v64, 1.0, v64
	v_add_f32_e32 v67, 1.0, v67
	v_pk_add_f32 v[60:61], v[60:61], 1.0 op_sel_hi:[1,0]
	v_rcp_f32_e32 v62, v62
	v_rcp_f32_e32 v64, v64
	v_rcp_f32_e32 v67, v67
	v_rcp_f32_e32 v60, v60
	v_rcp_f32_e32 v61, v61
	v_rcp_f32_e32 v63, v63
	v_fma_f32 v62, v222, v62, v13
	v_fma_f32 v64, v221, v64, v16
	v_fma_f32 v67, v161, v67, v17
	v_fma_f32 v60, v237, v60, v10
	v_fma_f32 v61, v236, v61, v11
	v_fma_f32 v63, v220, v63, v15
	v_log_f32_e32 v64, v64
	v_log_f32_e32 v67, v67
	v_log_f32_e32 v71, v62
	v_log_f32_e32 v60, v60
	v_log_f32_e32 v70, v63
	v_log_f32_e32 v72, v61
	s_and_b64 s[18:19], s[54:55], exec
	s_cselect_b32 s19, s87, s92
	s_cselect_b32 s18, s79, s89
	v_cvt_pk_f16_f32 v63, v64, v67
	v_cvt_pk_f16_f32 v61, v65, v71
	v_lshl_add_u64 v[64:65], s[18:19], 0, v[68:69]
	v_lshlrev_b32_e32 v176, 1, v160
	v_cvt_pk_f16_f32 v62, v66, v70
	v_cvt_pk_f16_f32 v60, v60, v72
	v_lshl_add_u64 v[64:65], v[64:65], 0, v[176:177]
	global_store_dwordx4 v[64:65], v[60:63], off
	s_nop 1
	s_branch .LBB0_1658

.LBB0_1658:
	v_pk_fma_f32 v[22:23], v[22:23], v[190:191], v[54:55] op_sel_hi:[1,0,1]
	v_pk_fma_f32 v[24:25], v[24:25], v[190:191], v[56:57] op_sel_hi:[1,0,1]
	v_pk_fma_f32 v[18:19], v[18:19], v[190:191], v[50:51] op_sel_hi:[1,0,1]
	v_pk_fma_f32 v[20:21], v[20:21], v[190:191], v[52:53] op_sel_hi:[1,0,1]
	s_and_b64 vcc, exec, s[4:5]
	s_mov_b64 s[18:19], -1
	s_cbranch_vccnz .LBB0_1676
	s_and_b64 vcc, exec, s[2:3]
	s_cbranch_vccnz .LBB0_1673
	s_cmp_lt_i32 s39, 4
	s_cbranch_scc1 .LBB0_1670
	s_cmp_lg_u32 s39, 4
	s_cbranch_scc0 .LBB0_1667
	s_andn2_b64 vcc, exec, s[56:57]
	s_cbranch_vccnz .LBB0_1664
	v_pk_mul_f32 v[42:43], v[22:23], s[20:21] op_sel_hi:[1,0]
	v_exp_f32_e32 v42, v42
	v_exp_f32_e32 v43, v43
	v_mul_f32_e32 v45, 0xbfb8aa3b, v25
	v_exp_f32_e32 v45, v45
	v_pk_add_f32 v[42:43], v[42:43], 1.0 op_sel_hi:[1,0]
	v_rcp_f32_e32 v42, v42
	v_rcp_f32_e32 v43, v43
	v_mul_f32_e32 v46, 0xbfb8aa3b, v21
	v_mul_f32_e32 v44, 0xbfb8aa3b, v24
	v_max_f32_e32 v48, 0x219392ef, v42
	v_max_f32_e32 v49, 0x219392ef, v43
	v_add_f32_e32 v42, 1.0, v45
	v_mul_f32_e32 v43, 0xbfb8aa3b, v18
	v_mul_f32_e32 v45, 0xbfb8aa3b, v19
	v_rcp_f32_e32 v42, v42
	v_exp_f32_e32 v43, v43
	v_exp_f32_e32 v45, v45
	v_exp_f32_e32 v46, v46
	v_max_f32_e32 v50, 0x219392ef, v42
	v_add_f32_e32 v42, 1.0, v43
	v_add_f32_e32 v43, 1.0, v45
	v_mul_f32_e32 v45, 0xbfb8aa3b, v20
	v_exp_f32_e32 v44, v44
	v_exp_f32_e32 v45, v45
	v_rcp_f32_e32 v42, v42
	v_rcp_f32_e32 v43, v43
	v_add_f32_e32 v46, 1.0, v46
	v_pk_add_f32 v[44:45], v[44:45], 1.0 op_sel_hi:[1,0]
	v_rcp_f32_e32 v46, v46
	v_rcp_f32_e32 v44, v44
	v_rcp_f32_e32 v45, v45
	v_max_f32_e32 v51, 0x219392ef, v42
	v_max_f32_e32 v52, 0x219392ef, v43
	v_lshlrev_b64 v[42:43], 12, v[188:189]
	v_lshl_add_u64 v[42:43], s[16:17], 0, v[42:43]
	v_max_f32_e32 v53, 0x219392ef, v46
	v_lshl_add_u64 v[46:47], v[186:187], 1, v[42:43]
	v_max_f32_e32 v44, 0x219392ef, v44
	v_max_f32_e32 v45, 0x219392ef, v45
	v_add_co_u32_e32 v46, vcc, 0xffffe000, v46
	v_cvt_pk_bf16_f32 v42, v48, v49
	v_cvt_pk_bf16_f32 v43, v44, v50
	v_cvt_pk_bf16_f32 v44, v51, v52
	v_cvt_pk_bf16_f32 v45, v45, v53
	v_addc_co_u32_e32 v47, vcc, -1, v47, vcc
	s_mov_b64 s[18:19], 0
	global_store_dwordx4 v[46:47], v[42:45], off nt
	s_nop 1
	v_lshlrev_b64 v[36:37], 10, v[188:189]
	v_lshl_add_u64 v[34:35], s[8:9], 0, v[36:37]
	s_branch .LBB0_1678

.LBB0_1667:
	s_andn2_b64 vcc, exec, s[18:19]
	s_cbranch_vccnz .LBB0_1669
	v_pk_mul_f32 v[42:43], v[22:23], s[20:21] op_sel_hi:[1,0]
	v_pk_mul_f32 v[44:45], v[24:25], s[20:21] op_sel_hi:[1,0]
	v_pk_mul_f32 v[46:47], v[18:19], s[20:21] op_sel_hi:[1,0]
	v_pk_mul_f32 v[48:49], v[20:21], s[20:21] op_sel_hi:[1,0]
	v_exp_f32_e32 v42, v42
	v_exp_f32_e32 v43, v43
	v_exp_f32_e32 v44, v44
	v_exp_f32_e32 v45, v45
	v_exp_f32_e32 v46, v46
	v_exp_f32_e32 v47, v47
	v_exp_f32_e32 v48, v48
	v_exp_f32_e32 v49, v49
	v_pk_add_f32 v[42:43], v[42:43], 1.0 op_sel_hi:[1,0]
	v_pk_add_f32 v[44:45], v[44:45], 1.0 op_sel_hi:[1,0]
	v_pk_add_f32 v[46:47], v[46:47], 1.0 op_sel_hi:[1,0]
	v_pk_add_f32 v[48:49], v[48:49], 1.0 op_sel_hi:[1,0]
	v_rcp_f32_e32 v42, v42
	v_rcp_f32_e32 v43, v43
	v_rcp_f32_e32 v44, v44
	v_rcp_f32_e32 v45, v45
	v_rcp_f32_e32 v46, v46
	v_rcp_f32_e32 v47, v47
	v_rcp_f32_e32 v48, v48
	v_rcp_f32_e32 v49, v49
	v_lshlrev_b64 v[50:51], 10, v[188:189]
	v_pk_mul_f32 v[42:43], v[22:23], v[42:43]
	v_pk_mul_f32 v[44:45], v[24:25], v[44:45]
	v_pk_mul_f32 v[46:47], v[18:19], v[46:47]
	v_pk_mul_f32 v[48:49], v[20:21], v[48:49]
	v_lshl_add_u64 v[50:51], s[12:13], 0, v[50:51]
	v_lshl_add_u64 v[50:51], v[186:187], 1, v[50:51]
	v_cvt_pk_bf16_f32 v42, v42, v43
	v_cvt_pk_bf16_f32 v43, v44, v45
	v_cvt_pk_bf16_f32 v44, v46, v47
	v_cvt_pk_bf16_f32 v45, v48, v49
	global_store_dwordx4 v[50:51], v[42:45], off offset:-4096 nt
	s_nop 1
	v_lshlrev_b64 v[36:37], 10, v[188:189]
	v_lshl_add_u64 v[34:35], s[8:9], 0, v[36:37]
	s_branch .LBB0_1678

.LBB0_1670:
	s_andn2_b64 vcc, exec, s[18:19]
	s_cbranch_vccnz .LBB0_1672
	v_pk_mul_f32 v[42:43], v[22:23], s[20:21] op_sel_hi:[1,0]
	v_pk_mul_f32 v[44:45], v[24:25], s[20:21] op_sel_hi:[1,0]
	v_pk_mul_f32 v[46:47], v[18:19], s[20:21] op_sel_hi:[1,0]
	v_pk_mul_f32 v[48:49], v[20:21], s[20:21] op_sel_hi:[1,0]
	v_exp_f32_e32 v42, v42
	v_exp_f32_e32 v43, v43
	v_exp_f32_e32 v44, v44
	v_exp_f32_e32 v45, v45
	v_exp_f32_e32 v46, v46
	v_exp_f32_e32 v47, v47
	v_exp_f32_e32 v48, v48
	v_exp_f32_e32 v49, v49
	v_pk_add_f32 v[42:43], v[42:43], 1.0 op_sel_hi:[1,0]
	v_pk_add_f32 v[44:45], v[44:45], 1.0 op_sel_hi:[1,0]
	v_pk_add_f32 v[46:47], v[46:47], 1.0 op_sel_hi:[1,0]
	v_pk_add_f32 v[48:49], v[48:49], 1.0 op_sel_hi:[1,0]
	v_rcp_f32_e32 v42, v42
	v_rcp_f32_e32 v43, v43
	v_rcp_f32_e32 v44, v44
	v_rcp_f32_e32 v45, v45
	v_rcp_f32_e32 v46, v46
	v_rcp_f32_e32 v47, v47
	v_rcp_f32_e32 v48, v48
	v_rcp_f32_e32 v49, v49
	v_lshlrev_b64 v[50:51], 10, v[188:189]
	v_pk_mul_f32 v[42:43], v[22:23], v[42:43]
	v_pk_mul_f32 v[44:45], v[24:25], v[44:45]
	v_pk_mul_f32 v[46:47], v[18:19], v[46:47]
	v_pk_mul_f32 v[48:49], v[20:21], v[48:49]
	v_lshl_add_u64 v[50:51], s[10:11], 0, v[50:51]
	v_lshl_add_u64 v[50:51], v[186:187], 1, v[50:51]
	v_cvt_pk_bf16_f32 v42, v42, v43
	v_cvt_pk_bf16_f32 v43, v44, v45
	v_cvt_pk_bf16_f32 v44, v46, v47
	v_cvt_pk_bf16_f32 v45, v48, v49
	global_store_dwordx4 v[50:51], v[42:45], off offset:-3072 nt
	s_nop 1
	v_lshlrev_b64 v[36:37], 10, v[188:189]
	v_lshl_add_u64 v[34:35], s[8:9], 0, v[36:37]
	s_branch .LBB0_1678

.LBB0_1678:
	v_mov_b32_e32 v191, v190
	v_pk_fma_f32 v[6:7], v[6:7], v[190:191], v[30:31]
	v_pk_fma_f32 v[8:9], v[8:9], v[190:191], v[32:33]
	v_pk_fma_f32 v[2:3], v[2:3], v[190:191], v[26:27]
	v_pk_fma_f32 v[4:5], v[4:5], v[190:191], v[28:29]
	s_and_b64 vcc, exec, s[4:5]
	s_mov_b64 s[4:5], -1
	s_cbranch_vccnz .LBB0_1696
	s_and_b64 vcc, exec, s[2:3]
	s_mov_b64 s[2:3], -1
	s_cbranch_vccnz .LBB0_1693
	s_cmp_lt_i32 s39, 4
	s_cbranch_scc1 .LBB0_1690
	s_cmp_lg_u32 s39, 4
	s_cbranch_scc0 .LBB0_1687
	s_andn2_b64 vcc, exec, s[56:57]
	s_cbranch_vccnz .LBB0_1684
	v_pk_mul_f32 v[18:19], v[6:7], s[20:21] op_sel_hi:[1,0]
	v_exp_f32_e32 v18, v18
	v_exp_f32_e32 v19, v19
	v_mul_f32_e32 v21, 0xbfb8aa3b, v9
	v_exp_f32_e32 v21, v21
	v_pk_add_f32 v[18:19], v[18:19], 1.0 op_sel_hi:[1,0]
	v_rcp_f32_e32 v18, v18
	v_rcp_f32_e32 v19, v19
	v_mul_f32_e32 v22, 0xbfb8aa3b, v5
	v_mul_f32_e32 v20, 0xbfb8aa3b, v8
	v_max_f32_e32 v24, 0x219392ef, v18
	v_max_f32_e32 v25, 0x219392ef, v19
	v_add_f32_e32 v18, 1.0, v21
	v_mul_f32_e32 v19, 0xbfb8aa3b, v2
	v_mul_f32_e32 v21, 0xbfb8aa3b, v3
	v_rcp_f32_e32 v18, v18
	v_exp_f32_e32 v19, v19
	v_exp_f32_e32 v21, v21
	v_exp_f32_e32 v22, v22
	v_max_f32_e32 v26, 0x219392ef, v18
	v_add_f32_e32 v18, 1.0, v19
	v_add_f32_e32 v19, 1.0, v21
	v_mul_f32_e32 v21, 0xbfb8aa3b, v4
	v_exp_f32_e32 v20, v20
	v_exp_f32_e32 v21, v21
	v_rcp_f32_e32 v18, v18
	v_rcp_f32_e32 v19, v19
	v_add_f32_e32 v22, 1.0, v22
	v_pk_add_f32 v[20:21], v[20:21], 1.0 op_sel_hi:[1,0]
	v_rcp_f32_e32 v22, v22
	v_rcp_f32_e32 v20, v20
	v_rcp_f32_e32 v21, v21
	v_max_f32_e32 v27, 0x219392ef, v18
	v_max_f32_e32 v28, 0x219392ef, v19
	v_lshlrev_b64 v[18:19], 12, v[188:189]
	v_lshl_add_u64 v[18:19], s[16:17], 0, v[18:19]
	v_max_f32_e32 v29, 0x219392ef, v22
	v_lshl_add_u64 v[22:23], v[186:187], 1, v[18:19]
	v_max_f32_e32 v20, 0x219392ef, v20
	v_max_f32_e32 v21, 0x219392ef, v21
	v_add_co_u32_e32 v22, vcc, 0xfffff000, v22
	v_cvt_pk_bf16_f32 v18, v24, v25
	v_cvt_pk_bf16_f32 v19, v20, v26
	v_cvt_pk_bf16_f32 v20, v27, v28
	v_cvt_pk_bf16_f32 v21, v21, v29
	v_addc_co_u32_e32 v23, vcc, -1, v23, vcc
	s_mov_b64 s[2:3], 0
	global_store_dwordx4 v[22:23], v[18:21], off offset:-3840 nt
	s_nop 1
	s_branch .LBB0_1368

.LBB0_1687:
	s_andn2_b64 vcc, exec, s[2:3]
	s_cbranch_vccnz .LBB0_1689
	v_pk_mul_f32 v[18:19], v[6:7], s[20:21] op_sel_hi:[1,0]
	v_pk_mul_f32 v[20:21], v[8:9], s[20:21] op_sel_hi:[1,0]
	v_pk_mul_f32 v[22:23], v[2:3], s[20:21] op_sel_hi:[1,0]
	v_pk_mul_f32 v[24:25], v[4:5], s[20:21] op_sel_hi:[1,0]
	v_exp_f32_e32 v18, v18
	v_exp_f32_e32 v19, v19
	v_exp_f32_e32 v20, v20
	v_exp_f32_e32 v21, v21
	v_exp_f32_e32 v22, v22
	v_exp_f32_e32 v23, v23
	v_exp_f32_e32 v24, v24
	v_exp_f32_e32 v25, v25
	v_pk_add_f32 v[18:19], v[18:19], 1.0 op_sel_hi:[1,0]
	v_pk_add_f32 v[20:21], v[20:21], 1.0 op_sel_hi:[1,0]
	v_pk_add_f32 v[22:23], v[22:23], 1.0 op_sel_hi:[1,0]
	v_pk_add_f32 v[24:25], v[24:25], 1.0 op_sel_hi:[1,0]
	v_rcp_f32_e32 v18, v18
	v_rcp_f32_e32 v19, v19
	v_rcp_f32_e32 v20, v20
	v_rcp_f32_e32 v21, v21
	v_rcp_f32_e32 v22, v22
	v_rcp_f32_e32 v23, v23
	v_rcp_f32_e32 v24, v24
	v_rcp_f32_e32 v25, v25
	v_pk_mul_f32 v[18:19], v[6:7], v[18:19]
	v_pk_mul_f32 v[20:21], v[8:9], v[20:21]
	v_pk_mul_f32 v[22:23], v[2:3], v[22:23]
	v_pk_mul_f32 v[24:25], v[4:5], v[24:25]
	v_lshl_add_u64 v[26:27], s[12:13], 0, v[36:37]
	v_lshl_add_u64 v[26:27], v[186:187], 1, v[26:27]
	v_cvt_pk_bf16_f32 v18, v18, v19
	v_cvt_pk_bf16_f32 v19, v20, v21
	v_cvt_pk_bf16_f32 v20, v22, v23
	v_cvt_pk_bf16_f32 v21, v24, v25
	global_store_dwordx4 v[26:27], v[18:21], off offset:-3840 nt
	s_nop 1
	s_branch .LBB0_1368

.LBB0_1690:
	s_andn2_b64 vcc, exec, s[2:3]
	s_cbranch_vccnz .LBB0_1692
	v_pk_mul_f32 v[18:19], v[6:7], s[20:21] op_sel_hi:[1,0]
	v_pk_mul_f32 v[20:21], v[8:9], s[20:21] op_sel_hi:[1,0]
	v_pk_mul_f32 v[22:23], v[2:3], s[20:21] op_sel_hi:[1,0]
	v_pk_mul_f32 v[24:25], v[4:5], s[20:21] op_sel_hi:[1,0]
	v_exp_f32_e32 v18, v18
	v_exp_f32_e32 v19, v19
	v_exp_f32_e32 v20, v20
	v_exp_f32_e32 v21, v21
	v_exp_f32_e32 v22, v22
	v_exp_f32_e32 v23, v23
	v_exp_f32_e32 v24, v24
	v_exp_f32_e32 v25, v25
	v_pk_add_f32 v[18:19], v[18:19], 1.0 op_sel_hi:[1,0]
	v_pk_add_f32 v[20:21], v[20:21], 1.0 op_sel_hi:[1,0]
	v_pk_add_f32 v[22:23], v[22:23], 1.0 op_sel_hi:[1,0]
	v_pk_add_f32 v[24:25], v[24:25], 1.0 op_sel_hi:[1,0]
	v_rcp_f32_e32 v18, v18
	v_rcp_f32_e32 v19, v19
	v_rcp_f32_e32 v20, v20
	v_rcp_f32_e32 v21, v21
	v_rcp_f32_e32 v22, v22
	v_rcp_f32_e32 v23, v23
	v_rcp_f32_e32 v24, v24
	v_rcp_f32_e32 v25, v25
	v_pk_mul_f32 v[18:19], v[6:7], v[18:19]
	v_pk_mul_f32 v[20:21], v[8:9], v[20:21]
	v_pk_mul_f32 v[22:23], v[2:3], v[22:23]
	v_pk_mul_f32 v[24:25], v[4:5], v[24:25]
	v_lshl_add_u64 v[26:27], s[10:11], 0, v[36:37]
	v_lshl_add_u64 v[26:27], v[186:187], 1, v[26:27]
	v_cvt_pk_bf16_f32 v18, v18, v19
	v_cvt_pk_bf16_f32 v19, v20, v21
	v_cvt_pk_bf16_f32 v20, v22, v23
	v_cvt_pk_bf16_f32 v21, v24, v25
	global_store_dwordx4 v[26:27], v[18:21], off offset:-2816 nt
	s_nop 1
	s_branch .LBB0_1368

.LBB0_1693:
	s_and_b64 vcc, exec, s[2:3]
	s_cbranch_vccz .LBB0_1695
	v_pk_mul_f32 v[18:19], v[6:7], s[20:21] op_sel_hi:[1,0]
	v_exp_f32_e32 v18, v18
	v_exp_f32_e32 v19, v19
	v_mul_f32_e32 v20, 0xbfb8aa3b, v8
	v_exp_f32_e32 v20, v20
	v_pk_add_f32 v[18:19], v[18:19], 1.0 op_sel_hi:[1,0]
	v_rcp_f32_e32 v18, v18
	v_rcp_f32_e32 v19, v19
	v_add_f32_e32 v20, 1.0, v20
	v_rcp_f32_e32 v20, v20
	v_fmac_f32_e32 v10, v237, v18
	v_fmac_f32_e32 v11, v236, v19
	v_mul_f32_e32 v18, 0xbfb8aa3b, v9
	v_mul_f32_e32 v19, 0xbfb8aa3b, v2
	v_exp_f32_e32 v18, v18
	v_exp_f32_e32 v19, v19
	v_fmac_f32_e32 v12, v235, v20
	v_log_f32_e32 v20, v12
	v_add_f32_e32 v12, 1.0, v18
	v_add_f32_e32 v18, 1.0, v19
	v_rcp_f32_e32 v18, v18
	v_mul_f32_e32 v19, 0xbfb8aa3b, v3
	v_rcp_f32_e32 v12, v12
	v_exp_f32_e32 v19, v19
	v_fmac_f32_e32 v14, v223, v18
	v_fmac_f32_e32 v13, v222, v12
	v_log_f32_e32 v12, v14
	v_add_f32_e32 v14, 1.0, v19
	v_pk_mul_f32 v[18:19], v[4:5], s[20:21] op_sel_hi:[1,0]
	v_exp_f32_e32 v18, v18
	v_exp_f32_e32 v19, v19
	v_rcp_f32_e32 v14, v14
	v_log_f32_e32 v10, v10
	v_pk_add_f32 v[18:19], v[18:19], 1.0 op_sel_hi:[1,0]
	v_rcp_f32_e32 v18, v18
	v_rcp_f32_e32 v19, v19
	v_fmac_f32_e32 v15, v220, v14
	v_log_f32_e32 v15, v15
	v_fmac_f32_e32 v16, v221, v18
	v_fmac_f32_e32 v17, v161, v19
	v_log_f32_e32 v14, v16
	v_log_f32_e32 v16, v17
	v_log_f32_e32 v17, v13
	v_log_f32_e32 v18, v11
	s_and_b64 s[2:3], s[54:55], exec
	s_cselect_b32 s3, s87, s92
	s_cselect_b32 s2, s79, s89
	v_cvt_pk_f16_f32 v13, v14, v16
	v_cvt_pk_f16_f32 v12, v12, v15
	v_lshl_add_u64 v[14:15], s[2:3], 0, v[36:37]
	v_lshlrev_b32_e32 v176, 1, v160
	v_cvt_pk_f16_f32 v11, v20, v17
	v_cvt_pk_f16_f32 v10, v10, v18
	v_lshl_add_u64 v[14:15], v[14:15], 0, v[176:177]
	global_store_dwordx4 v[14:15], v[10:13], off
	s_nop 1
	s_branch .LBB0_1368

.Ldfr_p12_b:
	s_mov_b32 s20, 0xbfb8aa3b
	s_setprio 0
	s_ashr_i32 s9, s16, 3
	s_mul_hi_i32 s11, s9, 0x5800
	s_mulk_i32 s9, 0x5800
	s_add_u32 s9, s48, s9
	s_addc_u32 s11, s49, s11
	s_lshl_b32 s18, s17, 8
	s_ashr_i32 s19, s18, 31
	s_lshl_b64 s[18:19], s[18:19], 2
	v_lshl_add_u32 v180, s16, 8, v1
	s_add_u32 s18, s9, s18
	s_addc_u32 s19, s11, s19
	v_lshlrev_b32_e32 v130, 2, v156
	v_ashrrev_i32_e32 v181, 31, v180
	global_load_dwordx4 v[142:145], v130, s[18:19]
	v_lshl_add_u64 v[182:183], v[180:181], 2, s[4:5]
	global_load_dword v190, v[182:183], off
	global_load_dwordx4 v[138:141], v130, s[18:19] offset:512
	global_load_dwordx4 v[134:137], v130, s[18:19] offset:16
	s_nop 0
	global_load_dwordx4 v[130:133], v130, s[18:19] offset:528
	v_or_b32_e32 v192, 16, v180
	v_ashrrev_i32_e32 v193, 31, v192
	v_lshl_add_u64 v[168:169], v[192:193], 2, s[4:5]
	global_load_dword v194, v[168:169], off
	v_or_b32_e32 v188, 32, v180
	v_or_b32_e32 v184, 48, v180
	v_mov_b64_e32 v[166:167], s[0:1]
	v_add_u32_e32 v178, 0x90, v180
	v_add_u32_e32 v174, 0xa0, v180
	v_add_u32_e32 v168, 0xb0, v180
	v_ashrrev_i32_e32 v189, 31, v188
	v_ashrrev_i32_e32 v185, 31, v184
	v_add_u32_e32 v193, 0x80, v180
	v_mad_i64_i32 v[196:197], s[18:19], v180, s56, v[166:167]
	v_ashrrev_i32_e32 v179, 31, v178
	v_ashrrev_i32_e32 v175, 31, v174
	v_ashrrev_i32_e32 v169, 31, v168
	v_lshl_add_u64 v[180:181], v[188:189], 2, s[4:5]
	v_lshl_add_u64 v[186:187], v[184:185], 2, s[4:5]
	v_lshl_add_u64 v[198:199], v[178:179], 2, s[4:5]
	v_lshl_add_u64 v[200:201], v[174:175], 2, s[4:5]
	v_lshl_add_u64 v[202:203], v[168:169], 2, s[4:5]
	global_load_dword v204, v[180:181], off
	s_nop 0
	global_load_dword v186, v[186:187], off
	s_nop 0
	global_load_dword v180, v[198:199], off
	global_load_dword v176, v[200:201], off
	global_load_dword v172, v[202:203], off
	s_nop 0
	global_load_dword v182, v[182:183], off offset:512
	s_lshl_b32 s16, s17, 7
	s_ashr_i32 s17, s16, 31
	s_lshl_b64 s[16:17], s[16:17], 1
	v_lshlrev_b32_e32 v154, 1, v156
	v_lshl_add_u64 v[196:197], v[196:197], 0, s[16:17]
	s_and_b64 vcc, exec, s[2:3]
	s_mov_b64 s[34:35], s[14:15]
	s_mov_b64 s[24:25], s[12:13]
	s_waitcnt vmcnt(0)
	v_pk_fma_f32 v[118:119], v[118:119], v[190:191], v[138:139] op_sel_hi:[1,0,1]
	v_pk_fma_f32 v[126:127], v[126:127], v[190:191], v[142:143] op_sel_hi:[1,0,1]
	v_pk_fma_f32 v[128:129], v[128:129], v[190:191], v[144:145] op_sel_hi:[1,0,1]
	v_pk_fma_f32 v[122:123], v[122:123], v[190:191], v[134:135] op_sel_hi:[1,0,1]
	v_pk_fma_f32 v[124:125], v[124:125], v[190:191], v[136:137] op_sel_hi:[1,0,1]
	v_mul_f32_e32 v169, 0xbfb8aa3b, v126
	v_mul_f32_e32 v175, 0xbfb8aa3b, v127
	v_mul_f32_e32 v179, 0xbfb8aa3b, v128
	v_mul_f32_e32 v181, 0xbfb8aa3b, v129
	v_mul_f32_e32 v183, 0xbfb8aa3b, v122
	v_mul_f32_e32 v185, 0xbfb8aa3b, v123
	v_mul_f32_e32 v187, 0xbfb8aa3b, v124
	v_mul_f32_e32 v189, 0xbfb8aa3b, v125
	v_exp_f32_e32 v169, v169
	v_exp_f32_e32 v175, v175
	v_exp_f32_e32 v179, v179
	v_exp_f32_e32 v181, v181
	v_exp_f32_e32 v183, v183
	v_exp_f32_e32 v185, v185
	v_exp_f32_e32 v187, v187
	v_exp_f32_e32 v189, v189
	v_add_f32_e32 v169, 1.0, v169
	v_add_f32_e32 v175, 1.0, v175
	v_add_f32_e32 v179, 1.0, v179
	v_add_f32_e32 v181, 1.0, v181
	v_add_f32_e32 v183, 1.0, v183
	v_add_f32_e32 v185, 1.0, v185
	v_add_f32_e32 v187, 1.0, v187
	v_add_f32_e32 v189, 1.0, v189
	v_pk_fma_f32 v[120:121], v[120:121], v[190:191], v[140:141] op_sel_hi:[1,0,1]
	v_pk_fma_f32 v[114:115], v[114:115], v[190:191], v[130:131] op_sel_hi:[1,0,1]
	v_pk_fma_f32 v[116:117], v[116:117], v[190:191], v[132:133] op_sel_hi:[1,0,1]
	v_rcp_f32_e32 v190, v169
	v_rcp_f32_e32 v191, v175
	v_rcp_f32_e32 v198, v179
	v_rcp_f32_e32 v199, v181
	v_rcp_f32_e32 v200, v183
	v_rcp_f32_e32 v201, v185
	v_rcp_f32_e32 v202, v187
	v_rcp_f32_e32 v203, v189
	v_pk_mul_f32 v[126:127], v[126:127], v[190:191]
	v_pk_mul_f32 v[128:129], v[128:129], v[198:199]
	v_pk_mul_f32 v[122:123], v[122:123], v[200:201]
	v_pk_mul_f32 v[124:125], v[124:125], v[202:203]
	v_pk_mul_f32 v[118:119], v[118:119], v[126:127]
	v_pk_mul_f32 v[120:121], v[120:121], v[128:129]
	v_pk_mul_f32 v[122:123], v[114:115], v[122:123]
	v_pk_mul_f32 v[124:125], v[116:117], v[124:125]
	v_pk_fma_f32 v[110:111], v[110:111], v[194:195], v[142:143] op_sel_hi:[1,0,1]
	v_lshl_add_u64 v[126:127], v[196:197], 0, v[154:155]
	v_cvt_pk_bf16_f32 v114, v118, v119
	v_cvt_pk_bf16_f32 v115, v120, v121
	v_cvt_pk_bf16_f32 v116, v122, v123
	v_cvt_pk_bf16_f32 v117, v124, v125
	v_pk_mul_f32 v[118:119], v[110:111], s[20:21] op_sel_hi:[1,0]
	v_pk_fma_f32 v[112:113], v[112:113], v[194:195], v[144:145] op_sel_hi:[1,0,1]
	v_exp_f32_e32 v118, v118
	v_exp_f32_e32 v119, v119
	global_store_dwordx4 v[126:127], v[114:117], off nt
	v_pk_fma_f32 v[102:103], v[102:103], v[194:195], v[138:139] op_sel_hi:[1,0,1]
	v_pk_fma_f32 v[106:107], v[106:107], v[194:195], v[134:135] op_sel_hi:[1,0,1]
	v_pk_mul_f32 v[116:117], v[112:113], s[20:21] op_sel_hi:[1,0]
	v_exp_f32_e32 v116, v116
	v_exp_f32_e32 v117, v117
	v_pk_add_f32 v[114:115], v[118:119], 1.0 op_sel_hi:[1,0]
	v_rcp_f32_e32 v114, v114
	v_rcp_f32_e32 v115, v115
	v_pk_add_f32 v[116:117], v[116:117], 1.0 op_sel_hi:[1,0]
	v_rcp_f32_e32 v116, v116
	v_rcp_f32_e32 v117, v117
	v_pk_mul_f32 v[110:111], v[110:111], v[114:115]
	v_pk_fma_f32 v[104:105], v[104:105], v[194:195], v[140:141] op_sel_hi:[1,0,1]
	v_pk_mul_f32 v[102:103], v[102:103], v[110:111]
	v_pk_mul_f32 v[110:111], v[112:113], v[116:117]
	v_pk_mul_f32 v[112:113], v[106:107], s[20:21] op_sel_hi:[1,0]
	v_exp_f32_e32 v112, v112
	v_exp_f32_e32 v113, v113
	v_pk_fma_f32 v[108:109], v[108:109], v[194:195], v[136:137] op_sel_hi:[1,0,1]
	v_pk_mul_f32 v[104:105], v[104:105], v[110:111]
	v_pk_add_f32 v[110:111], v[112:113], 1.0 op_sel_hi:[1,0]
	v_pk_mul_f32 v[112:113], v[108:109], s[20:21] op_sel_hi:[1,0]
	v_exp_f32_e32 v112, v112
	v_exp_f32_e32 v113, v113
	v_rcp_f32_e32 v110, v110
	v_rcp_f32_e32 v111, v111
	v_pk_add_f32 v[112:113], v[112:113], 1.0 op_sel_hi:[1,0]
	v_rcp_f32_e32 v112, v112
	v_rcp_f32_e32 v113, v113
	v_pk_mul_f32 v[106:107], v[106:107], v[110:111]
	v_pk_fma_f32 v[98:99], v[98:99], v[194:195], v[130:131] op_sel_hi:[1,0,1]
	v_pk_fma_f32 v[100:101], v[100:101], v[194:195], v[132:133] op_sel_hi:[1,0,1]
	v_pk_mul_f32 v[106:107], v[98:99], v[106:107]
	v_pk_mul_f32 v[98:99], v[108:109], v[112:113]
	v_pk_fma_f32 v[94:95], v[94:95], v[204:205], v[142:143] op_sel_hi:[1,0,1]
	v_pk_mul_f32 v[108:109], v[100:101], v[98:99]
	v_mad_i64_i32 v[98:99], s[18:19], v192, s56, v[166:167]
	v_lshl_add_u64 v[98:99], v[98:99], 0, s[16:17]
	v_lshl_add_u64 v[110:111], v[98:99], 0, v[154:155]
	v_cvt_pk_bf16_f32 v98, v102, v103
	v_cvt_pk_bf16_f32 v99, v104, v105
	v_cvt_pk_bf16_f32 v100, v106, v107
	v_cvt_pk_bf16_f32 v101, v108, v109
	v_pk_mul_f32 v[102:103], v[94:95], s[20:21] op_sel_hi:[1,0]
	v_pk_fma_f32 v[96:97], v[96:97], v[204:205], v[144:145] op_sel_hi:[1,0,1]
	v_exp_f32_e32 v102, v102
	v_exp_f32_e32 v103, v103
	global_store_dwordx4 v[110:111], v[98:101], off nt
	v_pk_fma_f32 v[86:87], v[86:87], v[204:205], v[138:139] op_sel_hi:[1,0,1]
	v_pk_fma_f32 v[90:91], v[90:91], v[204:205], v[134:135] op_sel_hi:[1,0,1]
	v_pk_mul_f32 v[100:101], v[96:97], s[20:21] op_sel_hi:[1,0]
	v_exp_f32_e32 v100, v100
	v_exp_f32_e32 v101, v101
	v_pk_add_f32 v[98:99], v[102:103], 1.0 op_sel_hi:[1,0]
	v_rcp_f32_e32 v98, v98
	v_rcp_f32_e32 v99, v99
	v_pk_add_f32 v[100:101], v[100:101], 1.0 op_sel_hi:[1,0]
	v_rcp_f32_e32 v100, v100
	v_rcp_f32_e32 v101, v101
	v_pk_mul_f32 v[94:95], v[94:95], v[98:99]
	v_pk_fma_f32 v[88:89], v[88:89], v[204:205], v[140:141] op_sel_hi:[1,0,1]
	v_pk_mul_f32 v[86:87], v[86:87], v[94:95]
	v_pk_mul_f32 v[94:95], v[96:97], v[100:101]
	v_pk_mul_f32 v[96:97], v[90:91], s[20:21] op_sel_hi:[1,0]
	v_exp_f32_e32 v96, v96
	v_exp_f32_e32 v97, v97
	v_pk_fma_f32 v[92:93], v[92:93], v[204:205], v[136:137] op_sel_hi:[1,0,1]
	v_pk_mul_f32 v[88:89], v[88:89], v[94:95]
	v_pk_add_f32 v[94:95], v[96:97], 1.0 op_sel_hi:[1,0]
	v_pk_mul_f32 v[96:97], v[92:93], s[20:21] op_sel_hi:[1,0]
	v_exp_f32_e32 v96, v96
	v_exp_f32_e32 v97, v97
	v_rcp_f32_e32 v94, v94
	v_rcp_f32_e32 v95, v95
	v_pk_add_f32 v[96:97], v[96:97], 1.0 op_sel_hi:[1,0]
	v_rcp_f32_e32 v96, v96
	v_rcp_f32_e32 v97, v97
	v_pk_mul_f32 v[90:91], v[90:91], v[94:95]
	v_pk_fma_f32 v[82:83], v[82:83], v[204:205], v[130:131] op_sel_hi:[1,0,1]
	v_pk_fma_f32 v[84:85], v[84:85], v[204:205], v[132:133] op_sel_hi:[1,0,1]
	v_pk_mul_f32 v[90:91], v[82:83], v[90:91]
	v_pk_mul_f32 v[82:83], v[92:93], v[96:97]
	v_pk_fma_f32 v[78:79], v[78:79], v[186:187], v[142:143] op_sel_hi:[1,0,1]
	v_pk_mul_f32 v[92:93], v[84:85], v[82:83]
	v_mad_i64_i32 v[82:83], s[18:19], v188, s56, v[166:167]
	v_lshl_add_u64 v[82:83], v[82:83], 0, s[16:17]
	v_lshl_add_u64 v[94:95], v[82:83], 0, v[154:155]
	v_cvt_pk_bf16_f32 v82, v86, v87
	v_cvt_pk_bf16_f32 v83, v88, v89
	v_cvt_pk_bf16_f32 v84, v90, v91
	v_cvt_pk_bf16_f32 v85, v92, v93
	v_pk_mul_f32 v[86:87], v[78:79], s[20:21] op_sel_hi:[1,0]
	v_pk_fma_f32 v[80:81], v[80:81], v[186:187], v[144:145] op_sel_hi:[1,0,1]
	v_exp_f32_e32 v86, v86
	v_exp_f32_e32 v87, v87
	global_store_dwordx4 v[94:95], v[82:85], off nt
	v_pk_fma_f32 v[70:71], v[70:71], v[186:187], v[138:139] op_sel_hi:[1,0,1]
	v_pk_fma_f32 v[74:75], v[74:75], v[186:187], v[134:135] op_sel_hi:[1,0,1]
	v_pk_mul_f32 v[84:85], v[80:81], s[20:21] op_sel_hi:[1,0]
	v_exp_f32_e32 v84, v84
	v_exp_f32_e32 v85, v85
	v_pk_add_f32 v[82:83], v[86:87], 1.0 op_sel_hi:[1,0]
	v_rcp_f32_e32 v82, v82
	v_rcp_f32_e32 v83, v83
	v_pk_add_f32 v[84:85], v[84:85], 1.0 op_sel_hi:[1,0]
	v_rcp_f32_e32 v84, v84
	v_rcp_f32_e32 v85, v85
	v_pk_mul_f32 v[78:79], v[78:79], v[82:83]
	v_pk_fma_f32 v[72:73], v[72:73], v[186:187], v[140:141] op_sel_hi:[1,0,1]
	v_pk_mul_f32 v[70:71], v[70:71], v[78:79]
	v_pk_mul_f32 v[78:79], v[80:81], v[84:85]
	v_pk_mul_f32 v[80:81], v[74:75], s[20:21] op_sel_hi:[1,0]
	v_exp_f32_e32 v80, v80
	v_exp_f32_e32 v81, v81
	v_pk_fma_f32 v[76:77], v[76:77], v[186:187], v[136:137] op_sel_hi:[1,0,1]
	v_pk_mul_f32 v[72:73], v[72:73], v[78:79]
	v_pk_add_f32 v[78:79], v[80:81], 1.0 op_sel_hi:[1,0]
	v_pk_mul_f32 v[80:81], v[76:77], s[20:21] op_sel_hi:[1,0]
	v_exp_f32_e32 v80, v80
	v_exp_f32_e32 v81, v81
	v_rcp_f32_e32 v78, v78
	v_rcp_f32_e32 v79, v79
	v_pk_add_f32 v[80:81], v[80:81], 1.0 op_sel_hi:[1,0]
	v_rcp_f32_e32 v80, v80
	v_rcp_f32_e32 v81, v81
	v_pk_mul_f32 v[74:75], v[74:75], v[78:79]
	v_pk_fma_f32 v[66:67], v[66:67], v[186:187], v[130:131] op_sel_hi:[1,0,1]
	v_pk_fma_f32 v[68:69], v[68:69], v[186:187], v[132:133] op_sel_hi:[1,0,1]
	v_pk_mul_f32 v[74:75], v[66:67], v[74:75]
	v_pk_mul_f32 v[66:67], v[76:77], v[80:81]
	v_pk_fma_f32 v[62:63], v[62:63], v[182:183], v[142:143] op_sel_hi:[1,0,1]
	v_pk_mul_f32 v[76:77], v[68:69], v[66:67]
	v_mad_i64_i32 v[66:67], s[18:19], v184, s56, v[166:167]
	v_lshl_add_u64 v[66:67], v[66:67], 0, s[16:17]
	v_lshl_add_u64 v[78:79], v[66:67], 0, v[154:155]
	v_cvt_pk_bf16_f32 v66, v70, v71
	v_cvt_pk_bf16_f32 v67, v72, v73
	v_cvt_pk_bf16_f32 v68, v74, v75
	v_cvt_pk_bf16_f32 v69, v76, v77
	v_pk_mul_f32 v[70:71], v[62:63], s[20:21] op_sel_hi:[1,0]
	v_pk_fma_f32 v[64:65], v[64:65], v[182:183], v[144:145] op_sel_hi:[1,0,1]
	v_exp_f32_e32 v70, v70
	v_exp_f32_e32 v71, v71
	global_store_dwordx4 v[78:79], v[66:69], off nt
	v_pk_fma_f32 v[54:55], v[54:55], v[182:183], v[138:139] op_sel_hi:[1,0,1]
	v_pk_fma_f32 v[58:59], v[58:59], v[182:183], v[134:135] op_sel_hi:[1,0,1]
	v_pk_mul_f32 v[68:69], v[64:65], s[20:21] op_sel_hi:[1,0]
	v_exp_f32_e32 v68, v68
	v_exp_f32_e32 v69, v69
	v_pk_add_f32 v[66:67], v[70:71], 1.0 op_sel_hi:[1,0]
	v_rcp_f32_e32 v66, v66
	v_rcp_f32_e32 v67, v67
	v_pk_add_f32 v[68:69], v[68:69], 1.0 op_sel_hi:[1,0]
	v_rcp_f32_e32 v68, v68
	v_rcp_f32_e32 v69, v69
	v_pk_mul_f32 v[62:63], v[62:63], v[66:67]
	v_pk_fma_f32 v[56:57], v[56:57], v[182:183], v[140:141] op_sel_hi:[1,0,1]
	v_pk_mul_f32 v[54:55], v[54:55], v[62:63]
	v_pk_mul_f32 v[62:63], v[64:65], v[68:69]
	v_pk_mul_f32 v[64:65], v[58:59], s[20:21] op_sel_hi:[1,0]
	v_exp_f32_e32 v64, v64
	v_exp_f32_e32 v65, v65
	v_pk_fma_f32 v[60:61], v[60:61], v[182:183], v[136:137] op_sel_hi:[1,0,1]
	v_pk_mul_f32 v[56:57], v[56:57], v[62:63]
	v_pk_add_f32 v[62:63], v[64:65], 1.0 op_sel_hi:[1,0]
	v_pk_mul_f32 v[64:65], v[60:61], s[20:21] op_sel_hi:[1,0]
	v_exp_f32_e32 v64, v64
	v_exp_f32_e32 v65, v65
	v_rcp_f32_e32 v62, v62
	v_rcp_f32_e32 v63, v63
	v_pk_add_f32 v[64:65], v[64:65], 1.0 op_sel_hi:[1,0]
	v_rcp_f32_e32 v64, v64
	v_rcp_f32_e32 v65, v65
	v_pk_mul_f32 v[58:59], v[58:59], v[62:63]
	v_pk_fma_f32 v[50:51], v[50:51], v[182:183], v[130:131] op_sel_hi:[1,0,1]
	v_pk_fma_f32 v[52:53], v[52:53], v[182:183], v[132:133] op_sel_hi:[1,0,1]
	v_pk_mul_f32 v[58:59], v[50:51], v[58:59]
	v_pk_mul_f32 v[50:51], v[60:61], v[64:65]
	v_pk_fma_f32 v[46:47], v[46:47], v[180:181], v[142:143] op_sel_hi:[1,0,1]
	v_pk_mul_f32 v[60:61], v[52:53], v[50:51]
	v_mad_i64_i32 v[50:51], s[18:19], v193, s56, v[166:167]
	v_lshl_add_u64 v[50:51], v[50:51], 0, s[16:17]
	v_lshl_add_u64 v[62:63], v[50:51], 0, v[154:155]
	v_cvt_pk_bf16_f32 v50, v54, v55
	v_cvt_pk_bf16_f32 v51, v56, v57
	v_cvt_pk_bf16_f32 v52, v58, v59
	v_cvt_pk_bf16_f32 v53, v60, v61
	v_pk_mul_f32 v[54:55], v[46:47], s[20:21] op_sel_hi:[1,0]
	v_pk_fma_f32 v[48:49], v[48:49], v[180:181], v[144:145] op_sel_hi:[1,0,1]
	v_exp_f32_e32 v54, v54
	v_exp_f32_e32 v55, v55
	global_store_dwordx4 v[62:63], v[50:53], off nt
	v_pk_fma_f32 v[38:39], v[38:39], v[180:181], v[138:139] op_sel_hi:[1,0,1]
	v_pk_fma_f32 v[42:43], v[42:43], v[180:181], v[134:135] op_sel_hi:[1,0,1]
	v_pk_mul_f32 v[52:53], v[48:49], s[20:21] op_sel_hi:[1,0]
	v_exp_f32_e32 v52, v52
	v_exp_f32_e32 v53, v53
	v_pk_add_f32 v[50:51], v[54:55], 1.0 op_sel_hi:[1,0]
	v_rcp_f32_e32 v50, v50
	v_rcp_f32_e32 v51, v51
	v_pk_add_f32 v[52:53], v[52:53], 1.0 op_sel_hi:[1,0]
	v_rcp_f32_e32 v52, v52
	v_rcp_f32_e32 v53, v53
	v_pk_mul_f32 v[46:47], v[46:47], v[50:51]
	v_pk_fma_f32 v[40:41], v[40:41], v[180:181], v[140:141] op_sel_hi:[1,0,1]
	v_pk_mul_f32 v[38:39], v[38:39], v[46:47]
	v_pk_mul_f32 v[46:47], v[48:49], v[52:53]
	v_pk_mul_f32 v[48:49], v[42:43], s[20:21] op_sel_hi:[1,0]
	v_exp_f32_e32 v48, v48
	v_exp_f32_e32 v49, v49
	v_pk_fma_f32 v[44:45], v[44:45], v[180:181], v[136:137] op_sel_hi:[1,0,1]
	v_pk_mul_f32 v[40:41], v[40:41], v[46:47]
	v_pk_add_f32 v[46:47], v[48:49], 1.0 op_sel_hi:[1,0]
	v_pk_mul_f32 v[48:49], v[44:45], s[20:21] op_sel_hi:[1,0]
	v_exp_f32_e32 v48, v48
	v_exp_f32_e32 v49, v49
	v_rcp_f32_e32 v46, v46
	v_rcp_f32_e32 v47, v47
	v_pk_add_f32 v[48:49], v[48:49], 1.0 op_sel_hi:[1,0]
	v_rcp_f32_e32 v48, v48
	v_rcp_f32_e32 v49, v49
	v_pk_mul_f32 v[42:43], v[42:43], v[46:47]
	v_pk_fma_f32 v[34:35], v[34:35], v[180:181], v[130:131] op_sel_hi:[1,0,1]
	v_pk_fma_f32 v[36:37], v[36:37], v[180:181], v[132:133] op_sel_hi:[1,0,1]
	v_pk_mul_f32 v[42:43], v[34:35], v[42:43]
	v_pk_mul_f32 v[34:35], v[44:45], v[48:49]
	v_pk_fma_f32 v[30:31], v[30:31], v[176:177], v[142:143] op_sel_hi:[1,0,1]
	v_pk_mul_f32 v[44:45], v[36:37], v[34:35]
	v_mad_i64_i32 v[34:35], s[18:19], v178, s56, v[166:167]
	v_lshl_add_u64 v[34:35], v[34:35], 0, s[16:17]
	v_lshl_add_u64 v[46:47], v[34:35], 0, v[154:155]
	v_cvt_pk_bf16_f32 v34, v38, v39
	v_cvt_pk_bf16_f32 v35, v40, v41
	v_cvt_pk_bf16_f32 v36, v42, v43
	v_cvt_pk_bf16_f32 v37, v44, v45
	v_pk_mul_f32 v[38:39], v[30:31], s[20:21] op_sel_hi:[1,0]
	v_pk_fma_f32 v[32:33], v[32:33], v[176:177], v[144:145] op_sel_hi:[1,0,1]
	v_exp_f32_e32 v38, v38
	v_exp_f32_e32 v39, v39
	global_store_dwordx4 v[46:47], v[34:37], off nt
	v_pk_fma_f32 v[22:23], v[22:23], v[176:177], v[138:139] op_sel_hi:[1,0,1]
	v_pk_fma_f32 v[26:27], v[26:27], v[176:177], v[134:135] op_sel_hi:[1,0,1]
	v_pk_mul_f32 v[36:37], v[32:33], s[20:21] op_sel_hi:[1,0]
	v_exp_f32_e32 v36, v36
	v_exp_f32_e32 v37, v37
	v_pk_add_f32 v[34:35], v[38:39], 1.0 op_sel_hi:[1,0]
	v_rcp_f32_e32 v34, v34
	v_rcp_f32_e32 v35, v35
	v_pk_add_f32 v[36:37], v[36:37], 1.0 op_sel_hi:[1,0]
	v_rcp_f32_e32 v36, v36
	v_rcp_f32_e32 v37, v37
	v_pk_mul_f32 v[30:31], v[30:31], v[34:35]
	v_pk_fma_f32 v[24:25], v[24:25], v[176:177], v[140:141] op_sel_hi:[1,0,1]
	v_pk_mul_f32 v[22:23], v[22:23], v[30:31]
	v_pk_mul_f32 v[30:31], v[32:33], v[36:37]
	v_pk_mul_f32 v[32:33], v[26:27], s[20:21] op_sel_hi:[1,0]
	v_exp_f32_e32 v32, v32
	v_exp_f32_e32 v33, v33
	v_pk_fma_f32 v[28:29], v[28:29], v[176:177], v[136:137] op_sel_hi:[1,0,1]
	v_pk_mul_f32 v[24:25], v[24:25], v[30:31]
	v_pk_add_f32 v[30:31], v[32:33], 1.0 op_sel_hi:[1,0]
	v_pk_mul_f32 v[32:33], v[28:29], s[20:21] op_sel_hi:[1,0]
	v_exp_f32_e32 v32, v32
	v_exp_f32_e32 v33, v33
	v_rcp_f32_e32 v30, v30
	v_rcp_f32_e32 v31, v31
	v_pk_add_f32 v[32:33], v[32:33], 1.0 op_sel_hi:[1,0]
	v_rcp_f32_e32 v32, v32
	v_rcp_f32_e32 v33, v33
	v_pk_mul_f32 v[26:27], v[26:27], v[30:31]
	v_pk_fma_f32 v[18:19], v[18:19], v[176:177], v[130:131] op_sel_hi:[1,0,1]
	v_pk_fma_f32 v[20:21], v[20:21], v[176:177], v[132:133] op_sel_hi:[1,0,1]
	v_pk_mul_f32 v[26:27], v[18:19], v[26:27]
	v_pk_mul_f32 v[18:19], v[28:29], v[32:33]
	v_pk_fma_f32 v[14:15], v[14:15], v[172:173], v[142:143] op_sel_hi:[1,0,1]
	v_pk_mul_f32 v[28:29], v[20:21], v[18:19]
	v_mad_i64_i32 v[18:19], s[18:19], v174, s56, v[166:167]
	v_lshl_add_u64 v[18:19], v[18:19], 0, s[16:17]
	v_lshl_add_u64 v[30:31], v[18:19], 0, v[154:155]
	v_cvt_pk_bf16_f32 v18, v22, v23
	v_cvt_pk_bf16_f32 v19, v24, v25
	v_cvt_pk_bf16_f32 v20, v26, v27
	v_cvt_pk_bf16_f32 v21, v28, v29
	v_pk_mul_f32 v[22:23], v[14:15], s[20:21] op_sel_hi:[1,0]
	v_pk_fma_f32 v[16:17], v[16:17], v[172:173], v[144:145] op_sel_hi:[1,0,1]
	v_exp_f32_e32 v22, v22
	v_exp_f32_e32 v23, v23
	global_store_dwordx4 v[30:31], v[18:21], off nt
	v_pk_fma_f32 v[6:7], v[6:7], v[172:173], v[138:139] op_sel_hi:[1,0,1]
	v_pk_fma_f32 v[10:11], v[10:11], v[172:173], v[134:135] op_sel_hi:[1,0,1]
	v_pk_mul_f32 v[20:21], v[16:17], s[20:21] op_sel_hi:[1,0]
	v_exp_f32_e32 v20, v20
	v_exp_f32_e32 v21, v21
	v_pk_add_f32 v[18:19], v[22:23], 1.0 op_sel_hi:[1,0]
	v_rcp_f32_e32 v18, v18
	v_rcp_f32_e32 v19, v19
	v_pk_add_f32 v[20:21], v[20:21], 1.0 op_sel_hi:[1,0]
	v_rcp_f32_e32 v20, v20
	v_rcp_f32_e32 v21, v21
	v_pk_mul_f32 v[14:15], v[14:15], v[18:19]
	v_pk_fma_f32 v[8:9], v[8:9], v[172:173], v[140:141] op_sel_hi:[1,0,1]
	v_pk_mul_f32 v[6:7], v[6:7], v[14:15]
	v_pk_mul_f32 v[14:15], v[16:17], v[20:21]
	v_pk_mul_f32 v[16:17], v[10:11], s[20:21] op_sel_hi:[1,0]
	v_exp_f32_e32 v16, v16
	v_exp_f32_e32 v17, v17
	v_pk_fma_f32 v[12:13], v[12:13], v[172:173], v[136:137] op_sel_hi:[1,0,1]
	v_pk_mul_f32 v[8:9], v[8:9], v[14:15]
	v_pk_add_f32 v[14:15], v[16:17], 1.0 op_sel_hi:[1,0]
	v_pk_mul_f32 v[16:17], v[12:13], s[20:21] op_sel_hi:[1,0]
	v_exp_f32_e32 v16, v16
	v_exp_f32_e32 v17, v17
	v_rcp_f32_e32 v14, v14
	v_rcp_f32_e32 v15, v15
	v_pk_add_f32 v[16:17], v[16:17], 1.0 op_sel_hi:[1,0]
	v_rcp_f32_e32 v16, v16
	v_rcp_f32_e32 v17, v17
	v_pk_mul_f32 v[10:11], v[10:11], v[14:15]
	v_pk_fma_f32 v[2:3], v[2:3], v[172:173], v[130:131] op_sel_hi:[1,0,1]
	v_pk_fma_f32 v[4:5], v[4:5], v[172:173], v[132:133] op_sel_hi:[1,0,1]
	v_pk_mul_f32 v[10:11], v[2:3], v[10:11]
	v_pk_mul_f32 v[2:3], v[12:13], v[16:17]
	s_nop 0
	v_pk_mul_f32 v[12:13], v[4:5], v[2:3]
	v_mad_i64_i32 v[2:3], s[18:19], v168, s56, v[166:167]
	v_lshl_add_u64 v[2:3], v[2:3], 0, s[16:17]
	v_lshl_add_u64 v[14:15], v[2:3], 0, v[154:155]
	v_cvt_pk_bf16_f32 v2, v6, v7
	v_cvt_pk_bf16_f32 v3, v8, v9
	v_cvt_pk_bf16_f32 v4, v10, v11
	v_cvt_pk_bf16_f32 v5, v12, v13
	s_mov_b32 s17, s8
	s_mov_b32 s16, s10
	global_store_dwordx4 v[14:15], v[2:5], off nt
	s_cmpk_gt_u32 s33, 0xff
	s_cbranch_scc0 .Ldfr_p12_c
	s_barrier
